# modulation-table GEMV rewritten: each wave 32 columns x 33 rows, K split over 8 lane groups (each weight row loaded once per workgroup), packed FMA with LDS-broadcast activations, DPP/permlane reduce;
# speedup vs baseline: 1.0145x; 1.0095x over previous
; #define LAS __attribute__((address_space(3)))
; __device__ __forceinline__ int bid_opaque() { int b = blockIdx.x; asm volatile("" : "+s"(b)); return b; }
; __device__ __forceinline__ float siluf_(float x) { return x * sigmoidf_(x); }
; __device__ void phase_setup(const Params& p, LAS unsigned char* lds) {
;     ...
;     if (bid_opaque() < NL * 36) {
;         LAS float* sc = (LAS float*)lds;
;         __syncthreads();
;         for (int i = tid; i < 33 * D; i += 512) { const int r = i >> 10, k = i & 1023; const float v = (r < 32) ? p.in[I_C][r * D + k] : p.in[I_CCTX][k]; sc[i] = siluf_(v); }
;         __syncthreads();
;         float* MOD = (float*)(p.ws + WS_MOD);
;         for (int it = bid_opaque(); it < NL * 36; it += gridDim.x) {
;             const int l = it / 36, cgp = it % 36, n0 = cgp * 256 + lane * 4;
;             const float* wp = p.in[I_WMOD] + (size_t)l * D * (NMOD * D) + n0;
;             f32x4 a[5];
; #pragma unroll
;             for (int i = 0; i < 5; ++i) a[i] = (f32x4){0.f, 0.f, 0.f, 0.f};
;             for (int k = 0; k < D; k += 16) {
;                 f32x4 w[16];
; #pragma unroll
;                 for (int kk = 0; kk < 16; ++kk) w[kk] = *(const f32x4*)(wp + (size_t)(k + kk) * (NMOD * D));
.LBB0_458:
	s_or_b64 exec, exec, s[0:1]
	s_mov_b32 s8, s2
	v_readlane_b32 s14, v254, 2
	s_waitcnt lgkmcnt(0)
	s_barrier
	s_cmpk_gt_i32 s8, 0x8f
	s_cbranch_scc1 .LBB0_465
	s_add_u32 s0, s42, 0xbc80000
	s_addc_u32 s1, s43, 0
	v_and_b32_e32 v214, 63, v218
	v_lshrrev_b32_e32 v215, 3, v214
	v_and_b32_e32 v216, 7, v214
	v_lshrrev_b32_e32 v217, 6, v218
	v_lshlrev_b32_e32 v217, 7, v217
	v_lshl_add_u32 v210, v216, 4, v217
.Lgv_item:
	s_mul_hi_u32 s4, s8, 0x38e38e39
	s_lshr_b32 s9, s4, 3
	s_mul_i32 s4, s9, 36
	s_sub_u32 s4, s8, s4
	s_lshl_b32 s5, s4, 10
	s_mul_i32 s6, s9, 0x2400000
	s_mul_hi_u32 s7, s9, 0x2400000
	s_add_u32 s6, s6, s5
	s_addc_u32 s7, s7, 0
	s_add_u32 s6, s20, s6
	s_addc_u32 s7, s21, s7
	v_mul_u32_u24_e32 v0, 0x12000, v215
	v_add_u32_e32 v0, v0, v210
	v_lshlrev_b32_e32 v211, 3, v215
	v_add_u32_e32 v212, 0x10000, v211
	v_add_u32_e32 v213, 0x20000, v211
	v_mov_b64_e32 v[78:79], 0
	v_mov_b64_e32 v[80:81], 0
	v_mov_b64_e32 v[82:83], 0
	v_mov_b64_e32 v[84:85], 0
	v_mov_b64_e32 v[86:87], 0
	v_mov_b64_e32 v[88:89], 0
	v_mov_b64_e32 v[90:91], 0
	v_mov_b64_e32 v[92:93], 0
	v_mov_b64_e32 v[94:95], 0
	v_mov_b64_e32 v[96:97], 0
	v_mov_b64_e32 v[98:99], 0
	v_mov_b64_e32 v[100:101], 0
	v_mov_b64_e32 v[102:103], 0
	v_mov_b64_e32 v[104:105], 0
	v_mov_b64_e32 v[106:107], 0
	v_mov_b64_e32 v[108:109], 0
	v_mov_b64_e32 v[110:111], 0
	v_mov_b64_e32 v[112:113], 0
	v_mov_b64_e32 v[114:115], 0
	v_mov_b64_e32 v[116:117], 0
	v_mov_b64_e32 v[118:119], 0
	v_mov_b64_e32 v[120:121], 0
	v_mov_b64_e32 v[122:123], 0
	v_mov_b64_e32 v[124:125], 0
	v_mov_b64_e32 v[126:127], 0
	v_mov_b64_e32 v[128:129], 0
	v_mov_b64_e32 v[130:131], 0
	v_mov_b64_e32 v[132:133], 0
	v_mov_b64_e32 v[134:135], 0
	v_mov_b64_e32 v[136:137], 0
	v_mov_b64_e32 v[138:139], 0
	v_mov_b64_e32 v[140:141], 0
	v_mov_b64_e32 v[142:143], 0
	v_mov_b64_e32 v[144:145], 0
	v_mov_b64_e32 v[146:147], 0
	v_mov_b64_e32 v[148:149], 0
	v_mov_b64_e32 v[150:151], 0
	v_mov_b64_e32 v[152:153], 0
	v_mov_b64_e32 v[154:155], 0
	v_mov_b64_e32 v[156:157], 0
	v_mov_b64_e32 v[158:159], 0
	v_mov_b64_e32 v[160:161], 0
	v_mov_b64_e32 v[162:163], 0
	v_mov_b64_e32 v[164:165], 0
	v_mov_b64_e32 v[166:167], 0
	v_mov_b64_e32 v[168:169], 0
	v_mov_b64_e32 v[170:171], 0
	v_mov_b64_e32 v[172:173], 0
	v_mov_b64_e32 v[174:175], 0
	v_mov_b64_e32 v[176:177], 0
	v_mov_b64_e32 v[178:179], 0
	v_mov_b64_e32 v[180:181], 0
	v_mov_b64_e32 v[182:183], 0
	v_mov_b64_e32 v[184:185], 0
	v_mov_b64_e32 v[186:187], 0
	v_mov_b64_e32 v[188:189], 0
	v_mov_b64_e32 v[190:191], 0
	v_mov_b64_e32 v[192:193], 0
	v_mov_b64_e32 v[194:195], 0
	v_mov_b64_e32 v[196:197], 0
	v_mov_b64_e32 v[198:199], 0
	v_mov_b64_e32 v[200:201], 0
	v_mov_b64_e32 v[202:203], 0
	v_mov_b64_e32 v[204:205], 0
	v_mov_b64_e32 v[206:207], 0
	v_mov_b64_e32 v[208:209], 0
	global_load_dwordx4 v[2:5], v0, s[6:7]
	v_add_u32_e32 v214, 0x9000, v0
	global_load_dwordx4 v[6:9], v214, s[6:7]
	v_add_u32_e32 v0, 0x90000, v0
	global_load_dwordx4 v[10:13], v0, s[6:7]
	v_add_u32_e32 v214, 0x9000, v0
	global_load_dwordx4 v[14:17], v214, s[6:7]
	v_add_u32_e32 v0, 0x90000, v0
	global_load_dwordx4 v[18:21], v0, s[6:7]
	v_add_u32_e32 v214, 0x9000, v0
	global_load_dwordx4 v[22:25], v214, s[6:7]
	v_add_u32_e32 v0, 0x90000, v0
	ds_read_b64 v[34:35], v211
	ds_read_b64 v[36:37], v211 offset:4096
	ds_read_b64 v[38:39], v211 offset:8192
	ds_read_b64 v[40:41], v211 offset:12288
	ds_read_b64 v[42:43], v211 offset:16384
	ds_read_b64 v[44:45], v211 offset:20480
	ds_read_b64 v[46:47], v211 offset:24576
	ds_read_b64 v[48:49], v211 offset:28672
	ds_read_b64 v[50:51], v211 offset:32768
	ds_read_b64 v[52:53], v211 offset:36864
	ds_read_b64 v[54:55], v211 offset:40960
	s_mov_b32 s11, 0
.Lgv_loop:
	global_load_dwordx4 v[26:29], v0, s[6:7]
	v_add_u32_e32 v214, 0x9000, v0
	global_load_dwordx4 v[30:33], v214, s[6:7]
	v_add_u32_e32 v0, 0x90000, v0
	ds_read_b64 v[56:57], v211 offset:45056
	ds_read_b64 v[58:59], v211 offset:49152
	ds_read_b64 v[60:61], v211 offset:53248
	ds_read_b64 v[62:63], v211 offset:57344
	ds_read_b64 v[64:65], v211 offset:61440
	ds_read_b64 v[66:67], v212
	ds_read_b64 v[68:69], v212 offset:4096
	ds_read_b64 v[70:71], v212 offset:8192
	ds_read_b64 v[72:73], v212 offset:12288
	ds_read_b64 v[74:75], v212 offset:16384
	ds_read_b64 v[76:77], v212 offset:20480
	s_waitcnt vmcnt(6) lgkmcnt(11)
; #define LAS __attribute__((address_space(3)))
; __device__ void phase_setup(const Params& p, LAS unsigned char* lds) {
;     ...
;             for (int k = 0; k < D; k += 16) {
;                 f32x4 w[16];
; #pragma unroll
;                 for (int kk = 0; kk < 16; ++kk) w[kk] = *(const f32x4*)(wp + (size_t)(k + kk) * (NMOD * D));
; #pragma unroll
;                 for (int i = 0; i < 5; ++i) { const int r = (i < 4) ? wid + 8 * i : 32;
; #pragma unroll
;                     for (int k4 = 0; k4 < 4; ++k4) { const f32x4 s4 = *(const LAS f32x4*)(sc + r * D + k + 4 * k4);
;                         a[i] += s4[0] * w[4 * k4] + s4[1] * w[4 * k4 + 1] + s4[2] * w[4 * k4 + 2] + s4[3] * w[4 * k4 + 3]; } }
;             }
	v_pk_fma_f32 v[78:79], v[2:3], v[34:35], v[78:79] op_sel_hi:[1,0,1]
	v_pk_fma_f32 v[80:81], v[4:5], v[34:35], v[80:81] op_sel_hi:[1,0,1]
	v_pk_fma_f32 v[78:79], v[6:7], v[34:35], v[78:79] op_sel:[0,1,0] op_sel_hi:[1,1,1]
	v_pk_fma_f32 v[80:81], v[8:9], v[34:35], v[80:81] op_sel:[0,1,0] op_sel_hi:[1,1,1]
	v_pk_fma_f32 v[82:83], v[2:3], v[36:37], v[82:83] op_sel_hi:[1,0,1]
	v_pk_fma_f32 v[84:85], v[4:5], v[36:37], v[84:85] op_sel_hi:[1,0,1]
	v_pk_fma_f32 v[82:83], v[6:7], v[36:37], v[82:83] op_sel:[0,1,0] op_sel_hi:[1,1,1]
	v_pk_fma_f32 v[84:85], v[8:9], v[36:37], v[84:85] op_sel:[0,1,0] op_sel_hi:[1,1,1]
	v_pk_fma_f32 v[86:87], v[2:3], v[38:39], v[86:87] op_sel_hi:[1,0,1]
	v_pk_fma_f32 v[88:89], v[4:5], v[38:39], v[88:89] op_sel_hi:[1,0,1]
	v_pk_fma_f32 v[86:87], v[6:7], v[38:39], v[86:87] op_sel:[0,1,0] op_sel_hi:[1,1,1]
	v_pk_fma_f32 v[88:89], v[8:9], v[38:39], v[88:89] op_sel:[0,1,0] op_sel_hi:[1,1,1]
	v_pk_fma_f32 v[90:91], v[2:3], v[40:41], v[90:91] op_sel_hi:[1,0,1]
	v_pk_fma_f32 v[92:93], v[4:5], v[40:41], v[92:93] op_sel_hi:[1,0,1]
	v_pk_fma_f32 v[90:91], v[6:7], v[40:41], v[90:91] op_sel:[0,1,0] op_sel_hi:[1,1,1]
	v_pk_fma_f32 v[92:93], v[8:9], v[40:41], v[92:93] op_sel:[0,1,0] op_sel_hi:[1,1,1]
	v_pk_fma_f32 v[94:95], v[2:3], v[42:43], v[94:95] op_sel_hi:[1,0,1]
	v_pk_fma_f32 v[96:97], v[4:5], v[42:43], v[96:97] op_sel_hi:[1,0,1]
	v_pk_fma_f32 v[94:95], v[6:7], v[42:43], v[94:95] op_sel:[0,1,0] op_sel_hi:[1,1,1]
	v_pk_fma_f32 v[96:97], v[8:9], v[42:43], v[96:97] op_sel:[0,1,0] op_sel_hi:[1,1,1]
	v_pk_fma_f32 v[98:99], v[2:3], v[44:45], v[98:99] op_sel_hi:[1,0,1]
	v_pk_fma_f32 v[100:101], v[4:5], v[44:45], v[100:101] op_sel_hi:[1,0,1]
	v_pk_fma_f32 v[98:99], v[6:7], v[44:45], v[98:99] op_sel:[0,1,0] op_sel_hi:[1,1,1]
	v_pk_fma_f32 v[100:101], v[8:9], v[44:45], v[100:101] op_sel:[0,1,0] op_sel_hi:[1,1,1]
	v_pk_fma_f32 v[102:103], v[2:3], v[46:47], v[102:103] op_sel_hi:[1,0,1]
	v_pk_fma_f32 v[104:105], v[4:5], v[46:47], v[104:105] op_sel_hi:[1,0,1]
	v_pk_fma_f32 v[102:103], v[6:7], v[46:47], v[102:103] op_sel:[0,1,0] op_sel_hi:[1,1,1]
	v_pk_fma_f32 v[104:105], v[8:9], v[46:47], v[104:105] op_sel:[0,1,0] op_sel_hi:[1,1,1]
	v_pk_fma_f32 v[106:107], v[2:3], v[48:49], v[106:107] op_sel_hi:[1,0,1]
	v_pk_fma_f32 v[108:109], v[4:5], v[48:49], v[108:109] op_sel_hi:[1,0,1]
	v_pk_fma_f32 v[106:107], v[6:7], v[48:49], v[106:107] op_sel:[0,1,0] op_sel_hi:[1,1,1]
	v_pk_fma_f32 v[108:109], v[8:9], v[48:49], v[108:109] op_sel:[0,1,0] op_sel_hi:[1,1,1]
	v_pk_fma_f32 v[110:111], v[2:3], v[50:51], v[110:111] op_sel_hi:[1,0,1]
	v_pk_fma_f32 v[112:113], v[4:5], v[50:51], v[112:113] op_sel_hi:[1,0,1]
	v_pk_fma_f32 v[110:111], v[6:7], v[50:51], v[110:111] op_sel:[0,1,0] op_sel_hi:[1,1,1]
	v_pk_fma_f32 v[112:113], v[8:9], v[50:51], v[112:113] op_sel:[0,1,0] op_sel_hi:[1,1,1]
	v_pk_fma_f32 v[114:115], v[2:3], v[52:53], v[114:115] op_sel_hi:[1,0,1]
	v_pk_fma_f32 v[116:117], v[4:5], v[52:53], v[116:117] op_sel_hi:[1,0,1]
	v_pk_fma_f32 v[114:115], v[6:7], v[52:53], v[114:115] op_sel:[0,1,0] op_sel_hi:[1,1,1]
	v_pk_fma_f32 v[116:117], v[8:9], v[52:53], v[116:117] op_sel:[0,1,0] op_sel_hi:[1,1,1]
	v_pk_fma_f32 v[118:119], v[2:3], v[54:55], v[118:119] op_sel_hi:[1,0,1]
	v_pk_fma_f32 v[120:121], v[4:5], v[54:55], v[120:121] op_sel_hi:[1,0,1]
	v_pk_fma_f32 v[118:119], v[6:7], v[54:55], v[118:119] op_sel:[0,1,0] op_sel_hi:[1,1,1]
	v_pk_fma_f32 v[120:121], v[8:9], v[54:55], v[120:121] op_sel:[0,1,0] op_sel_hi:[1,1,1]
	ds_read_b64 v[34:35], v212 offset:24576
	ds_read_b64 v[36:37], v212 offset:28672
	ds_read_b64 v[38:39], v212 offset:32768
	ds_read_b64 v[40:41], v212 offset:36864
	ds_read_b64 v[42:43], v212 offset:40960
	ds_read_b64 v[44:45], v212 offset:45056
	ds_read_b64 v[46:47], v212 offset:49152
	ds_read_b64 v[48:49], v212 offset:53248
	ds_read_b64 v[50:51], v212 offset:57344
	ds_read_b64 v[52:53], v212 offset:61440
	ds_read_b64 v[54:55], v213
	s_waitcnt lgkmcnt(11)
	v_pk_fma_f32 v[122:123], v[2:3], v[56:57], v[122:123] op_sel_hi:[1,0,1]
	v_pk_fma_f32 v[124:125], v[4:5], v[56:57], v[124:125] op_sel_hi:[1,0,1]
	v_pk_fma_f32 v[122:123], v[6:7], v[56:57], v[122:123] op_sel:[0,1,0] op_sel_hi:[1,1,1]
	v_pk_fma_f32 v[124:125], v[8:9], v[56:57], v[124:125] op_sel:[0,1,0] op_sel_hi:[1,1,1]
	v_pk_fma_f32 v[126:127], v[2:3], v[58:59], v[126:127] op_sel_hi:[1,0,1]
	v_pk_fma_f32 v[128:129], v[4:5], v[58:59], v[128:129] op_sel_hi:[1,0,1]
	v_pk_fma_f32 v[126:127], v[6:7], v[58:59], v[126:127] op_sel:[0,1,0] op_sel_hi:[1,1,1]
	v_pk_fma_f32 v[128:129], v[8:9], v[58:59], v[128:129] op_sel:[0,1,0] op_sel_hi:[1,1,1]
	v_pk_fma_f32 v[130:131], v[2:3], v[60:61], v[130:131] op_sel_hi:[1,0,1]
	v_pk_fma_f32 v[132:133], v[4:5], v[60:61], v[132:133] op_sel_hi:[1,0,1]
	v_pk_fma_f32 v[130:131], v[6:7], v[60:61], v[130:131] op_sel:[0,1,0] op_sel_hi:[1,1,1]
	v_pk_fma_f32 v[132:133], v[8:9], v[60:61], v[132:133] op_sel:[0,1,0] op_sel_hi:[1,1,1]
	v_pk_fma_f32 v[134:135], v[2:3], v[62:63], v[134:135] op_sel_hi:[1,0,1]
	v_pk_fma_f32 v[136:137], v[4:5], v[62:63], v[136:137] op_sel_hi:[1,0,1]
	v_pk_fma_f32 v[134:135], v[6:7], v[62:63], v[134:135] op_sel:[0,1,0] op_sel_hi:[1,1,1]
	v_pk_fma_f32 v[136:137], v[8:9], v[62:63], v[136:137] op_sel:[0,1,0] op_sel_hi:[1,1,1]
	v_pk_fma_f32 v[138:139], v[2:3], v[64:65], v[138:139] op_sel_hi:[1,0,1]
	v_pk_fma_f32 v[140:141], v[4:5], v[64:65], v[140:141] op_sel_hi:[1,0,1]
	v_pk_fma_f32 v[138:139], v[6:7], v[64:65], v[138:139] op_sel:[0,1,0] op_sel_hi:[1,1,1]
	v_pk_fma_f32 v[140:141], v[8:9], v[64:65], v[140:141] op_sel:[0,1,0] op_sel_hi:[1,1,1]
	v_pk_fma_f32 v[142:143], v[2:3], v[66:67], v[142:143] op_sel_hi:[1,0,1]
	v_pk_fma_f32 v[144:145], v[4:5], v[66:67], v[144:145] op_sel_hi:[1,0,1]
; #define LAS __attribute__((address_space(3)))
; __device__ void phase_setup(const Params& p, LAS unsigned char* lds) {
;     ...
;             for (int k = 0; k < D; k += 16) {
;                 f32x4 w[16];
; #pragma unroll
;                 for (int kk = 0; kk < 16; ++kk) w[kk] = *(const f32x4*)(wp + (size_t)(k + kk) * (NMOD * D));
; #pragma unroll
;                 for (int i = 0; i < 5; ++i) { const int r = (i < 4) ? wid + 8 * i : 32;
; #pragma unroll
;                     for (int k4 = 0; k4 < 4; ++k4) { const f32x4 s4 = *(const LAS f32x4*)(sc + r * D + k + 4 * k4);
;                         a[i] += s4[0] * w[4 * k4] + s4[1] * w[4 * k4 + 1] + s4[2] * w[4 * k4 + 2] + s4[3] * w[4 * k4 + 3]; } }
;             }
	v_pk_fma_f32 v[142:143], v[6:7], v[66:67], v[142:143] op_sel:[0,1,0] op_sel_hi:[1,1,1]
	v_pk_fma_f32 v[144:145], v[8:9], v[66:67], v[144:145] op_sel:[0,1,0] op_sel_hi:[1,1,1]
	v_pk_fma_f32 v[146:147], v[2:3], v[68:69], v[146:147] op_sel_hi:[1,0,1]
	v_pk_fma_f32 v[148:149], v[4:5], v[68:69], v[148:149] op_sel_hi:[1,0,1]
	v_pk_fma_f32 v[146:147], v[6:7], v[68:69], v[146:147] op_sel:[0,1,0] op_sel_hi:[1,1,1]
	v_pk_fma_f32 v[148:149], v[8:9], v[68:69], v[148:149] op_sel:[0,1,0] op_sel_hi:[1,1,1]
	v_pk_fma_f32 v[150:151], v[2:3], v[70:71], v[150:151] op_sel_hi:[1,0,1]
	v_pk_fma_f32 v[152:153], v[4:5], v[70:71], v[152:153] op_sel_hi:[1,0,1]
	v_pk_fma_f32 v[150:151], v[6:7], v[70:71], v[150:151] op_sel:[0,1,0] op_sel_hi:[1,1,1]
	v_pk_fma_f32 v[152:153], v[8:9], v[70:71], v[152:153] op_sel:[0,1,0] op_sel_hi:[1,1,1]
	v_pk_fma_f32 v[154:155], v[2:3], v[72:73], v[154:155] op_sel_hi:[1,0,1]
	v_pk_fma_f32 v[156:157], v[4:5], v[72:73], v[156:157] op_sel_hi:[1,0,1]
	v_pk_fma_f32 v[154:155], v[6:7], v[72:73], v[154:155] op_sel:[0,1,0] op_sel_hi:[1,1,1]
	v_pk_fma_f32 v[156:157], v[8:9], v[72:73], v[156:157] op_sel:[0,1,0] op_sel_hi:[1,1,1]
	v_pk_fma_f32 v[158:159], v[2:3], v[74:75], v[158:159] op_sel_hi:[1,0,1]
	v_pk_fma_f32 v[160:161], v[4:5], v[74:75], v[160:161] op_sel_hi:[1,0,1]
	v_pk_fma_f32 v[158:159], v[6:7], v[74:75], v[158:159] op_sel:[0,1,0] op_sel_hi:[1,1,1]
	v_pk_fma_f32 v[160:161], v[8:9], v[74:75], v[160:161] op_sel:[0,1,0] op_sel_hi:[1,1,1]
	v_pk_fma_f32 v[162:163], v[2:3], v[76:77], v[162:163] op_sel_hi:[1,0,1]
	v_pk_fma_f32 v[164:165], v[4:5], v[76:77], v[164:165] op_sel_hi:[1,0,1]
	v_pk_fma_f32 v[162:163], v[6:7], v[76:77], v[162:163] op_sel:[0,1,0] op_sel_hi:[1,1,1]
	v_pk_fma_f32 v[164:165], v[8:9], v[76:77], v[164:165] op_sel:[0,1,0] op_sel_hi:[1,1,1]
	ds_read_b64 v[56:57], v211 offset:64
	ds_read_b64 v[58:59], v211 offset:4160
	ds_read_b64 v[60:61], v211 offset:8256
	ds_read_b64 v[62:63], v211 offset:12352
	ds_read_b64 v[64:65], v211 offset:16448
	ds_read_b64 v[66:67], v211 offset:20544
	ds_read_b64 v[68:69], v211 offset:24640
	ds_read_b64 v[70:71], v211 offset:28736
	ds_read_b64 v[72:73], v211 offset:32832
	ds_read_b64 v[74:75], v211 offset:36928
	ds_read_b64 v[76:77], v211 offset:41024
	v_add_u32_e32 v211, 64, v211
	v_add_u32_e32 v212, 64, v212
	v_add_u32_e32 v213, 64, v213
	s_waitcnt lgkmcnt(11)
	v_pk_fma_f32 v[166:167], v[2:3], v[34:35], v[166:167] op_sel_hi:[1,0,1]
	v_pk_fma_f32 v[168:169], v[4:5], v[34:35], v[168:169] op_sel_hi:[1,0,1]
	v_pk_fma_f32 v[166:167], v[6:7], v[34:35], v[166:167] op_sel:[0,1,0] op_sel_hi:[1,1,1]
	v_pk_fma_f32 v[168:169], v[8:9], v[34:35], v[168:169] op_sel:[0,1,0] op_sel_hi:[1,1,1]
	v_pk_fma_f32 v[170:171], v[2:3], v[36:37], v[170:171] op_sel_hi:[1,0,1]
	v_pk_fma_f32 v[172:173], v[4:5], v[36:37], v[172:173] op_sel_hi:[1,0,1]
	v_pk_fma_f32 v[170:171], v[6:7], v[36:37], v[170:171] op_sel:[0,1,0] op_sel_hi:[1,1,1]
	v_pk_fma_f32 v[172:173], v[8:9], v[36:37], v[172:173] op_sel:[0,1,0] op_sel_hi:[1,1,1]
	v_pk_fma_f32 v[174:175], v[2:3], v[38:39], v[174:175] op_sel_hi:[1,0,1]
	v_pk_fma_f32 v[176:177], v[4:5], v[38:39], v[176:177] op_sel_hi:[1,0,1]
	v_pk_fma_f32 v[174:175], v[6:7], v[38:39], v[174:175] op_sel:[0,1,0] op_sel_hi:[1,1,1]
	v_pk_fma_f32 v[176:177], v[8:9], v[38:39], v[176:177] op_sel:[0,1,0] op_sel_hi:[1,1,1]
	v_pk_fma_f32 v[178:179], v[2:3], v[40:41], v[178:179] op_sel_hi:[1,0,1]
	v_pk_fma_f32 v[180:181], v[4:5], v[40:41], v[180:181] op_sel_hi:[1,0,1]
	v_pk_fma_f32 v[178:179], v[6:7], v[40:41], v[178:179] op_sel:[0,1,0] op_sel_hi:[1,1,1]
	v_pk_fma_f32 v[180:181], v[8:9], v[40:41], v[180:181] op_sel:[0,1,0] op_sel_hi:[1,1,1]
	v_pk_fma_f32 v[182:183], v[2:3], v[42:43], v[182:183] op_sel_hi:[1,0,1]
	v_pk_fma_f32 v[184:185], v[4:5], v[42:43], v[184:185] op_sel_hi:[1,0,1]
	v_pk_fma_f32 v[182:183], v[6:7], v[42:43], v[182:183] op_sel:[0,1,0] op_sel_hi:[1,1,1]
	v_pk_fma_f32 v[184:185], v[8:9], v[42:43], v[184:185] op_sel:[0,1,0] op_sel_hi:[1,1,1]
	v_pk_fma_f32 v[186:187], v[2:3], v[44:45], v[186:187] op_sel_hi:[1,0,1]
	v_pk_fma_f32 v[188:189], v[4:5], v[44:45], v[188:189] op_sel_hi:[1,0,1]
	v_pk_fma_f32 v[186:187], v[6:7], v[44:45], v[186:187] op_sel:[0,1,0] op_sel_hi:[1,1,1]
	v_pk_fma_f32 v[188:189], v[8:9], v[44:45], v[188:189] op_sel:[0,1,0] op_sel_hi:[1,1,1]
	v_pk_fma_f32 v[190:191], v[2:3], v[46:47], v[190:191] op_sel_hi:[1,0,1]
	v_pk_fma_f32 v[192:193], v[4:5], v[46:47], v[192:193] op_sel_hi:[1,0,1]
	v_pk_fma_f32 v[190:191], v[6:7], v[46:47], v[190:191] op_sel:[0,1,0] op_sel_hi:[1,1,1]
	v_pk_fma_f32 v[192:193], v[8:9], v[46:47], v[192:193] op_sel:[0,1,0] op_sel_hi:[1,1,1]
	v_pk_fma_f32 v[194:195], v[2:3], v[48:49], v[194:195] op_sel_hi:[1,0,1]
	v_pk_fma_f32 v[196:197], v[4:5], v[48:49], v[196:197] op_sel_hi:[1,0,1]
	v_pk_fma_f32 v[194:195], v[6:7], v[48:49], v[194:195] op_sel:[0,1,0] op_sel_hi:[1,1,1]
	v_pk_fma_f32 v[196:197], v[8:9], v[48:49], v[196:197] op_sel:[0,1,0] op_sel_hi:[1,1,1]
	v_pk_fma_f32 v[198:199], v[2:3], v[50:51], v[198:199] op_sel_hi:[1,0,1]
	v_pk_fma_f32 v[200:201], v[4:5], v[50:51], v[200:201] op_sel_hi:[1,0,1]
	v_pk_fma_f32 v[198:199], v[6:7], v[50:51], v[198:199] op_sel:[0,1,0] op_sel_hi:[1,1,1]
	v_pk_fma_f32 v[200:201], v[8:9], v[50:51], v[200:201] op_sel:[0,1,0] op_sel_hi:[1,1,1]
	v_pk_fma_f32 v[202:203], v[2:3], v[52:53], v[202:203] op_sel_hi:[1,0,1]
	v_pk_fma_f32 v[204:205], v[4:5], v[52:53], v[204:205] op_sel_hi:[1,0,1]
	v_pk_fma_f32 v[202:203], v[6:7], v[52:53], v[202:203] op_sel:[0,1,0] op_sel_hi:[1,1,1]
	v_pk_fma_f32 v[204:205], v[8:9], v[52:53], v[204:205] op_sel:[0,1,0] op_sel_hi:[1,1,1]
	v_pk_fma_f32 v[206:207], v[2:3], v[54:55], v[206:207] op_sel_hi:[1,0,1]
	v_pk_fma_f32 v[208:209], v[4:5], v[54:55], v[208:209] op_sel_hi:[1,0,1]
	v_pk_fma_f32 v[206:207], v[6:7], v[54:55], v[206:207] op_sel:[0,1,0] op_sel_hi:[1,1,1]
	v_pk_fma_f32 v[208:209], v[8:9], v[54:55], v[208:209] op_sel:[0,1,0] op_sel_hi:[1,1,1]
	global_load_dwordx4 v[2:5], v0, s[6:7]
	v_add_u32_e32 v214, 0x9000, v0
	global_load_dwordx4 v[6:9], v214, s[6:7]
	v_add_u32_e32 v0, 0x90000, v0
	ds_read_b64 v[34:35], v211 offset:45056
	ds_read_b64 v[36:37], v211 offset:49152
	ds_read_b64 v[38:39], v211 offset:53248
	ds_read_b64 v[40:41], v211 offset:57344
	ds_read_b64 v[42:43], v211 offset:61440
	ds_read_b64 v[44:45], v212
	ds_read_b64 v[46:47], v212 offset:4096
	ds_read_b64 v[48:49], v212 offset:8192
	ds_read_b64 v[50:51], v212 offset:12288
	ds_read_b64 v[52:53], v212 offset:16384
	ds_read_b64 v[54:55], v212 offset:20480
	s_waitcnt vmcnt(6) lgkmcnt(11)
; #define LAS __attribute__((address_space(3)))
; __device__ void phase_setup(const Params& p, LAS unsigned char* lds) {
;     ...
;             for (int k = 0; k < D; k += 16) {
;                 f32x4 w[16];
; #pragma unroll
;                 for (int kk = 0; kk < 16; ++kk) w[kk] = *(const f32x4*)(wp + (size_t)(k + kk) * (NMOD * D));
; #pragma unroll
;                 for (int i = 0; i < 5; ++i) { const int r = (i < 4) ? wid + 8 * i : 32;
; #pragma unroll
;                     for (int k4 = 0; k4 < 4; ++k4) { const f32x4 s4 = *(const LAS f32x4*)(sc + r * D + k + 4 * k4);
;                         a[i] += s4[0] * w[4 * k4] + s4[1] * w[4 * k4 + 1] + s4[2] * w[4 * k4 + 2] + s4[3] * w[4 * k4 + 3]; } }
;             }
	v_pk_fma_f32 v[78:79], v[10:11], v[56:57], v[78:79] op_sel_hi:[1,0,1]
	v_pk_fma_f32 v[80:81], v[12:13], v[56:57], v[80:81] op_sel_hi:[1,0,1]
	v_pk_fma_f32 v[78:79], v[14:15], v[56:57], v[78:79] op_sel:[0,1,0] op_sel_hi:[1,1,1]
	v_pk_fma_f32 v[80:81], v[16:17], v[56:57], v[80:81] op_sel:[0,1,0] op_sel_hi:[1,1,1]
	v_pk_fma_f32 v[82:83], v[10:11], v[58:59], v[82:83] op_sel_hi:[1,0,1]
	v_pk_fma_f32 v[84:85], v[12:13], v[58:59], v[84:85] op_sel_hi:[1,0,1]
	v_pk_fma_f32 v[82:83], v[14:15], v[58:59], v[82:83] op_sel:[0,1,0] op_sel_hi:[1,1,1]
	v_pk_fma_f32 v[84:85], v[16:17], v[58:59], v[84:85] op_sel:[0,1,0] op_sel_hi:[1,1,1]
	v_pk_fma_f32 v[86:87], v[10:11], v[60:61], v[86:87] op_sel_hi:[1,0,1]
	v_pk_fma_f32 v[88:89], v[12:13], v[60:61], v[88:89] op_sel_hi:[1,0,1]
	v_pk_fma_f32 v[86:87], v[14:15], v[60:61], v[86:87] op_sel:[0,1,0] op_sel_hi:[1,1,1]
	v_pk_fma_f32 v[88:89], v[16:17], v[60:61], v[88:89] op_sel:[0,1,0] op_sel_hi:[1,1,1]
	v_pk_fma_f32 v[90:91], v[10:11], v[62:63], v[90:91] op_sel_hi:[1,0,1]
	v_pk_fma_f32 v[92:93], v[12:13], v[62:63], v[92:93] op_sel_hi:[1,0,1]
	v_pk_fma_f32 v[90:91], v[14:15], v[62:63], v[90:91] op_sel:[0,1,0] op_sel_hi:[1,1,1]
	v_pk_fma_f32 v[92:93], v[16:17], v[62:63], v[92:93] op_sel:[0,1,0] op_sel_hi:[1,1,1]
	v_pk_fma_f32 v[94:95], v[10:11], v[64:65], v[94:95] op_sel_hi:[1,0,1]
	v_pk_fma_f32 v[96:97], v[12:13], v[64:65], v[96:97] op_sel_hi:[1,0,1]
	v_pk_fma_f32 v[94:95], v[14:15], v[64:65], v[94:95] op_sel:[0,1,0] op_sel_hi:[1,1,1]
	v_pk_fma_f32 v[96:97], v[16:17], v[64:65], v[96:97] op_sel:[0,1,0] op_sel_hi:[1,1,1]
	v_pk_fma_f32 v[98:99], v[10:11], v[66:67], v[98:99] op_sel_hi:[1,0,1]
	v_pk_fma_f32 v[100:101], v[12:13], v[66:67], v[100:101] op_sel_hi:[1,0,1]
	v_pk_fma_f32 v[98:99], v[14:15], v[66:67], v[98:99] op_sel:[0,1,0] op_sel_hi:[1,1,1]
	v_pk_fma_f32 v[100:101], v[16:17], v[66:67], v[100:101] op_sel:[0,1,0] op_sel_hi:[1,1,1]
	v_pk_fma_f32 v[102:103], v[10:11], v[68:69], v[102:103] op_sel_hi:[1,0,1]
	v_pk_fma_f32 v[104:105], v[12:13], v[68:69], v[104:105] op_sel_hi:[1,0,1]
	v_pk_fma_f32 v[102:103], v[14:15], v[68:69], v[102:103] op_sel:[0,1,0] op_sel_hi:[1,1,1]
	v_pk_fma_f32 v[104:105], v[16:17], v[68:69], v[104:105] op_sel:[0,1,0] op_sel_hi:[1,1,1]
	v_pk_fma_f32 v[106:107], v[10:11], v[70:71], v[106:107] op_sel_hi:[1,0,1]
	v_pk_fma_f32 v[108:109], v[12:13], v[70:71], v[108:109] op_sel_hi:[1,0,1]
	v_pk_fma_f32 v[106:107], v[14:15], v[70:71], v[106:107] op_sel:[0,1,0] op_sel_hi:[1,1,1]
	v_pk_fma_f32 v[108:109], v[16:17], v[70:71], v[108:109] op_sel:[0,1,0] op_sel_hi:[1,1,1]
	v_pk_fma_f32 v[110:111], v[10:11], v[72:73], v[110:111] op_sel_hi:[1,0,1]
	v_pk_fma_f32 v[112:113], v[12:13], v[72:73], v[112:113] op_sel_hi:[1,0,1]
	v_pk_fma_f32 v[110:111], v[14:15], v[72:73], v[110:111] op_sel:[0,1,0] op_sel_hi:[1,1,1]
	v_pk_fma_f32 v[112:113], v[16:17], v[72:73], v[112:113] op_sel:[0,1,0] op_sel_hi:[1,1,1]
	v_pk_fma_f32 v[114:115], v[10:11], v[74:75], v[114:115] op_sel_hi:[1,0,1]
	v_pk_fma_f32 v[116:117], v[12:13], v[74:75], v[116:117] op_sel_hi:[1,0,1]
	v_pk_fma_f32 v[114:115], v[14:15], v[74:75], v[114:115] op_sel:[0,1,0] op_sel_hi:[1,1,1]
	v_pk_fma_f32 v[116:117], v[16:17], v[74:75], v[116:117] op_sel:[0,1,0] op_sel_hi:[1,1,1]
	v_pk_fma_f32 v[118:119], v[10:11], v[76:77], v[118:119] op_sel_hi:[1,0,1]
	v_pk_fma_f32 v[120:121], v[12:13], v[76:77], v[120:121] op_sel_hi:[1,0,1]
	v_pk_fma_f32 v[118:119], v[14:15], v[76:77], v[118:119] op_sel:[0,1,0] op_sel_hi:[1,1,1]
	v_pk_fma_f32 v[120:121], v[16:17], v[76:77], v[120:121] op_sel:[0,1,0] op_sel_hi:[1,1,1]
	ds_read_b64 v[56:57], v212 offset:24576
	ds_read_b64 v[58:59], v212 offset:28672
	ds_read_b64 v[60:61], v212 offset:32768
	ds_read_b64 v[62:63], v212 offset:36864
	ds_read_b64 v[64:65], v212 offset:40960
	ds_read_b64 v[66:67], v212 offset:45056
	ds_read_b64 v[68:69], v212 offset:49152
	ds_read_b64 v[70:71], v212 offset:53248
	ds_read_b64 v[72:73], v212 offset:57344
	ds_read_b64 v[74:75], v212 offset:61440
	ds_read_b64 v[76:77], v213
	s_waitcnt lgkmcnt(11)
	v_pk_fma_f32 v[122:123], v[10:11], v[34:35], v[122:123] op_sel_hi:[1,0,1]
	v_pk_fma_f32 v[124:125], v[12:13], v[34:35], v[124:125] op_sel_hi:[1,0,1]
	v_pk_fma_f32 v[122:123], v[14:15], v[34:35], v[122:123] op_sel:[0,1,0] op_sel_hi:[1,1,1]
	v_pk_fma_f32 v[124:125], v[16:17], v[34:35], v[124:125] op_sel:[0,1,0] op_sel_hi:[1,1,1]
	v_pk_fma_f32 v[126:127], v[10:11], v[36:37], v[126:127] op_sel_hi:[1,0,1]
	v_pk_fma_f32 v[128:129], v[12:13], v[36:37], v[128:129] op_sel_hi:[1,0,1]
	v_pk_fma_f32 v[126:127], v[14:15], v[36:37], v[126:127] op_sel:[0,1,0] op_sel_hi:[1,1,1]
	v_pk_fma_f32 v[128:129], v[16:17], v[36:37], v[128:129] op_sel:[0,1,0] op_sel_hi:[1,1,1]
	v_pk_fma_f32 v[130:131], v[10:11], v[38:39], v[130:131] op_sel_hi:[1,0,1]
	v_pk_fma_f32 v[132:133], v[12:13], v[38:39], v[132:133] op_sel_hi:[1,0,1]
	v_pk_fma_f32 v[130:131], v[14:15], v[38:39], v[130:131] op_sel:[0,1,0] op_sel_hi:[1,1,1]
	v_pk_fma_f32 v[132:133], v[16:17], v[38:39], v[132:133] op_sel:[0,1,0] op_sel_hi:[1,1,1]
	v_pk_fma_f32 v[134:135], v[10:11], v[40:41], v[134:135] op_sel_hi:[1,0,1]
	v_pk_fma_f32 v[136:137], v[12:13], v[40:41], v[136:137] op_sel_hi:[1,0,1]
	v_pk_fma_f32 v[134:135], v[14:15], v[40:41], v[134:135] op_sel:[0,1,0] op_sel_hi:[1,1,1]
	v_pk_fma_f32 v[136:137], v[16:17], v[40:41], v[136:137] op_sel:[0,1,0] op_sel_hi:[1,1,1]
	v_pk_fma_f32 v[138:139], v[10:11], v[42:43], v[138:139] op_sel_hi:[1,0,1]
	v_pk_fma_f32 v[140:141], v[12:13], v[42:43], v[140:141] op_sel_hi:[1,0,1]
	v_pk_fma_f32 v[138:139], v[14:15], v[42:43], v[138:139] op_sel:[0,1,0] op_sel_hi:[1,1,1]
	v_pk_fma_f32 v[140:141], v[16:17], v[42:43], v[140:141] op_sel:[0,1,0] op_sel_hi:[1,1,1]
; #define LAS __attribute__((address_space(3)))
; __device__ void phase_setup(const Params& p, LAS unsigned char* lds) {
;     ...
;             for (int k = 0; k < D; k += 16) {
;                 f32x4 w[16];
; #pragma unroll
;                 for (int kk = 0; kk < 16; ++kk) w[kk] = *(const f32x4*)(wp + (size_t)(k + kk) * (NMOD * D));
; #pragma unroll
;                 for (int i = 0; i < 5; ++i) { const int r = (i < 4) ? wid + 8 * i : 32;
; #pragma unroll
;                     for (int k4 = 0; k4 < 4; ++k4) { const f32x4 s4 = *(const LAS f32x4*)(sc + r * D + k + 4 * k4);
;                         a[i] += s4[0] * w[4 * k4] + s4[1] * w[4 * k4 + 1] + s4[2] * w[4 * k4 + 2] + s4[3] * w[4 * k4 + 3]; } }
;             }
	v_pk_fma_f32 v[142:143], v[10:11], v[44:45], v[142:143] op_sel_hi:[1,0,1]
	v_pk_fma_f32 v[144:145], v[12:13], v[44:45], v[144:145] op_sel_hi:[1,0,1]
	v_pk_fma_f32 v[142:143], v[14:15], v[44:45], v[142:143] op_sel:[0,1,0] op_sel_hi:[1,1,1]
	v_pk_fma_f32 v[144:145], v[16:17], v[44:45], v[144:145] op_sel:[0,1,0] op_sel_hi:[1,1,1]
	v_pk_fma_f32 v[146:147], v[10:11], v[46:47], v[146:147] op_sel_hi:[1,0,1]
	v_pk_fma_f32 v[148:149], v[12:13], v[46:47], v[148:149] op_sel_hi:[1,0,1]
	v_pk_fma_f32 v[146:147], v[14:15], v[46:47], v[146:147] op_sel:[0,1,0] op_sel_hi:[1,1,1]
	v_pk_fma_f32 v[148:149], v[16:17], v[46:47], v[148:149] op_sel:[0,1,0] op_sel_hi:[1,1,1]
	v_pk_fma_f32 v[150:151], v[10:11], v[48:49], v[150:151] op_sel_hi:[1,0,1]
	v_pk_fma_f32 v[152:153], v[12:13], v[48:49], v[152:153] op_sel_hi:[1,0,1]
	v_pk_fma_f32 v[150:151], v[14:15], v[48:49], v[150:151] op_sel:[0,1,0] op_sel_hi:[1,1,1]
	v_pk_fma_f32 v[152:153], v[16:17], v[48:49], v[152:153] op_sel:[0,1,0] op_sel_hi:[1,1,1]
	v_pk_fma_f32 v[154:155], v[10:11], v[50:51], v[154:155] op_sel_hi:[1,0,1]
	v_pk_fma_f32 v[156:157], v[12:13], v[50:51], v[156:157] op_sel_hi:[1,0,1]
	v_pk_fma_f32 v[154:155], v[14:15], v[50:51], v[154:155] op_sel:[0,1,0] op_sel_hi:[1,1,1]
	v_pk_fma_f32 v[156:157], v[16:17], v[50:51], v[156:157] op_sel:[0,1,0] op_sel_hi:[1,1,1]
	v_pk_fma_f32 v[158:159], v[10:11], v[52:53], v[158:159] op_sel_hi:[1,0,1]
	v_pk_fma_f32 v[160:161], v[12:13], v[52:53], v[160:161] op_sel_hi:[1,0,1]
	v_pk_fma_f32 v[158:159], v[14:15], v[52:53], v[158:159] op_sel:[0,1,0] op_sel_hi:[1,1,1]
	v_pk_fma_f32 v[160:161], v[16:17], v[52:53], v[160:161] op_sel:[0,1,0] op_sel_hi:[1,1,1]
	v_pk_fma_f32 v[162:163], v[10:11], v[54:55], v[162:163] op_sel_hi:[1,0,1]
	v_pk_fma_f32 v[164:165], v[12:13], v[54:55], v[164:165] op_sel_hi:[1,0,1]
	v_pk_fma_f32 v[162:163], v[14:15], v[54:55], v[162:163] op_sel:[0,1,0] op_sel_hi:[1,1,1]
	v_pk_fma_f32 v[164:165], v[16:17], v[54:55], v[164:165] op_sel:[0,1,0] op_sel_hi:[1,1,1]
	ds_read_b64 v[34:35], v211 offset:64
	ds_read_b64 v[36:37], v211 offset:4160
	ds_read_b64 v[38:39], v211 offset:8256
	ds_read_b64 v[40:41], v211 offset:12352
	ds_read_b64 v[42:43], v211 offset:16448
	ds_read_b64 v[44:45], v211 offset:20544
	ds_read_b64 v[46:47], v211 offset:24640
	ds_read_b64 v[48:49], v211 offset:28736
	ds_read_b64 v[50:51], v211 offset:32832
	ds_read_b64 v[52:53], v211 offset:36928
	ds_read_b64 v[54:55], v211 offset:41024
	v_add_u32_e32 v211, 64, v211
	v_add_u32_e32 v212, 64, v212
	v_add_u32_e32 v213, 64, v213
	s_waitcnt lgkmcnt(11)
	v_pk_fma_f32 v[166:167], v[10:11], v[56:57], v[166:167] op_sel_hi:[1,0,1]
	v_pk_fma_f32 v[168:169], v[12:13], v[56:57], v[168:169] op_sel_hi:[1,0,1]
	v_pk_fma_f32 v[166:167], v[14:15], v[56:57], v[166:167] op_sel:[0,1,0] op_sel_hi:[1,1,1]
	v_pk_fma_f32 v[168:169], v[16:17], v[56:57], v[168:169] op_sel:[0,1,0] op_sel_hi:[1,1,1]
	v_pk_fma_f32 v[170:171], v[10:11], v[58:59], v[170:171] op_sel_hi:[1,0,1]
	v_pk_fma_f32 v[172:173], v[12:13], v[58:59], v[172:173] op_sel_hi:[1,0,1]
	v_pk_fma_f32 v[170:171], v[14:15], v[58:59], v[170:171] op_sel:[0,1,0] op_sel_hi:[1,1,1]
	v_pk_fma_f32 v[172:173], v[16:17], v[58:59], v[172:173] op_sel:[0,1,0] op_sel_hi:[1,1,1]
	v_pk_fma_f32 v[174:175], v[10:11], v[60:61], v[174:175] op_sel_hi:[1,0,1]
	v_pk_fma_f32 v[176:177], v[12:13], v[60:61], v[176:177] op_sel_hi:[1,0,1]
	v_pk_fma_f32 v[174:175], v[14:15], v[60:61], v[174:175] op_sel:[0,1,0] op_sel_hi:[1,1,1]
	v_pk_fma_f32 v[176:177], v[16:17], v[60:61], v[176:177] op_sel:[0,1,0] op_sel_hi:[1,1,1]
	v_pk_fma_f32 v[178:179], v[10:11], v[62:63], v[178:179] op_sel_hi:[1,0,1]
	v_pk_fma_f32 v[180:181], v[12:13], v[62:63], v[180:181] op_sel_hi:[1,0,1]
	v_pk_fma_f32 v[178:179], v[14:15], v[62:63], v[178:179] op_sel:[0,1,0] op_sel_hi:[1,1,1]
	v_pk_fma_f32 v[180:181], v[16:17], v[62:63], v[180:181] op_sel:[0,1,0] op_sel_hi:[1,1,1]
	v_pk_fma_f32 v[182:183], v[10:11], v[64:65], v[182:183] op_sel_hi:[1,0,1]
	v_pk_fma_f32 v[184:185], v[12:13], v[64:65], v[184:185] op_sel_hi:[1,0,1]
	v_pk_fma_f32 v[182:183], v[14:15], v[64:65], v[182:183] op_sel:[0,1,0] op_sel_hi:[1,1,1]
	v_pk_fma_f32 v[184:185], v[16:17], v[64:65], v[184:185] op_sel:[0,1,0] op_sel_hi:[1,1,1]
	v_pk_fma_f32 v[186:187], v[10:11], v[66:67], v[186:187] op_sel_hi:[1,0,1]
	v_pk_fma_f32 v[188:189], v[12:13], v[66:67], v[188:189] op_sel_hi:[1,0,1]
	v_pk_fma_f32 v[186:187], v[14:15], v[66:67], v[186:187] op_sel:[0,1,0] op_sel_hi:[1,1,1]
	v_pk_fma_f32 v[188:189], v[16:17], v[66:67], v[188:189] op_sel:[0,1,0] op_sel_hi:[1,1,1]
	v_pk_fma_f32 v[190:191], v[10:11], v[68:69], v[190:191] op_sel_hi:[1,0,1]
	v_pk_fma_f32 v[192:193], v[12:13], v[68:69], v[192:193] op_sel_hi:[1,0,1]
	v_pk_fma_f32 v[190:191], v[14:15], v[68:69], v[190:191] op_sel:[0,1,0] op_sel_hi:[1,1,1]
	v_pk_fma_f32 v[192:193], v[16:17], v[68:69], v[192:193] op_sel:[0,1,0] op_sel_hi:[1,1,1]
	v_pk_fma_f32 v[194:195], v[10:11], v[70:71], v[194:195] op_sel_hi:[1,0,1]
	v_pk_fma_f32 v[196:197], v[12:13], v[70:71], v[196:197] op_sel_hi:[1,0,1]
	v_pk_fma_f32 v[194:195], v[14:15], v[70:71], v[194:195] op_sel:[0,1,0] op_sel_hi:[1,1,1]
	v_pk_fma_f32 v[196:197], v[16:17], v[70:71], v[196:197] op_sel:[0,1,0] op_sel_hi:[1,1,1]
	v_pk_fma_f32 v[198:199], v[10:11], v[72:73], v[198:199] op_sel_hi:[1,0,1]
	v_pk_fma_f32 v[200:201], v[12:13], v[72:73], v[200:201] op_sel_hi:[1,0,1]
	v_pk_fma_f32 v[198:199], v[14:15], v[72:73], v[198:199] op_sel:[0,1,0] op_sel_hi:[1,1,1]
	v_pk_fma_f32 v[200:201], v[16:17], v[72:73], v[200:201] op_sel:[0,1,0] op_sel_hi:[1,1,1]
	v_pk_fma_f32 v[202:203], v[10:11], v[74:75], v[202:203] op_sel_hi:[1,0,1]
	v_pk_fma_f32 v[204:205], v[12:13], v[74:75], v[204:205] op_sel_hi:[1,0,1]
	v_pk_fma_f32 v[202:203], v[14:15], v[74:75], v[202:203] op_sel:[0,1,0] op_sel_hi:[1,1,1]
	v_pk_fma_f32 v[204:205], v[16:17], v[74:75], v[204:205] op_sel:[0,1,0] op_sel_hi:[1,1,1]
	v_pk_fma_f32 v[206:207], v[10:11], v[76:77], v[206:207] op_sel_hi:[1,0,1]
	v_pk_fma_f32 v[208:209], v[12:13], v[76:77], v[208:209] op_sel_hi:[1,0,1]
	v_pk_fma_f32 v[206:207], v[14:15], v[76:77], v[206:207] op_sel:[0,1,0] op_sel_hi:[1,1,1]
	v_pk_fma_f32 v[208:209], v[16:17], v[76:77], v[208:209] op_sel:[0,1,0] op_sel_hi:[1,1,1]
	global_load_dwordx4 v[10:13], v0, s[6:7]
	v_add_u32_e32 v214, 0x9000, v0
	global_load_dwordx4 v[14:17], v214, s[6:7]
	v_add_u32_e32 v0, 0x90000, v0
	ds_read_b64 v[56:57], v211 offset:45056
	ds_read_b64 v[58:59], v211 offset:49152
	ds_read_b64 v[60:61], v211 offset:53248
	ds_read_b64 v[62:63], v211 offset:57344
	ds_read_b64 v[64:65], v211 offset:61440
	ds_read_b64 v[66:67], v212
	ds_read_b64 v[68:69], v212 offset:4096
	ds_read_b64 v[70:71], v212 offset:8192
	ds_read_b64 v[72:73], v212 offset:12288
	ds_read_b64 v[74:75], v212 offset:16384
	ds_read_b64 v[76:77], v212 offset:20480
	s_waitcnt vmcnt(6) lgkmcnt(11)
; #define LAS __attribute__((address_space(3)))
; __device__ void phase_setup(const Params& p, LAS unsigned char* lds) {
;     ...
;             for (int k = 0; k < D; k += 16) {
;                 f32x4 w[16];
; #pragma unroll
;                 for (int kk = 0; kk < 16; ++kk) w[kk] = *(const f32x4*)(wp + (size_t)(k + kk) * (NMOD * D));
; #pragma unroll
;                 for (int i = 0; i < 5; ++i) { const int r = (i < 4) ? wid + 8 * i : 32;
; #pragma unroll
;                     for (int k4 = 0; k4 < 4; ++k4) { const f32x4 s4 = *(const LAS f32x4*)(sc + r * D + k + 4 * k4);
;                         a[i] += s4[0] * w[4 * k4] + s4[1] * w[4 * k4 + 1] + s4[2] * w[4 * k4 + 2] + s4[3] * w[4 * k4 + 3]; } }
;             }
	v_pk_fma_f32 v[78:79], v[18:19], v[34:35], v[78:79] op_sel_hi:[1,0,1]
	v_pk_fma_f32 v[80:81], v[20:21], v[34:35], v[80:81] op_sel_hi:[1,0,1]
	v_pk_fma_f32 v[78:79], v[22:23], v[34:35], v[78:79] op_sel:[0,1,0] op_sel_hi:[1,1,1]
	v_pk_fma_f32 v[80:81], v[24:25], v[34:35], v[80:81] op_sel:[0,1,0] op_sel_hi:[1,1,1]
	v_pk_fma_f32 v[82:83], v[18:19], v[36:37], v[82:83] op_sel_hi:[1,0,1]
	v_pk_fma_f32 v[84:85], v[20:21], v[36:37], v[84:85] op_sel_hi:[1,0,1]
	v_pk_fma_f32 v[82:83], v[22:23], v[36:37], v[82:83] op_sel:[0,1,0] op_sel_hi:[1,1,1]
	v_pk_fma_f32 v[84:85], v[24:25], v[36:37], v[84:85] op_sel:[0,1,0] op_sel_hi:[1,1,1]
	v_pk_fma_f32 v[86:87], v[18:19], v[38:39], v[86:87] op_sel_hi:[1,0,1]
	v_pk_fma_f32 v[88:89], v[20:21], v[38:39], v[88:89] op_sel_hi:[1,0,1]
	v_pk_fma_f32 v[86:87], v[22:23], v[38:39], v[86:87] op_sel:[0,1,0] op_sel_hi:[1,1,1]
	v_pk_fma_f32 v[88:89], v[24:25], v[38:39], v[88:89] op_sel:[0,1,0] op_sel_hi:[1,1,1]
	v_pk_fma_f32 v[90:91], v[18:19], v[40:41], v[90:91] op_sel_hi:[1,0,1]
	v_pk_fma_f32 v[92:93], v[20:21], v[40:41], v[92:93] op_sel_hi:[1,0,1]
	v_pk_fma_f32 v[90:91], v[22:23], v[40:41], v[90:91] op_sel:[0,1,0] op_sel_hi:[1,1,1]
	v_pk_fma_f32 v[92:93], v[24:25], v[40:41], v[92:93] op_sel:[0,1,0] op_sel_hi:[1,1,1]
	v_pk_fma_f32 v[94:95], v[18:19], v[42:43], v[94:95] op_sel_hi:[1,0,1]
	v_pk_fma_f32 v[96:97], v[20:21], v[42:43], v[96:97] op_sel_hi:[1,0,1]
	v_pk_fma_f32 v[94:95], v[22:23], v[42:43], v[94:95] op_sel:[0,1,0] op_sel_hi:[1,1,1]
	v_pk_fma_f32 v[96:97], v[24:25], v[42:43], v[96:97] op_sel:[0,1,0] op_sel_hi:[1,1,1]
	v_pk_fma_f32 v[98:99], v[18:19], v[44:45], v[98:99] op_sel_hi:[1,0,1]
	v_pk_fma_f32 v[100:101], v[20:21], v[44:45], v[100:101] op_sel_hi:[1,0,1]
	v_pk_fma_f32 v[98:99], v[22:23], v[44:45], v[98:99] op_sel:[0,1,0] op_sel_hi:[1,1,1]
	v_pk_fma_f32 v[100:101], v[24:25], v[44:45], v[100:101] op_sel:[0,1,0] op_sel_hi:[1,1,1]
	v_pk_fma_f32 v[102:103], v[18:19], v[46:47], v[102:103] op_sel_hi:[1,0,1]
	v_pk_fma_f32 v[104:105], v[20:21], v[46:47], v[104:105] op_sel_hi:[1,0,1]
	v_pk_fma_f32 v[102:103], v[22:23], v[46:47], v[102:103] op_sel:[0,1,0] op_sel_hi:[1,1,1]
	v_pk_fma_f32 v[104:105], v[24:25], v[46:47], v[104:105] op_sel:[0,1,0] op_sel_hi:[1,1,1]
	v_pk_fma_f32 v[106:107], v[18:19], v[48:49], v[106:107] op_sel_hi:[1,0,1]
	v_pk_fma_f32 v[108:109], v[20:21], v[48:49], v[108:109] op_sel_hi:[1,0,1]
	v_pk_fma_f32 v[106:107], v[22:23], v[48:49], v[106:107] op_sel:[0,1,0] op_sel_hi:[1,1,1]
	v_pk_fma_f32 v[108:109], v[24:25], v[48:49], v[108:109] op_sel:[0,1,0] op_sel_hi:[1,1,1]
	v_pk_fma_f32 v[110:111], v[18:19], v[50:51], v[110:111] op_sel_hi:[1,0,1]
	v_pk_fma_f32 v[112:113], v[20:21], v[50:51], v[112:113] op_sel_hi:[1,0,1]
	v_pk_fma_f32 v[110:111], v[22:23], v[50:51], v[110:111] op_sel:[0,1,0] op_sel_hi:[1,1,1]
	v_pk_fma_f32 v[112:113], v[24:25], v[50:51], v[112:113] op_sel:[0,1,0] op_sel_hi:[1,1,1]
	v_pk_fma_f32 v[114:115], v[18:19], v[52:53], v[114:115] op_sel_hi:[1,0,1]
	v_pk_fma_f32 v[116:117], v[20:21], v[52:53], v[116:117] op_sel_hi:[1,0,1]
	v_pk_fma_f32 v[114:115], v[22:23], v[52:53], v[114:115] op_sel:[0,1,0] op_sel_hi:[1,1,1]
	v_pk_fma_f32 v[116:117], v[24:25], v[52:53], v[116:117] op_sel:[0,1,0] op_sel_hi:[1,1,1]
	v_pk_fma_f32 v[118:119], v[18:19], v[54:55], v[118:119] op_sel_hi:[1,0,1]
	v_pk_fma_f32 v[120:121], v[20:21], v[54:55], v[120:121] op_sel_hi:[1,0,1]
	v_pk_fma_f32 v[118:119], v[22:23], v[54:55], v[118:119] op_sel:[0,1,0] op_sel_hi:[1,1,1]
	v_pk_fma_f32 v[120:121], v[24:25], v[54:55], v[120:121] op_sel:[0,1,0] op_sel_hi:[1,1,1]
	ds_read_b64 v[34:35], v212 offset:24576
	ds_read_b64 v[36:37], v212 offset:28672
	ds_read_b64 v[38:39], v212 offset:32768
	ds_read_b64 v[40:41], v212 offset:36864
	ds_read_b64 v[42:43], v212 offset:40960
	ds_read_b64 v[44:45], v212 offset:45056
	ds_read_b64 v[46:47], v212 offset:49152
	ds_read_b64 v[48:49], v212 offset:53248
	ds_read_b64 v[50:51], v212 offset:57344
	ds_read_b64 v[52:53], v212 offset:61440
	ds_read_b64 v[54:55], v213
	s_waitcnt lgkmcnt(11)
	v_pk_fma_f32 v[122:123], v[18:19], v[56:57], v[122:123] op_sel_hi:[1,0,1]
	v_pk_fma_f32 v[124:125], v[20:21], v[56:57], v[124:125] op_sel_hi:[1,0,1]
	v_pk_fma_f32 v[122:123], v[22:23], v[56:57], v[122:123] op_sel:[0,1,0] op_sel_hi:[1,1,1]
	v_pk_fma_f32 v[124:125], v[24:25], v[56:57], v[124:125] op_sel:[0,1,0] op_sel_hi:[1,1,1]
	v_pk_fma_f32 v[126:127], v[18:19], v[58:59], v[126:127] op_sel_hi:[1,0,1]
	v_pk_fma_f32 v[128:129], v[20:21], v[58:59], v[128:129] op_sel_hi:[1,0,1]
	v_pk_fma_f32 v[126:127], v[22:23], v[58:59], v[126:127] op_sel:[0,1,0] op_sel_hi:[1,1,1]
	v_pk_fma_f32 v[128:129], v[24:25], v[58:59], v[128:129] op_sel:[0,1,0] op_sel_hi:[1,1,1]
	v_pk_fma_f32 v[130:131], v[18:19], v[60:61], v[130:131] op_sel_hi:[1,0,1]
	v_pk_fma_f32 v[132:133], v[20:21], v[60:61], v[132:133] op_sel_hi:[1,0,1]
	v_pk_fma_f32 v[130:131], v[22:23], v[60:61], v[130:131] op_sel:[0,1,0] op_sel_hi:[1,1,1]
	v_pk_fma_f32 v[132:133], v[24:25], v[60:61], v[132:133] op_sel:[0,1,0] op_sel_hi:[1,1,1]
	v_pk_fma_f32 v[134:135], v[18:19], v[62:63], v[134:135] op_sel_hi:[1,0,1]
	v_pk_fma_f32 v[136:137], v[20:21], v[62:63], v[136:137] op_sel_hi:[1,0,1]
	v_pk_fma_f32 v[134:135], v[22:23], v[62:63], v[134:135] op_sel:[0,1,0] op_sel_hi:[1,1,1]
	v_pk_fma_f32 v[136:137], v[24:25], v[62:63], v[136:137] op_sel:[0,1,0] op_sel_hi:[1,1,1]
	v_pk_fma_f32 v[138:139], v[18:19], v[64:65], v[138:139] op_sel_hi:[1,0,1]
	v_pk_fma_f32 v[140:141], v[20:21], v[64:65], v[140:141] op_sel_hi:[1,0,1]
	v_pk_fma_f32 v[138:139], v[22:23], v[64:65], v[138:139] op_sel:[0,1,0] op_sel_hi:[1,1,1]
	v_pk_fma_f32 v[140:141], v[24:25], v[64:65], v[140:141] op_sel:[0,1,0] op_sel_hi:[1,1,1]
; #define LAS __attribute__((address_space(3)))
; __device__ void phase_setup(const Params& p, LAS unsigned char* lds) {
;     ...
;             for (int k = 0; k < D; k += 16) {
;                 f32x4 w[16];
; #pragma unroll
;                 for (int kk = 0; kk < 16; ++kk) w[kk] = *(const f32x4*)(wp + (size_t)(k + kk) * (NMOD * D));
; #pragma unroll
;                 for (int i = 0; i < 5; ++i) { const int r = (i < 4) ? wid + 8 * i : 32;
; #pragma unroll
;                     for (int k4 = 0; k4 < 4; ++k4) { const f32x4 s4 = *(const LAS f32x4*)(sc + r * D + k + 4 * k4);
;                         a[i] += s4[0] * w[4 * k4] + s4[1] * w[4 * k4 + 1] + s4[2] * w[4 * k4 + 2] + s4[3] * w[4 * k4 + 3]; } }
;             }
	v_pk_fma_f32 v[142:143], v[18:19], v[66:67], v[142:143] op_sel_hi:[1,0,1]
	v_pk_fma_f32 v[144:145], v[20:21], v[66:67], v[144:145] op_sel_hi:[1,0,1]
	v_pk_fma_f32 v[142:143], v[22:23], v[66:67], v[142:143] op_sel:[0,1,0] op_sel_hi:[1,1,1]
	v_pk_fma_f32 v[144:145], v[24:25], v[66:67], v[144:145] op_sel:[0,1,0] op_sel_hi:[1,1,1]
	v_pk_fma_f32 v[146:147], v[18:19], v[68:69], v[146:147] op_sel_hi:[1,0,1]
	v_pk_fma_f32 v[148:149], v[20:21], v[68:69], v[148:149] op_sel_hi:[1,0,1]
	v_pk_fma_f32 v[146:147], v[22:23], v[68:69], v[146:147] op_sel:[0,1,0] op_sel_hi:[1,1,1]
	v_pk_fma_f32 v[148:149], v[24:25], v[68:69], v[148:149] op_sel:[0,1,0] op_sel_hi:[1,1,1]
	v_pk_fma_f32 v[150:151], v[18:19], v[70:71], v[150:151] op_sel_hi:[1,0,1]
	v_pk_fma_f32 v[152:153], v[20:21], v[70:71], v[152:153] op_sel_hi:[1,0,1]
	v_pk_fma_f32 v[150:151], v[22:23], v[70:71], v[150:151] op_sel:[0,1,0] op_sel_hi:[1,1,1]
	v_pk_fma_f32 v[152:153], v[24:25], v[70:71], v[152:153] op_sel:[0,1,0] op_sel_hi:[1,1,1]
	v_pk_fma_f32 v[154:155], v[18:19], v[72:73], v[154:155] op_sel_hi:[1,0,1]
	v_pk_fma_f32 v[156:157], v[20:21], v[72:73], v[156:157] op_sel_hi:[1,0,1]
	v_pk_fma_f32 v[154:155], v[22:23], v[72:73], v[154:155] op_sel:[0,1,0] op_sel_hi:[1,1,1]
	v_pk_fma_f32 v[156:157], v[24:25], v[72:73], v[156:157] op_sel:[0,1,0] op_sel_hi:[1,1,1]
	v_pk_fma_f32 v[158:159], v[18:19], v[74:75], v[158:159] op_sel_hi:[1,0,1]
	v_pk_fma_f32 v[160:161], v[20:21], v[74:75], v[160:161] op_sel_hi:[1,0,1]
	v_pk_fma_f32 v[158:159], v[22:23], v[74:75], v[158:159] op_sel:[0,1,0] op_sel_hi:[1,1,1]
	v_pk_fma_f32 v[160:161], v[24:25], v[74:75], v[160:161] op_sel:[0,1,0] op_sel_hi:[1,1,1]
	v_pk_fma_f32 v[162:163], v[18:19], v[76:77], v[162:163] op_sel_hi:[1,0,1]
	v_pk_fma_f32 v[164:165], v[20:21], v[76:77], v[164:165] op_sel_hi:[1,0,1]
	v_pk_fma_f32 v[162:163], v[22:23], v[76:77], v[162:163] op_sel:[0,1,0] op_sel_hi:[1,1,1]
	v_pk_fma_f32 v[164:165], v[24:25], v[76:77], v[164:165] op_sel:[0,1,0] op_sel_hi:[1,1,1]
	ds_read_b64 v[56:57], v211 offset:64
	ds_read_b64 v[58:59], v211 offset:4160
	ds_read_b64 v[60:61], v211 offset:8256
	ds_read_b64 v[62:63], v211 offset:12352
	ds_read_b64 v[64:65], v211 offset:16448
	ds_read_b64 v[66:67], v211 offset:20544
	ds_read_b64 v[68:69], v211 offset:24640
	ds_read_b64 v[70:71], v211 offset:28736
	ds_read_b64 v[72:73], v211 offset:32832
	ds_read_b64 v[74:75], v211 offset:36928
	ds_read_b64 v[76:77], v211 offset:41024
	v_add_u32_e32 v211, 64, v211
	v_add_u32_e32 v212, 64, v212
	v_add_u32_e32 v213, 64, v213
	s_waitcnt lgkmcnt(11)
	v_pk_fma_f32 v[166:167], v[18:19], v[34:35], v[166:167] op_sel_hi:[1,0,1]
	v_pk_fma_f32 v[168:169], v[20:21], v[34:35], v[168:169] op_sel_hi:[1,0,1]
	v_pk_fma_f32 v[166:167], v[22:23], v[34:35], v[166:167] op_sel:[0,1,0] op_sel_hi:[1,1,1]
	v_pk_fma_f32 v[168:169], v[24:25], v[34:35], v[168:169] op_sel:[0,1,0] op_sel_hi:[1,1,1]
	v_pk_fma_f32 v[170:171], v[18:19], v[36:37], v[170:171] op_sel_hi:[1,0,1]
	v_pk_fma_f32 v[172:173], v[20:21], v[36:37], v[172:173] op_sel_hi:[1,0,1]
	v_pk_fma_f32 v[170:171], v[22:23], v[36:37], v[170:171] op_sel:[0,1,0] op_sel_hi:[1,1,1]
	v_pk_fma_f32 v[172:173], v[24:25], v[36:37], v[172:173] op_sel:[0,1,0] op_sel_hi:[1,1,1]
	v_pk_fma_f32 v[174:175], v[18:19], v[38:39], v[174:175] op_sel_hi:[1,0,1]
	v_pk_fma_f32 v[176:177], v[20:21], v[38:39], v[176:177] op_sel_hi:[1,0,1]
	v_pk_fma_f32 v[174:175], v[22:23], v[38:39], v[174:175] op_sel:[0,1,0] op_sel_hi:[1,1,1]
	v_pk_fma_f32 v[176:177], v[24:25], v[38:39], v[176:177] op_sel:[0,1,0] op_sel_hi:[1,1,1]
	v_pk_fma_f32 v[178:179], v[18:19], v[40:41], v[178:179] op_sel_hi:[1,0,1]
	v_pk_fma_f32 v[180:181], v[20:21], v[40:41], v[180:181] op_sel_hi:[1,0,1]
	v_pk_fma_f32 v[178:179], v[22:23], v[40:41], v[178:179] op_sel:[0,1,0] op_sel_hi:[1,1,1]
	v_pk_fma_f32 v[180:181], v[24:25], v[40:41], v[180:181] op_sel:[0,1,0] op_sel_hi:[1,1,1]
	v_pk_fma_f32 v[182:183], v[18:19], v[42:43], v[182:183] op_sel_hi:[1,0,1]
	v_pk_fma_f32 v[184:185], v[20:21], v[42:43], v[184:185] op_sel_hi:[1,0,1]
	v_pk_fma_f32 v[182:183], v[22:23], v[42:43], v[182:183] op_sel:[0,1,0] op_sel_hi:[1,1,1]
	v_pk_fma_f32 v[184:185], v[24:25], v[42:43], v[184:185] op_sel:[0,1,0] op_sel_hi:[1,1,1]
	v_pk_fma_f32 v[186:187], v[18:19], v[44:45], v[186:187] op_sel_hi:[1,0,1]
	v_pk_fma_f32 v[188:189], v[20:21], v[44:45], v[188:189] op_sel_hi:[1,0,1]
	v_pk_fma_f32 v[186:187], v[22:23], v[44:45], v[186:187] op_sel:[0,1,0] op_sel_hi:[1,1,1]
	v_pk_fma_f32 v[188:189], v[24:25], v[44:45], v[188:189] op_sel:[0,1,0] op_sel_hi:[1,1,1]
	v_pk_fma_f32 v[190:191], v[18:19], v[46:47], v[190:191] op_sel_hi:[1,0,1]
	v_pk_fma_f32 v[192:193], v[20:21], v[46:47], v[192:193] op_sel_hi:[1,0,1]
	v_pk_fma_f32 v[190:191], v[22:23], v[46:47], v[190:191] op_sel:[0,1,0] op_sel_hi:[1,1,1]
	v_pk_fma_f32 v[192:193], v[24:25], v[46:47], v[192:193] op_sel:[0,1,0] op_sel_hi:[1,1,1]
	v_pk_fma_f32 v[194:195], v[18:19], v[48:49], v[194:195] op_sel_hi:[1,0,1]
	v_pk_fma_f32 v[196:197], v[20:21], v[48:49], v[196:197] op_sel_hi:[1,0,1]
	v_pk_fma_f32 v[194:195], v[22:23], v[48:49], v[194:195] op_sel:[0,1,0] op_sel_hi:[1,1,1]
	v_pk_fma_f32 v[196:197], v[24:25], v[48:49], v[196:197] op_sel:[0,1,0] op_sel_hi:[1,1,1]
	v_pk_fma_f32 v[198:199], v[18:19], v[50:51], v[198:199] op_sel_hi:[1,0,1]
	v_pk_fma_f32 v[200:201], v[20:21], v[50:51], v[200:201] op_sel_hi:[1,0,1]
	v_pk_fma_f32 v[198:199], v[22:23], v[50:51], v[198:199] op_sel:[0,1,0] op_sel_hi:[1,1,1]
	v_pk_fma_f32 v[200:201], v[24:25], v[50:51], v[200:201] op_sel:[0,1,0] op_sel_hi:[1,1,1]
	v_pk_fma_f32 v[202:203], v[18:19], v[52:53], v[202:203] op_sel_hi:[1,0,1]
	v_pk_fma_f32 v[204:205], v[20:21], v[52:53], v[204:205] op_sel_hi:[1,0,1]
	v_pk_fma_f32 v[202:203], v[22:23], v[52:53], v[202:203] op_sel:[0,1,0] op_sel_hi:[1,1,1]
	v_pk_fma_f32 v[204:205], v[24:25], v[52:53], v[204:205] op_sel:[0,1,0] op_sel_hi:[1,1,1]
	v_pk_fma_f32 v[206:207], v[18:19], v[54:55], v[206:207] op_sel_hi:[1,0,1]
	v_pk_fma_f32 v[208:209], v[20:21], v[54:55], v[208:209] op_sel_hi:[1,0,1]
	v_pk_fma_f32 v[206:207], v[22:23], v[54:55], v[206:207] op_sel:[0,1,0] op_sel_hi:[1,1,1]
	v_pk_fma_f32 v[208:209], v[24:25], v[54:55], v[208:209] op_sel:[0,1,0] op_sel_hi:[1,1,1]
	global_load_dwordx4 v[18:21], v0, s[6:7]
	v_add_u32_e32 v214, 0x9000, v0
	global_load_dwordx4 v[22:25], v214, s[6:7]
	v_add_u32_e32 v0, 0x90000, v0
	ds_read_b64 v[34:35], v211 offset:45056
	ds_read_b64 v[36:37], v211 offset:49152
	ds_read_b64 v[38:39], v211 offset:53248
	ds_read_b64 v[40:41], v211 offset:57344
	ds_read_b64 v[42:43], v211 offset:61440
	ds_read_b64 v[44:45], v212
	ds_read_b64 v[46:47], v212 offset:4096
	ds_read_b64 v[48:49], v212 offset:8192
	ds_read_b64 v[50:51], v212 offset:12288
	ds_read_b64 v[52:53], v212 offset:16384
	ds_read_b64 v[54:55], v212 offset:20480
	s_waitcnt vmcnt(6) lgkmcnt(11)
; #define LAS __attribute__((address_space(3)))
; __device__ void phase_setup(const Params& p, LAS unsigned char* lds) {
;     ...
;             for (int k = 0; k < D; k += 16) {
;                 f32x4 w[16];
; #pragma unroll
;                 for (int kk = 0; kk < 16; ++kk) w[kk] = *(const f32x4*)(wp + (size_t)(k + kk) * (NMOD * D));
; #pragma unroll
;                 for (int i = 0; i < 5; ++i) { const int r = (i < 4) ? wid + 8 * i : 32;
; #pragma unroll
;                     for (int k4 = 0; k4 < 4; ++k4) { const f32x4 s4 = *(const LAS f32x4*)(sc + r * D + k + 4 * k4);
;                         a[i] += s4[0] * w[4 * k4] + s4[1] * w[4 * k4 + 1] + s4[2] * w[4 * k4 + 2] + s4[3] * w[4 * k4 + 3]; } }
;             }
	v_pk_fma_f32 v[78:79], v[26:27], v[56:57], v[78:79] op_sel_hi:[1,0,1]
	v_pk_fma_f32 v[80:81], v[28:29], v[56:57], v[80:81] op_sel_hi:[1,0,1]
	v_pk_fma_f32 v[78:79], v[30:31], v[56:57], v[78:79] op_sel:[0,1,0] op_sel_hi:[1,1,1]
	v_pk_fma_f32 v[80:81], v[32:33], v[56:57], v[80:81] op_sel:[0,1,0] op_sel_hi:[1,1,1]
	v_pk_fma_f32 v[82:83], v[26:27], v[58:59], v[82:83] op_sel_hi:[1,0,1]
	v_pk_fma_f32 v[84:85], v[28:29], v[58:59], v[84:85] op_sel_hi:[1,0,1]
	v_pk_fma_f32 v[82:83], v[30:31], v[58:59], v[82:83] op_sel:[0,1,0] op_sel_hi:[1,1,1]
	v_pk_fma_f32 v[84:85], v[32:33], v[58:59], v[84:85] op_sel:[0,1,0] op_sel_hi:[1,1,1]
	v_pk_fma_f32 v[86:87], v[26:27], v[60:61], v[86:87] op_sel_hi:[1,0,1]
	v_pk_fma_f32 v[88:89], v[28:29], v[60:61], v[88:89] op_sel_hi:[1,0,1]
	v_pk_fma_f32 v[86:87], v[30:31], v[60:61], v[86:87] op_sel:[0,1,0] op_sel_hi:[1,1,1]
	v_pk_fma_f32 v[88:89], v[32:33], v[60:61], v[88:89] op_sel:[0,1,0] op_sel_hi:[1,1,1]
	v_pk_fma_f32 v[90:91], v[26:27], v[62:63], v[90:91] op_sel_hi:[1,0,1]
	v_pk_fma_f32 v[92:93], v[28:29], v[62:63], v[92:93] op_sel_hi:[1,0,1]
	v_pk_fma_f32 v[90:91], v[30:31], v[62:63], v[90:91] op_sel:[0,1,0] op_sel_hi:[1,1,1]
	v_pk_fma_f32 v[92:93], v[32:33], v[62:63], v[92:93] op_sel:[0,1,0] op_sel_hi:[1,1,1]
	v_pk_fma_f32 v[94:95], v[26:27], v[64:65], v[94:95] op_sel_hi:[1,0,1]
	v_pk_fma_f32 v[96:97], v[28:29], v[64:65], v[96:97] op_sel_hi:[1,0,1]
	v_pk_fma_f32 v[94:95], v[30:31], v[64:65], v[94:95] op_sel:[0,1,0] op_sel_hi:[1,1,1]
	v_pk_fma_f32 v[96:97], v[32:33], v[64:65], v[96:97] op_sel:[0,1,0] op_sel_hi:[1,1,1]
	v_pk_fma_f32 v[98:99], v[26:27], v[66:67], v[98:99] op_sel_hi:[1,0,1]
	v_pk_fma_f32 v[100:101], v[28:29], v[66:67], v[100:101] op_sel_hi:[1,0,1]
	v_pk_fma_f32 v[98:99], v[30:31], v[66:67], v[98:99] op_sel:[0,1,0] op_sel_hi:[1,1,1]
	v_pk_fma_f32 v[100:101], v[32:33], v[66:67], v[100:101] op_sel:[0,1,0] op_sel_hi:[1,1,1]
	v_pk_fma_f32 v[102:103], v[26:27], v[68:69], v[102:103] op_sel_hi:[1,0,1]
	v_pk_fma_f32 v[104:105], v[28:29], v[68:69], v[104:105] op_sel_hi:[1,0,1]
	v_pk_fma_f32 v[102:103], v[30:31], v[68:69], v[102:103] op_sel:[0,1,0] op_sel_hi:[1,1,1]
	v_pk_fma_f32 v[104:105], v[32:33], v[68:69], v[104:105] op_sel:[0,1,0] op_sel_hi:[1,1,1]
	v_pk_fma_f32 v[106:107], v[26:27], v[70:71], v[106:107] op_sel_hi:[1,0,1]
	v_pk_fma_f32 v[108:109], v[28:29], v[70:71], v[108:109] op_sel_hi:[1,0,1]
	v_pk_fma_f32 v[106:107], v[30:31], v[70:71], v[106:107] op_sel:[0,1,0] op_sel_hi:[1,1,1]
	v_pk_fma_f32 v[108:109], v[32:33], v[70:71], v[108:109] op_sel:[0,1,0] op_sel_hi:[1,1,1]
	v_pk_fma_f32 v[110:111], v[26:27], v[72:73], v[110:111] op_sel_hi:[1,0,1]
	v_pk_fma_f32 v[112:113], v[28:29], v[72:73], v[112:113] op_sel_hi:[1,0,1]
	v_pk_fma_f32 v[110:111], v[30:31], v[72:73], v[110:111] op_sel:[0,1,0] op_sel_hi:[1,1,1]
	v_pk_fma_f32 v[112:113], v[32:33], v[72:73], v[112:113] op_sel:[0,1,0] op_sel_hi:[1,1,1]
	v_pk_fma_f32 v[114:115], v[26:27], v[74:75], v[114:115] op_sel_hi:[1,0,1]
	v_pk_fma_f32 v[116:117], v[28:29], v[74:75], v[116:117] op_sel_hi:[1,0,1]
	v_pk_fma_f32 v[114:115], v[30:31], v[74:75], v[114:115] op_sel:[0,1,0] op_sel_hi:[1,1,1]
	v_pk_fma_f32 v[116:117], v[32:33], v[74:75], v[116:117] op_sel:[0,1,0] op_sel_hi:[1,1,1]
	v_pk_fma_f32 v[118:119], v[26:27], v[76:77], v[118:119] op_sel_hi:[1,0,1]
	v_pk_fma_f32 v[120:121], v[28:29], v[76:77], v[120:121] op_sel_hi:[1,0,1]
	v_pk_fma_f32 v[118:119], v[30:31], v[76:77], v[118:119] op_sel:[0,1,0] op_sel_hi:[1,1,1]
	v_pk_fma_f32 v[120:121], v[32:33], v[76:77], v[120:121] op_sel:[0,1,0] op_sel_hi:[1,1,1]
	ds_read_b64 v[56:57], v212 offset:24576
	ds_read_b64 v[58:59], v212 offset:28672
	ds_read_b64 v[60:61], v212 offset:32768
	ds_read_b64 v[62:63], v212 offset:36864
	ds_read_b64 v[64:65], v212 offset:40960
	ds_read_b64 v[66:67], v212 offset:45056
	ds_read_b64 v[68:69], v212 offset:49152
	ds_read_b64 v[70:71], v212 offset:53248
	ds_read_b64 v[72:73], v212 offset:57344
	ds_read_b64 v[74:75], v212 offset:61440
	ds_read_b64 v[76:77], v213
	s_waitcnt lgkmcnt(11)
	v_pk_fma_f32 v[122:123], v[26:27], v[34:35], v[122:123] op_sel_hi:[1,0,1]
	v_pk_fma_f32 v[124:125], v[28:29], v[34:35], v[124:125] op_sel_hi:[1,0,1]
	v_pk_fma_f32 v[122:123], v[30:31], v[34:35], v[122:123] op_sel:[0,1,0] op_sel_hi:[1,1,1]
	v_pk_fma_f32 v[124:125], v[32:33], v[34:35], v[124:125] op_sel:[0,1,0] op_sel_hi:[1,1,1]
	v_pk_fma_f32 v[126:127], v[26:27], v[36:37], v[126:127] op_sel_hi:[1,0,1]
	v_pk_fma_f32 v[128:129], v[28:29], v[36:37], v[128:129] op_sel_hi:[1,0,1]
	v_pk_fma_f32 v[126:127], v[30:31], v[36:37], v[126:127] op_sel:[0,1,0] op_sel_hi:[1,1,1]
	v_pk_fma_f32 v[128:129], v[32:33], v[36:37], v[128:129] op_sel:[0,1,0] op_sel_hi:[1,1,1]
	v_pk_fma_f32 v[130:131], v[26:27], v[38:39], v[130:131] op_sel_hi:[1,0,1]
	v_pk_fma_f32 v[132:133], v[28:29], v[38:39], v[132:133] op_sel_hi:[1,0,1]
	v_pk_fma_f32 v[130:131], v[30:31], v[38:39], v[130:131] op_sel:[0,1,0] op_sel_hi:[1,1,1]
	v_pk_fma_f32 v[132:133], v[32:33], v[38:39], v[132:133] op_sel:[0,1,0] op_sel_hi:[1,1,1]
	v_pk_fma_f32 v[134:135], v[26:27], v[40:41], v[134:135] op_sel_hi:[1,0,1]
	v_pk_fma_f32 v[136:137], v[28:29], v[40:41], v[136:137] op_sel_hi:[1,0,1]
	v_pk_fma_f32 v[134:135], v[30:31], v[40:41], v[134:135] op_sel:[0,1,0] op_sel_hi:[1,1,1]
	v_pk_fma_f32 v[136:137], v[32:33], v[40:41], v[136:137] op_sel:[0,1,0] op_sel_hi:[1,1,1]
	v_pk_fma_f32 v[138:139], v[26:27], v[42:43], v[138:139] op_sel_hi:[1,0,1]
	v_pk_fma_f32 v[140:141], v[28:29], v[42:43], v[140:141] op_sel_hi:[1,0,1]
	v_pk_fma_f32 v[138:139], v[30:31], v[42:43], v[138:139] op_sel:[0,1,0] op_sel_hi:[1,1,1]
	v_pk_fma_f32 v[140:141], v[32:33], v[42:43], v[140:141] op_sel:[0,1,0] op_sel_hi:[1,1,1]
; #define LAS __attribute__((address_space(3)))
; __device__ void phase_setup(const Params& p, LAS unsigned char* lds) {
;     ...
;             for (int k = 0; k < D; k += 16) {
;                 f32x4 w[16];
; #pragma unroll
;                 for (int kk = 0; kk < 16; ++kk) w[kk] = *(const f32x4*)(wp + (size_t)(k + kk) * (NMOD * D));
; #pragma unroll
;                 for (int i = 0; i < 5; ++i) { const int r = (i < 4) ? wid + 8 * i : 32;
; #pragma unroll
;                     for (int k4 = 0; k4 < 4; ++k4) { const f32x4 s4 = *(const LAS f32x4*)(sc + r * D + k + 4 * k4);
;                         a[i] += s4[0] * w[4 * k4] + s4[1] * w[4 * k4 + 1] + s4[2] * w[4 * k4 + 2] + s4[3] * w[4 * k4 + 3]; } }
;             }
	v_pk_fma_f32 v[142:143], v[26:27], v[44:45], v[142:143] op_sel_hi:[1,0,1]
	v_pk_fma_f32 v[144:145], v[28:29], v[44:45], v[144:145] op_sel_hi:[1,0,1]
	v_pk_fma_f32 v[142:143], v[30:31], v[44:45], v[142:143] op_sel:[0,1,0] op_sel_hi:[1,1,1]
	v_pk_fma_f32 v[144:145], v[32:33], v[44:45], v[144:145] op_sel:[0,1,0] op_sel_hi:[1,1,1]
	v_pk_fma_f32 v[146:147], v[26:27], v[46:47], v[146:147] op_sel_hi:[1,0,1]
	v_pk_fma_f32 v[148:149], v[28:29], v[46:47], v[148:149] op_sel_hi:[1,0,1]
	v_pk_fma_f32 v[146:147], v[30:31], v[46:47], v[146:147] op_sel:[0,1,0] op_sel_hi:[1,1,1]
	v_pk_fma_f32 v[148:149], v[32:33], v[46:47], v[148:149] op_sel:[0,1,0] op_sel_hi:[1,1,1]
	v_pk_fma_f32 v[150:151], v[26:27], v[48:49], v[150:151] op_sel_hi:[1,0,1]
	v_pk_fma_f32 v[152:153], v[28:29], v[48:49], v[152:153] op_sel_hi:[1,0,1]
	v_pk_fma_f32 v[150:151], v[30:31], v[48:49], v[150:151] op_sel:[0,1,0] op_sel_hi:[1,1,1]
	v_pk_fma_f32 v[152:153], v[32:33], v[48:49], v[152:153] op_sel:[0,1,0] op_sel_hi:[1,1,1]
	v_pk_fma_f32 v[154:155], v[26:27], v[50:51], v[154:155] op_sel_hi:[1,0,1]
	v_pk_fma_f32 v[156:157], v[28:29], v[50:51], v[156:157] op_sel_hi:[1,0,1]
	v_pk_fma_f32 v[154:155], v[30:31], v[50:51], v[154:155] op_sel:[0,1,0] op_sel_hi:[1,1,1]
	v_pk_fma_f32 v[156:157], v[32:33], v[50:51], v[156:157] op_sel:[0,1,0] op_sel_hi:[1,1,1]
	v_pk_fma_f32 v[158:159], v[26:27], v[52:53], v[158:159] op_sel_hi:[1,0,1]
	v_pk_fma_f32 v[160:161], v[28:29], v[52:53], v[160:161] op_sel_hi:[1,0,1]
	v_pk_fma_f32 v[158:159], v[30:31], v[52:53], v[158:159] op_sel:[0,1,0] op_sel_hi:[1,1,1]
	v_pk_fma_f32 v[160:161], v[32:33], v[52:53], v[160:161] op_sel:[0,1,0] op_sel_hi:[1,1,1]
	v_pk_fma_f32 v[162:163], v[26:27], v[54:55], v[162:163] op_sel_hi:[1,0,1]
	v_pk_fma_f32 v[164:165], v[28:29], v[54:55], v[164:165] op_sel_hi:[1,0,1]
	v_pk_fma_f32 v[162:163], v[30:31], v[54:55], v[162:163] op_sel:[0,1,0] op_sel_hi:[1,1,1]
	v_pk_fma_f32 v[164:165], v[32:33], v[54:55], v[164:165] op_sel:[0,1,0] op_sel_hi:[1,1,1]
	ds_read_b64 v[34:35], v211 offset:64
	ds_read_b64 v[36:37], v211 offset:4160
	ds_read_b64 v[38:39], v211 offset:8256
	ds_read_b64 v[40:41], v211 offset:12352
	ds_read_b64 v[42:43], v211 offset:16448
	ds_read_b64 v[44:45], v211 offset:20544
	ds_read_b64 v[46:47], v211 offset:24640
	ds_read_b64 v[48:49], v211 offset:28736
	ds_read_b64 v[50:51], v211 offset:32832
	ds_read_b64 v[52:53], v211 offset:36928
	ds_read_b64 v[54:55], v211 offset:41024
	v_add_u32_e32 v211, 64, v211
	v_add_u32_e32 v212, 64, v212
	v_add_u32_e32 v213, 64, v213
	s_waitcnt lgkmcnt(11)
	v_pk_fma_f32 v[166:167], v[26:27], v[56:57], v[166:167] op_sel_hi:[1,0,1]
	v_pk_fma_f32 v[168:169], v[28:29], v[56:57], v[168:169] op_sel_hi:[1,0,1]
	v_pk_fma_f32 v[166:167], v[30:31], v[56:57], v[166:167] op_sel:[0,1,0] op_sel_hi:[1,1,1]
	v_pk_fma_f32 v[168:169], v[32:33], v[56:57], v[168:169] op_sel:[0,1,0] op_sel_hi:[1,1,1]
	v_pk_fma_f32 v[170:171], v[26:27], v[58:59], v[170:171] op_sel_hi:[1,0,1]
	v_pk_fma_f32 v[172:173], v[28:29], v[58:59], v[172:173] op_sel_hi:[1,0,1]
	v_pk_fma_f32 v[170:171], v[30:31], v[58:59], v[170:171] op_sel:[0,1,0] op_sel_hi:[1,1,1]
	v_pk_fma_f32 v[172:173], v[32:33], v[58:59], v[172:173] op_sel:[0,1,0] op_sel_hi:[1,1,1]
	v_pk_fma_f32 v[174:175], v[26:27], v[60:61], v[174:175] op_sel_hi:[1,0,1]
	v_pk_fma_f32 v[176:177], v[28:29], v[60:61], v[176:177] op_sel_hi:[1,0,1]
	v_pk_fma_f32 v[174:175], v[30:31], v[60:61], v[174:175] op_sel:[0,1,0] op_sel_hi:[1,1,1]
	v_pk_fma_f32 v[176:177], v[32:33], v[60:61], v[176:177] op_sel:[0,1,0] op_sel_hi:[1,1,1]
	v_pk_fma_f32 v[178:179], v[26:27], v[62:63], v[178:179] op_sel_hi:[1,0,1]
	v_pk_fma_f32 v[180:181], v[28:29], v[62:63], v[180:181] op_sel_hi:[1,0,1]
	v_pk_fma_f32 v[178:179], v[30:31], v[62:63], v[178:179] op_sel:[0,1,0] op_sel_hi:[1,1,1]
	v_pk_fma_f32 v[180:181], v[32:33], v[62:63], v[180:181] op_sel:[0,1,0] op_sel_hi:[1,1,1]
	v_pk_fma_f32 v[182:183], v[26:27], v[64:65], v[182:183] op_sel_hi:[1,0,1]
	v_pk_fma_f32 v[184:185], v[28:29], v[64:65], v[184:185] op_sel_hi:[1,0,1]
	v_pk_fma_f32 v[182:183], v[30:31], v[64:65], v[182:183] op_sel:[0,1,0] op_sel_hi:[1,1,1]
	v_pk_fma_f32 v[184:185], v[32:33], v[64:65], v[184:185] op_sel:[0,1,0] op_sel_hi:[1,1,1]
	v_pk_fma_f32 v[186:187], v[26:27], v[66:67], v[186:187] op_sel_hi:[1,0,1]
	v_pk_fma_f32 v[188:189], v[28:29], v[66:67], v[188:189] op_sel_hi:[1,0,1]
	v_pk_fma_f32 v[186:187], v[30:31], v[66:67], v[186:187] op_sel:[0,1,0] op_sel_hi:[1,1,1]
	v_pk_fma_f32 v[188:189], v[32:33], v[66:67], v[188:189] op_sel:[0,1,0] op_sel_hi:[1,1,1]
	v_pk_fma_f32 v[190:191], v[26:27], v[68:69], v[190:191] op_sel_hi:[1,0,1]
	v_pk_fma_f32 v[192:193], v[28:29], v[68:69], v[192:193] op_sel_hi:[1,0,1]
	v_pk_fma_f32 v[190:191], v[30:31], v[68:69], v[190:191] op_sel:[0,1,0] op_sel_hi:[1,1,1]
	v_pk_fma_f32 v[192:193], v[32:33], v[68:69], v[192:193] op_sel:[0,1,0] op_sel_hi:[1,1,1]
	v_pk_fma_f32 v[194:195], v[26:27], v[70:71], v[194:195] op_sel_hi:[1,0,1]
	v_pk_fma_f32 v[196:197], v[28:29], v[70:71], v[196:197] op_sel_hi:[1,0,1]
	v_pk_fma_f32 v[194:195], v[30:31], v[70:71], v[194:195] op_sel:[0,1,0] op_sel_hi:[1,1,1]
	v_pk_fma_f32 v[196:197], v[32:33], v[70:71], v[196:197] op_sel:[0,1,0] op_sel_hi:[1,1,1]
	v_pk_fma_f32 v[198:199], v[26:27], v[72:73], v[198:199] op_sel_hi:[1,0,1]
	v_pk_fma_f32 v[200:201], v[28:29], v[72:73], v[200:201] op_sel_hi:[1,0,1]
	v_pk_fma_f32 v[198:199], v[30:31], v[72:73], v[198:199] op_sel:[0,1,0] op_sel_hi:[1,1,1]
	v_pk_fma_f32 v[200:201], v[32:33], v[72:73], v[200:201] op_sel:[0,1,0] op_sel_hi:[1,1,1]
	v_pk_fma_f32 v[202:203], v[26:27], v[74:75], v[202:203] op_sel_hi:[1,0,1]
	v_pk_fma_f32 v[204:205], v[28:29], v[74:75], v[204:205] op_sel_hi:[1,0,1]
	v_pk_fma_f32 v[202:203], v[30:31], v[74:75], v[202:203] op_sel:[0,1,0] op_sel_hi:[1,1,1]
	v_pk_fma_f32 v[204:205], v[32:33], v[74:75], v[204:205] op_sel:[0,1,0] op_sel_hi:[1,1,1]
	v_pk_fma_f32 v[206:207], v[26:27], v[76:77], v[206:207] op_sel_hi:[1,0,1]
	v_pk_fma_f32 v[208:209], v[28:29], v[76:77], v[208:209] op_sel_hi:[1,0,1]
	v_pk_fma_f32 v[206:207], v[30:31], v[76:77], v[206:207] op_sel:[0,1,0] op_sel_hi:[1,1,1]
	v_pk_fma_f32 v[208:209], v[32:33], v[76:77], v[208:209] op_sel:[0,1,0] op_sel_hi:[1,1,1]
	s_add_u32 s11, s11, 1
	s_cmp_lt_u32 s11, 15
	s_cbranch_scc1 .Lgv_loop
; #define LAS __attribute__((address_space(3)))
; __device__ void phase_setup(const Params& p, LAS unsigned char* lds) {
;     ...
;             for (int k = 0; k < D; k += 16) {
;                 f32x4 w[16];
; #pragma unroll
;                 for (int kk = 0; kk < 16; ++kk) w[kk] = *(const f32x4*)(wp + (size_t)(k + kk) * (NMOD * D));
; #pragma unroll
;                 for (int i = 0; i < 5; ++i) { const int r = (i < 4) ? wid + 8 * i : 32;
; #pragma unroll
;                     for (int k4 = 0; k4 < 4; ++k4) { const f32x4 s4 = *(const LAS f32x4*)(sc + r * D + k + 4 * k4);
;                         a[i] += s4[0] * w[4 * k4] + s4[1] * w[4 * k4 + 1] + s4[2] * w[4 * k4 + 2] + s4[3] * w[4 * k4 + 3]; } }
	global_load_dwordx4 v[26:29], v0, s[6:7]
	v_add_u32_e32 v214, 0x9000, v0
	global_load_dwordx4 v[30:33], v214, s[6:7]
	v_add_u32_e32 v0, 0x90000, v0
	ds_read_b64 v[56:57], v211 offset:45056
	ds_read_b64 v[58:59], v211 offset:49152
	ds_read_b64 v[60:61], v211 offset:53248
	ds_read_b64 v[62:63], v211 offset:57344
	ds_read_b64 v[64:65], v211 offset:61440
	ds_read_b64 v[66:67], v212
	ds_read_b64 v[68:69], v212 offset:4096
	ds_read_b64 v[70:71], v212 offset:8192
	ds_read_b64 v[72:73], v212 offset:12288
	ds_read_b64 v[74:75], v212 offset:16384
	ds_read_b64 v[76:77], v212 offset:20480
	s_waitcnt vmcnt(6) lgkmcnt(11)
	v_pk_fma_f32 v[78:79], v[2:3], v[34:35], v[78:79] op_sel_hi:[1,0,1]
	v_pk_fma_f32 v[80:81], v[4:5], v[34:35], v[80:81] op_sel_hi:[1,0,1]
	v_pk_fma_f32 v[78:79], v[6:7], v[34:35], v[78:79] op_sel:[0,1,0] op_sel_hi:[1,1,1]
	v_pk_fma_f32 v[80:81], v[8:9], v[34:35], v[80:81] op_sel:[0,1,0] op_sel_hi:[1,1,1]
	v_pk_fma_f32 v[82:83], v[2:3], v[36:37], v[82:83] op_sel_hi:[1,0,1]
	v_pk_fma_f32 v[84:85], v[4:5], v[36:37], v[84:85] op_sel_hi:[1,0,1]
	v_pk_fma_f32 v[82:83], v[6:7], v[36:37], v[82:83] op_sel:[0,1,0] op_sel_hi:[1,1,1]
	v_pk_fma_f32 v[84:85], v[8:9], v[36:37], v[84:85] op_sel:[0,1,0] op_sel_hi:[1,1,1]
	v_pk_fma_f32 v[86:87], v[2:3], v[38:39], v[86:87] op_sel_hi:[1,0,1]
	v_pk_fma_f32 v[88:89], v[4:5], v[38:39], v[88:89] op_sel_hi:[1,0,1]
	v_pk_fma_f32 v[86:87], v[6:7], v[38:39], v[86:87] op_sel:[0,1,0] op_sel_hi:[1,1,1]
	v_pk_fma_f32 v[88:89], v[8:9], v[38:39], v[88:89] op_sel:[0,1,0] op_sel_hi:[1,1,1]
	v_pk_fma_f32 v[90:91], v[2:3], v[40:41], v[90:91] op_sel_hi:[1,0,1]
	v_pk_fma_f32 v[92:93], v[4:5], v[40:41], v[92:93] op_sel_hi:[1,0,1]
	v_pk_fma_f32 v[90:91], v[6:7], v[40:41], v[90:91] op_sel:[0,1,0] op_sel_hi:[1,1,1]
	v_pk_fma_f32 v[92:93], v[8:9], v[40:41], v[92:93] op_sel:[0,1,0] op_sel_hi:[1,1,1]
	v_pk_fma_f32 v[94:95], v[2:3], v[42:43], v[94:95] op_sel_hi:[1,0,1]
	v_pk_fma_f32 v[96:97], v[4:5], v[42:43], v[96:97] op_sel_hi:[1,0,1]
	v_pk_fma_f32 v[94:95], v[6:7], v[42:43], v[94:95] op_sel:[0,1,0] op_sel_hi:[1,1,1]
	v_pk_fma_f32 v[96:97], v[8:9], v[42:43], v[96:97] op_sel:[0,1,0] op_sel_hi:[1,1,1]
	v_pk_fma_f32 v[98:99], v[2:3], v[44:45], v[98:99] op_sel_hi:[1,0,1]
	v_pk_fma_f32 v[100:101], v[4:5], v[44:45], v[100:101] op_sel_hi:[1,0,1]
	v_pk_fma_f32 v[98:99], v[6:7], v[44:45], v[98:99] op_sel:[0,1,0] op_sel_hi:[1,1,1]
	v_pk_fma_f32 v[100:101], v[8:9], v[44:45], v[100:101] op_sel:[0,1,0] op_sel_hi:[1,1,1]
	v_pk_fma_f32 v[102:103], v[2:3], v[46:47], v[102:103] op_sel_hi:[1,0,1]
	v_pk_fma_f32 v[104:105], v[4:5], v[46:47], v[104:105] op_sel_hi:[1,0,1]
	v_pk_fma_f32 v[102:103], v[6:7], v[46:47], v[102:103] op_sel:[0,1,0] op_sel_hi:[1,1,1]
	v_pk_fma_f32 v[104:105], v[8:9], v[46:47], v[104:105] op_sel:[0,1,0] op_sel_hi:[1,1,1]
	v_pk_fma_f32 v[106:107], v[2:3], v[48:49], v[106:107] op_sel_hi:[1,0,1]
	v_pk_fma_f32 v[108:109], v[4:5], v[48:49], v[108:109] op_sel_hi:[1,0,1]
	v_pk_fma_f32 v[106:107], v[6:7], v[48:49], v[106:107] op_sel:[0,1,0] op_sel_hi:[1,1,1]
	v_pk_fma_f32 v[108:109], v[8:9], v[48:49], v[108:109] op_sel:[0,1,0] op_sel_hi:[1,1,1]
	v_pk_fma_f32 v[110:111], v[2:3], v[50:51], v[110:111] op_sel_hi:[1,0,1]
	v_pk_fma_f32 v[112:113], v[4:5], v[50:51], v[112:113] op_sel_hi:[1,0,1]
	v_pk_fma_f32 v[110:111], v[6:7], v[50:51], v[110:111] op_sel:[0,1,0] op_sel_hi:[1,1,1]
	v_pk_fma_f32 v[112:113], v[8:9], v[50:51], v[112:113] op_sel:[0,1,0] op_sel_hi:[1,1,1]
	v_pk_fma_f32 v[114:115], v[2:3], v[52:53], v[114:115] op_sel_hi:[1,0,1]
	v_pk_fma_f32 v[116:117], v[4:5], v[52:53], v[116:117] op_sel_hi:[1,0,1]
	v_pk_fma_f32 v[114:115], v[6:7], v[52:53], v[114:115] op_sel:[0,1,0] op_sel_hi:[1,1,1]
	v_pk_fma_f32 v[116:117], v[8:9], v[52:53], v[116:117] op_sel:[0,1,0] op_sel_hi:[1,1,1]
	v_pk_fma_f32 v[118:119], v[2:3], v[54:55], v[118:119] op_sel_hi:[1,0,1]
	v_pk_fma_f32 v[120:121], v[4:5], v[54:55], v[120:121] op_sel_hi:[1,0,1]
	v_pk_fma_f32 v[118:119], v[6:7], v[54:55], v[118:119] op_sel:[0,1,0] op_sel_hi:[1,1,1]
	v_pk_fma_f32 v[120:121], v[8:9], v[54:55], v[120:121] op_sel:[0,1,0] op_sel_hi:[1,1,1]
	ds_read_b64 v[34:35], v212 offset:24576
	ds_read_b64 v[36:37], v212 offset:28672
	ds_read_b64 v[38:39], v212 offset:32768
	ds_read_b64 v[40:41], v212 offset:36864
	ds_read_b64 v[42:43], v212 offset:40960
	ds_read_b64 v[44:45], v212 offset:45056
	ds_read_b64 v[46:47], v212 offset:49152
	ds_read_b64 v[48:49], v212 offset:53248
	ds_read_b64 v[50:51], v212 offset:57344
	ds_read_b64 v[52:53], v212 offset:61440
	ds_read_b64 v[54:55], v213
	s_waitcnt lgkmcnt(11)
; #define LAS __attribute__((address_space(3)))
; __device__ void phase_setup(const Params& p, LAS unsigned char* lds) {
;     ...
;             for (int k = 0; k < D; k += 16) {
;                 f32x4 w[16];
; #pragma unroll
;                 for (int kk = 0; kk < 16; ++kk) w[kk] = *(const f32x4*)(wp + (size_t)(k + kk) * (NMOD * D));
; #pragma unroll
;                 for (int i = 0; i < 5; ++i) { const int r = (i < 4) ? wid + 8 * i : 32;
; #pragma unroll
;                     for (int k4 = 0; k4 < 4; ++k4) { const f32x4 s4 = *(const LAS f32x4*)(sc + r * D + k + 4 * k4);
;                         a[i] += s4[0] * w[4 * k4] + s4[1] * w[4 * k4 + 1] + s4[2] * w[4 * k4 + 2] + s4[3] * w[4 * k4 + 3]; } }
	v_pk_fma_f32 v[122:123], v[2:3], v[56:57], v[122:123] op_sel_hi:[1,0,1]
	v_pk_fma_f32 v[124:125], v[4:5], v[56:57], v[124:125] op_sel_hi:[1,0,1]
	v_pk_fma_f32 v[122:123], v[6:7], v[56:57], v[122:123] op_sel:[0,1,0] op_sel_hi:[1,1,1]
	v_pk_fma_f32 v[124:125], v[8:9], v[56:57], v[124:125] op_sel:[0,1,0] op_sel_hi:[1,1,1]
	v_pk_fma_f32 v[126:127], v[2:3], v[58:59], v[126:127] op_sel_hi:[1,0,1]
	v_pk_fma_f32 v[128:129], v[4:5], v[58:59], v[128:129] op_sel_hi:[1,0,1]
	v_pk_fma_f32 v[126:127], v[6:7], v[58:59], v[126:127] op_sel:[0,1,0] op_sel_hi:[1,1,1]
	v_pk_fma_f32 v[128:129], v[8:9], v[58:59], v[128:129] op_sel:[0,1,0] op_sel_hi:[1,1,1]
	v_pk_fma_f32 v[130:131], v[2:3], v[60:61], v[130:131] op_sel_hi:[1,0,1]
	v_pk_fma_f32 v[132:133], v[4:5], v[60:61], v[132:133] op_sel_hi:[1,0,1]
	v_pk_fma_f32 v[130:131], v[6:7], v[60:61], v[130:131] op_sel:[0,1,0] op_sel_hi:[1,1,1]
	v_pk_fma_f32 v[132:133], v[8:9], v[60:61], v[132:133] op_sel:[0,1,0] op_sel_hi:[1,1,1]
	v_pk_fma_f32 v[134:135], v[2:3], v[62:63], v[134:135] op_sel_hi:[1,0,1]
	v_pk_fma_f32 v[136:137], v[4:5], v[62:63], v[136:137] op_sel_hi:[1,0,1]
	v_pk_fma_f32 v[134:135], v[6:7], v[62:63], v[134:135] op_sel:[0,1,0] op_sel_hi:[1,1,1]
	v_pk_fma_f32 v[136:137], v[8:9], v[62:63], v[136:137] op_sel:[0,1,0] op_sel_hi:[1,1,1]
	v_pk_fma_f32 v[138:139], v[2:3], v[64:65], v[138:139] op_sel_hi:[1,0,1]
	v_pk_fma_f32 v[140:141], v[4:5], v[64:65], v[140:141] op_sel_hi:[1,0,1]
	v_pk_fma_f32 v[138:139], v[6:7], v[64:65], v[138:139] op_sel:[0,1,0] op_sel_hi:[1,1,1]
	v_pk_fma_f32 v[140:141], v[8:9], v[64:65], v[140:141] op_sel:[0,1,0] op_sel_hi:[1,1,1]
	v_pk_fma_f32 v[142:143], v[2:3], v[66:67], v[142:143] op_sel_hi:[1,0,1]
	v_pk_fma_f32 v[144:145], v[4:5], v[66:67], v[144:145] op_sel_hi:[1,0,1]
	v_pk_fma_f32 v[142:143], v[6:7], v[66:67], v[142:143] op_sel:[0,1,0] op_sel_hi:[1,1,1]
	v_pk_fma_f32 v[144:145], v[8:9], v[66:67], v[144:145] op_sel:[0,1,0] op_sel_hi:[1,1,1]
	v_pk_fma_f32 v[146:147], v[2:3], v[68:69], v[146:147] op_sel_hi:[1,0,1]
	v_pk_fma_f32 v[148:149], v[4:5], v[68:69], v[148:149] op_sel_hi:[1,0,1]
	v_pk_fma_f32 v[146:147], v[6:7], v[68:69], v[146:147] op_sel:[0,1,0] op_sel_hi:[1,1,1]
	v_pk_fma_f32 v[148:149], v[8:9], v[68:69], v[148:149] op_sel:[0,1,0] op_sel_hi:[1,1,1]
	v_pk_fma_f32 v[150:151], v[2:3], v[70:71], v[150:151] op_sel_hi:[1,0,1]
	v_pk_fma_f32 v[152:153], v[4:5], v[70:71], v[152:153] op_sel_hi:[1,0,1]
	v_pk_fma_f32 v[150:151], v[6:7], v[70:71], v[150:151] op_sel:[0,1,0] op_sel_hi:[1,1,1]
	v_pk_fma_f32 v[152:153], v[8:9], v[70:71], v[152:153] op_sel:[0,1,0] op_sel_hi:[1,1,1]
	v_pk_fma_f32 v[154:155], v[2:3], v[72:73], v[154:155] op_sel_hi:[1,0,1]
	v_pk_fma_f32 v[156:157], v[4:5], v[72:73], v[156:157] op_sel_hi:[1,0,1]
	v_pk_fma_f32 v[154:155], v[6:7], v[72:73], v[154:155] op_sel:[0,1,0] op_sel_hi:[1,1,1]
	v_pk_fma_f32 v[156:157], v[8:9], v[72:73], v[156:157] op_sel:[0,1,0] op_sel_hi:[1,1,1]
	v_pk_fma_f32 v[158:159], v[2:3], v[74:75], v[158:159] op_sel_hi:[1,0,1]
	v_pk_fma_f32 v[160:161], v[4:5], v[74:75], v[160:161] op_sel_hi:[1,0,1]
	v_pk_fma_f32 v[158:159], v[6:7], v[74:75], v[158:159] op_sel:[0,1,0] op_sel_hi:[1,1,1]
	v_pk_fma_f32 v[160:161], v[8:9], v[74:75], v[160:161] op_sel:[0,1,0] op_sel_hi:[1,1,1]
	v_pk_fma_f32 v[162:163], v[2:3], v[76:77], v[162:163] op_sel_hi:[1,0,1]
	v_pk_fma_f32 v[164:165], v[4:5], v[76:77], v[164:165] op_sel_hi:[1,0,1]
	v_pk_fma_f32 v[162:163], v[6:7], v[76:77], v[162:163] op_sel:[0,1,0] op_sel_hi:[1,1,1]
	v_pk_fma_f32 v[164:165], v[8:9], v[76:77], v[164:165] op_sel:[0,1,0] op_sel_hi:[1,1,1]
	ds_read_b64 v[56:57], v211 offset:64
	ds_read_b64 v[58:59], v211 offset:4160
	ds_read_b64 v[60:61], v211 offset:8256
	ds_read_b64 v[62:63], v211 offset:12352
	ds_read_b64 v[64:65], v211 offset:16448
	ds_read_b64 v[66:67], v211 offset:20544
	ds_read_b64 v[68:69], v211 offset:24640
	ds_read_b64 v[70:71], v211 offset:28736
	ds_read_b64 v[72:73], v211 offset:32832
	ds_read_b64 v[74:75], v211 offset:36928
	ds_read_b64 v[76:77], v211 offset:41024
	v_add_u32_e32 v211, 64, v211
	v_add_u32_e32 v212, 64, v212
	v_add_u32_e32 v213, 64, v213
	s_waitcnt lgkmcnt(11)
	v_pk_fma_f32 v[166:167], v[2:3], v[34:35], v[166:167] op_sel_hi:[1,0,1]
	v_pk_fma_f32 v[168:169], v[4:5], v[34:35], v[168:169] op_sel_hi:[1,0,1]
	v_pk_fma_f32 v[166:167], v[6:7], v[34:35], v[166:167] op_sel:[0,1,0] op_sel_hi:[1,1,1]
	v_pk_fma_f32 v[168:169], v[8:9], v[34:35], v[168:169] op_sel:[0,1,0] op_sel_hi:[1,1,1]
	v_pk_fma_f32 v[170:171], v[2:3], v[36:37], v[170:171] op_sel_hi:[1,0,1]
	v_pk_fma_f32 v[172:173], v[4:5], v[36:37], v[172:173] op_sel_hi:[1,0,1]
	v_pk_fma_f32 v[170:171], v[6:7], v[36:37], v[170:171] op_sel:[0,1,0] op_sel_hi:[1,1,1]
	v_pk_fma_f32 v[172:173], v[8:9], v[36:37], v[172:173] op_sel:[0,1,0] op_sel_hi:[1,1,1]
	v_pk_fma_f32 v[174:175], v[2:3], v[38:39], v[174:175] op_sel_hi:[1,0,1]
	v_pk_fma_f32 v[176:177], v[4:5], v[38:39], v[176:177] op_sel_hi:[1,0,1]
	v_pk_fma_f32 v[174:175], v[6:7], v[38:39], v[174:175] op_sel:[0,1,0] op_sel_hi:[1,1,1]
	v_pk_fma_f32 v[176:177], v[8:9], v[38:39], v[176:177] op_sel:[0,1,0] op_sel_hi:[1,1,1]
	v_pk_fma_f32 v[178:179], v[2:3], v[40:41], v[178:179] op_sel_hi:[1,0,1]
	v_pk_fma_f32 v[180:181], v[4:5], v[40:41], v[180:181] op_sel_hi:[1,0,1]
	v_pk_fma_f32 v[178:179], v[6:7], v[40:41], v[178:179] op_sel:[0,1,0] op_sel_hi:[1,1,1]
	v_pk_fma_f32 v[180:181], v[8:9], v[40:41], v[180:181] op_sel:[0,1,0] op_sel_hi:[1,1,1]
	v_pk_fma_f32 v[182:183], v[2:3], v[42:43], v[182:183] op_sel_hi:[1,0,1]
	v_pk_fma_f32 v[184:185], v[4:5], v[42:43], v[184:185] op_sel_hi:[1,0,1]
	v_pk_fma_f32 v[182:183], v[6:7], v[42:43], v[182:183] op_sel:[0,1,0] op_sel_hi:[1,1,1]
; #define LAS __attribute__((address_space(3)))
; __device__ void phase_setup(const Params& p, LAS unsigned char* lds) {
;     ...
;             for (int k = 0; k < D; k += 16) {
;                 f32x4 w[16];
; #pragma unroll
;                 for (int kk = 0; kk < 16; ++kk) w[kk] = *(const f32x4*)(wp + (size_t)(k + kk) * (NMOD * D));
; #pragma unroll
;                 for (int i = 0; i < 5; ++i) { const int r = (i < 4) ? wid + 8 * i : 32;
; #pragma unroll
;                     for (int k4 = 0; k4 < 4; ++k4) { const f32x4 s4 = *(const LAS f32x4*)(sc + r * D + k + 4 * k4);
;                         a[i] += s4[0] * w[4 * k4] + s4[1] * w[4 * k4 + 1] + s4[2] * w[4 * k4 + 2] + s4[3] * w[4 * k4 + 3]; } }
	v_pk_fma_f32 v[184:185], v[8:9], v[42:43], v[184:185] op_sel:[0,1,0] op_sel_hi:[1,1,1]
	v_pk_fma_f32 v[186:187], v[2:3], v[44:45], v[186:187] op_sel_hi:[1,0,1]
	v_pk_fma_f32 v[188:189], v[4:5], v[44:45], v[188:189] op_sel_hi:[1,0,1]
	v_pk_fma_f32 v[186:187], v[6:7], v[44:45], v[186:187] op_sel:[0,1,0] op_sel_hi:[1,1,1]
	v_pk_fma_f32 v[188:189], v[8:9], v[44:45], v[188:189] op_sel:[0,1,0] op_sel_hi:[1,1,1]
	v_pk_fma_f32 v[190:191], v[2:3], v[46:47], v[190:191] op_sel_hi:[1,0,1]
	v_pk_fma_f32 v[192:193], v[4:5], v[46:47], v[192:193] op_sel_hi:[1,0,1]
	v_pk_fma_f32 v[190:191], v[6:7], v[46:47], v[190:191] op_sel:[0,1,0] op_sel_hi:[1,1,1]
	v_pk_fma_f32 v[192:193], v[8:9], v[46:47], v[192:193] op_sel:[0,1,0] op_sel_hi:[1,1,1]
	v_pk_fma_f32 v[194:195], v[2:3], v[48:49], v[194:195] op_sel_hi:[1,0,1]
	v_pk_fma_f32 v[196:197], v[4:5], v[48:49], v[196:197] op_sel_hi:[1,0,1]
	v_pk_fma_f32 v[194:195], v[6:7], v[48:49], v[194:195] op_sel:[0,1,0] op_sel_hi:[1,1,1]
	v_pk_fma_f32 v[196:197], v[8:9], v[48:49], v[196:197] op_sel:[0,1,0] op_sel_hi:[1,1,1]
	v_pk_fma_f32 v[198:199], v[2:3], v[50:51], v[198:199] op_sel_hi:[1,0,1]
	v_pk_fma_f32 v[200:201], v[4:5], v[50:51], v[200:201] op_sel_hi:[1,0,1]
	v_pk_fma_f32 v[198:199], v[6:7], v[50:51], v[198:199] op_sel:[0,1,0] op_sel_hi:[1,1,1]
	v_pk_fma_f32 v[200:201], v[8:9], v[50:51], v[200:201] op_sel:[0,1,0] op_sel_hi:[1,1,1]
	v_pk_fma_f32 v[202:203], v[2:3], v[52:53], v[202:203] op_sel_hi:[1,0,1]
	v_pk_fma_f32 v[204:205], v[4:5], v[52:53], v[204:205] op_sel_hi:[1,0,1]
	v_pk_fma_f32 v[202:203], v[6:7], v[52:53], v[202:203] op_sel:[0,1,0] op_sel_hi:[1,1,1]
	v_pk_fma_f32 v[204:205], v[8:9], v[52:53], v[204:205] op_sel:[0,1,0] op_sel_hi:[1,1,1]
	v_pk_fma_f32 v[206:207], v[2:3], v[54:55], v[206:207] op_sel_hi:[1,0,1]
	v_pk_fma_f32 v[208:209], v[4:5], v[54:55], v[208:209] op_sel_hi:[1,0,1]
	v_pk_fma_f32 v[206:207], v[6:7], v[54:55], v[206:207] op_sel:[0,1,0] op_sel_hi:[1,1,1]
	v_pk_fma_f32 v[208:209], v[8:9], v[54:55], v[208:209] op_sel:[0,1,0] op_sel_hi:[1,1,1]
	ds_read_b64 v[34:35], v211 offset:45056
	ds_read_b64 v[36:37], v211 offset:49152
	ds_read_b64 v[38:39], v211 offset:53248
	ds_read_b64 v[40:41], v211 offset:57344
	ds_read_b64 v[42:43], v211 offset:61440
	ds_read_b64 v[44:45], v212
	ds_read_b64 v[46:47], v212 offset:4096
	ds_read_b64 v[48:49], v212 offset:8192
	ds_read_b64 v[50:51], v212 offset:12288
	ds_read_b64 v[52:53], v212 offset:16384
	ds_read_b64 v[54:55], v212 offset:20480
	s_waitcnt vmcnt(4) lgkmcnt(11)
	v_pk_fma_f32 v[78:79], v[10:11], v[56:57], v[78:79] op_sel_hi:[1,0,1]
	v_pk_fma_f32 v[80:81], v[12:13], v[56:57], v[80:81] op_sel_hi:[1,0,1]
	v_pk_fma_f32 v[78:79], v[14:15], v[56:57], v[78:79] op_sel:[0,1,0] op_sel_hi:[1,1,1]
	v_pk_fma_f32 v[80:81], v[16:17], v[56:57], v[80:81] op_sel:[0,1,0] op_sel_hi:[1,1,1]
	v_pk_fma_f32 v[82:83], v[10:11], v[58:59], v[82:83] op_sel_hi:[1,0,1]
	v_pk_fma_f32 v[84:85], v[12:13], v[58:59], v[84:85] op_sel_hi:[1,0,1]
	v_pk_fma_f32 v[82:83], v[14:15], v[58:59], v[82:83] op_sel:[0,1,0] op_sel_hi:[1,1,1]
	v_pk_fma_f32 v[84:85], v[16:17], v[58:59], v[84:85] op_sel:[0,1,0] op_sel_hi:[1,1,1]
	v_pk_fma_f32 v[86:87], v[10:11], v[60:61], v[86:87] op_sel_hi:[1,0,1]
	v_pk_fma_f32 v[88:89], v[12:13], v[60:61], v[88:89] op_sel_hi:[1,0,1]
	v_pk_fma_f32 v[86:87], v[14:15], v[60:61], v[86:87] op_sel:[0,1,0] op_sel_hi:[1,1,1]
	v_pk_fma_f32 v[88:89], v[16:17], v[60:61], v[88:89] op_sel:[0,1,0] op_sel_hi:[1,1,1]
	v_pk_fma_f32 v[90:91], v[10:11], v[62:63], v[90:91] op_sel_hi:[1,0,1]
	v_pk_fma_f32 v[92:93], v[12:13], v[62:63], v[92:93] op_sel_hi:[1,0,1]
	v_pk_fma_f32 v[90:91], v[14:15], v[62:63], v[90:91] op_sel:[0,1,0] op_sel_hi:[1,1,1]
	v_pk_fma_f32 v[92:93], v[16:17], v[62:63], v[92:93] op_sel:[0,1,0] op_sel_hi:[1,1,1]
	v_pk_fma_f32 v[94:95], v[10:11], v[64:65], v[94:95] op_sel_hi:[1,0,1]
	v_pk_fma_f32 v[96:97], v[12:13], v[64:65], v[96:97] op_sel_hi:[1,0,1]
	v_pk_fma_f32 v[94:95], v[14:15], v[64:65], v[94:95] op_sel:[0,1,0] op_sel_hi:[1,1,1]
	v_pk_fma_f32 v[96:97], v[16:17], v[64:65], v[96:97] op_sel:[0,1,0] op_sel_hi:[1,1,1]
	v_pk_fma_f32 v[98:99], v[10:11], v[66:67], v[98:99] op_sel_hi:[1,0,1]
	v_pk_fma_f32 v[100:101], v[12:13], v[66:67], v[100:101] op_sel_hi:[1,0,1]
	v_pk_fma_f32 v[98:99], v[14:15], v[66:67], v[98:99] op_sel:[0,1,0] op_sel_hi:[1,1,1]
	v_pk_fma_f32 v[100:101], v[16:17], v[66:67], v[100:101] op_sel:[0,1,0] op_sel_hi:[1,1,1]
	v_pk_fma_f32 v[102:103], v[10:11], v[68:69], v[102:103] op_sel_hi:[1,0,1]
	v_pk_fma_f32 v[104:105], v[12:13], v[68:69], v[104:105] op_sel_hi:[1,0,1]
	v_pk_fma_f32 v[102:103], v[14:15], v[68:69], v[102:103] op_sel:[0,1,0] op_sel_hi:[1,1,1]
	v_pk_fma_f32 v[104:105], v[16:17], v[68:69], v[104:105] op_sel:[0,1,0] op_sel_hi:[1,1,1]
	v_pk_fma_f32 v[106:107], v[10:11], v[70:71], v[106:107] op_sel_hi:[1,0,1]
	v_pk_fma_f32 v[108:109], v[12:13], v[70:71], v[108:109] op_sel_hi:[1,0,1]
	v_pk_fma_f32 v[106:107], v[14:15], v[70:71], v[106:107] op_sel:[0,1,0] op_sel_hi:[1,1,1]
	v_pk_fma_f32 v[108:109], v[16:17], v[70:71], v[108:109] op_sel:[0,1,0] op_sel_hi:[1,1,1]
	v_pk_fma_f32 v[110:111], v[10:11], v[72:73], v[110:111] op_sel_hi:[1,0,1]
	v_pk_fma_f32 v[112:113], v[12:13], v[72:73], v[112:113] op_sel_hi:[1,0,1]
	v_pk_fma_f32 v[110:111], v[14:15], v[72:73], v[110:111] op_sel:[0,1,0] op_sel_hi:[1,1,1]
	v_pk_fma_f32 v[112:113], v[16:17], v[72:73], v[112:113] op_sel:[0,1,0] op_sel_hi:[1,1,1]
	v_pk_fma_f32 v[114:115], v[10:11], v[74:75], v[114:115] op_sel_hi:[1,0,1]
	v_pk_fma_f32 v[116:117], v[12:13], v[74:75], v[116:117] op_sel_hi:[1,0,1]
	v_pk_fma_f32 v[114:115], v[14:15], v[74:75], v[114:115] op_sel:[0,1,0] op_sel_hi:[1,1,1]
	v_pk_fma_f32 v[116:117], v[16:17], v[74:75], v[116:117] op_sel:[0,1,0] op_sel_hi:[1,1,1]
	v_pk_fma_f32 v[118:119], v[10:11], v[76:77], v[118:119] op_sel_hi:[1,0,1]
	v_pk_fma_f32 v[120:121], v[12:13], v[76:77], v[120:121] op_sel_hi:[1,0,1]
	v_pk_fma_f32 v[118:119], v[14:15], v[76:77], v[118:119] op_sel:[0,1,0] op_sel_hi:[1,1,1]
	v_pk_fma_f32 v[120:121], v[16:17], v[76:77], v[120:121] op_sel:[0,1,0] op_sel_hi:[1,1,1]
	ds_read_b64 v[56:57], v212 offset:24576
	ds_read_b64 v[58:59], v212 offset:28672
	ds_read_b64 v[60:61], v212 offset:32768
	ds_read_b64 v[62:63], v212 offset:36864
	ds_read_b64 v[64:65], v212 offset:40960
	ds_read_b64 v[66:67], v212 offset:45056
	ds_read_b64 v[68:69], v212 offset:49152
	ds_read_b64 v[70:71], v212 offset:53248
	ds_read_b64 v[72:73], v212 offset:57344
	ds_read_b64 v[74:75], v212 offset:61440
	ds_read_b64 v[76:77], v213
	s_waitcnt lgkmcnt(11)
; #define LAS __attribute__((address_space(3)))
; __device__ void phase_setup(const Params& p, LAS unsigned char* lds) {
;     ...
;             for (int k = 0; k < D; k += 16) {
;                 f32x4 w[16];
; #pragma unroll
;                 for (int kk = 0; kk < 16; ++kk) w[kk] = *(const f32x4*)(wp + (size_t)(k + kk) * (NMOD * D));
; #pragma unroll
;                 for (int i = 0; i < 5; ++i) { const int r = (i < 4) ? wid + 8 * i : 32;
; #pragma unroll
;                     for (int k4 = 0; k4 < 4; ++k4) { const f32x4 s4 = *(const LAS f32x4*)(sc + r * D + k + 4 * k4);
;                         a[i] += s4[0] * w[4 * k4] + s4[1] * w[4 * k4 + 1] + s4[2] * w[4 * k4 + 2] + s4[3] * w[4 * k4 + 3]; } }
	v_pk_fma_f32 v[122:123], v[10:11], v[34:35], v[122:123] op_sel_hi:[1,0,1]
	v_pk_fma_f32 v[124:125], v[12:13], v[34:35], v[124:125] op_sel_hi:[1,0,1]
	v_pk_fma_f32 v[122:123], v[14:15], v[34:35], v[122:123] op_sel:[0,1,0] op_sel_hi:[1,1,1]
	v_pk_fma_f32 v[124:125], v[16:17], v[34:35], v[124:125] op_sel:[0,1,0] op_sel_hi:[1,1,1]
	v_pk_fma_f32 v[126:127], v[10:11], v[36:37], v[126:127] op_sel_hi:[1,0,1]
	v_pk_fma_f32 v[128:129], v[12:13], v[36:37], v[128:129] op_sel_hi:[1,0,1]
	v_pk_fma_f32 v[126:127], v[14:15], v[36:37], v[126:127] op_sel:[0,1,0] op_sel_hi:[1,1,1]
	v_pk_fma_f32 v[128:129], v[16:17], v[36:37], v[128:129] op_sel:[0,1,0] op_sel_hi:[1,1,1]
	v_pk_fma_f32 v[130:131], v[10:11], v[38:39], v[130:131] op_sel_hi:[1,0,1]
	v_pk_fma_f32 v[132:133], v[12:13], v[38:39], v[132:133] op_sel_hi:[1,0,1]
	v_pk_fma_f32 v[130:131], v[14:15], v[38:39], v[130:131] op_sel:[0,1,0] op_sel_hi:[1,1,1]
	v_pk_fma_f32 v[132:133], v[16:17], v[38:39], v[132:133] op_sel:[0,1,0] op_sel_hi:[1,1,1]
	v_pk_fma_f32 v[134:135], v[10:11], v[40:41], v[134:135] op_sel_hi:[1,0,1]
	v_pk_fma_f32 v[136:137], v[12:13], v[40:41], v[136:137] op_sel_hi:[1,0,1]
	v_pk_fma_f32 v[134:135], v[14:15], v[40:41], v[134:135] op_sel:[0,1,0] op_sel_hi:[1,1,1]
	v_pk_fma_f32 v[136:137], v[16:17], v[40:41], v[136:137] op_sel:[0,1,0] op_sel_hi:[1,1,1]
	v_pk_fma_f32 v[138:139], v[10:11], v[42:43], v[138:139] op_sel_hi:[1,0,1]
	v_pk_fma_f32 v[140:141], v[12:13], v[42:43], v[140:141] op_sel_hi:[1,0,1]
	v_pk_fma_f32 v[138:139], v[14:15], v[42:43], v[138:139] op_sel:[0,1,0] op_sel_hi:[1,1,1]
	v_pk_fma_f32 v[140:141], v[16:17], v[42:43], v[140:141] op_sel:[0,1,0] op_sel_hi:[1,1,1]
	v_pk_fma_f32 v[142:143], v[10:11], v[44:45], v[142:143] op_sel_hi:[1,0,1]
	v_pk_fma_f32 v[144:145], v[12:13], v[44:45], v[144:145] op_sel_hi:[1,0,1]
	v_pk_fma_f32 v[142:143], v[14:15], v[44:45], v[142:143] op_sel:[0,1,0] op_sel_hi:[1,1,1]
	v_pk_fma_f32 v[144:145], v[16:17], v[44:45], v[144:145] op_sel:[0,1,0] op_sel_hi:[1,1,1]
	v_pk_fma_f32 v[146:147], v[10:11], v[46:47], v[146:147] op_sel_hi:[1,0,1]
	v_pk_fma_f32 v[148:149], v[12:13], v[46:47], v[148:149] op_sel_hi:[1,0,1]
	v_pk_fma_f32 v[146:147], v[14:15], v[46:47], v[146:147] op_sel:[0,1,0] op_sel_hi:[1,1,1]
	v_pk_fma_f32 v[148:149], v[16:17], v[46:47], v[148:149] op_sel:[0,1,0] op_sel_hi:[1,1,1]
	v_pk_fma_f32 v[150:151], v[10:11], v[48:49], v[150:151] op_sel_hi:[1,0,1]
	v_pk_fma_f32 v[152:153], v[12:13], v[48:49], v[152:153] op_sel_hi:[1,0,1]
	v_pk_fma_f32 v[150:151], v[14:15], v[48:49], v[150:151] op_sel:[0,1,0] op_sel_hi:[1,1,1]
	v_pk_fma_f32 v[152:153], v[16:17], v[48:49], v[152:153] op_sel:[0,1,0] op_sel_hi:[1,1,1]
	v_pk_fma_f32 v[154:155], v[10:11], v[50:51], v[154:155] op_sel_hi:[1,0,1]
	v_pk_fma_f32 v[156:157], v[12:13], v[50:51], v[156:157] op_sel_hi:[1,0,1]
	v_pk_fma_f32 v[154:155], v[14:15], v[50:51], v[154:155] op_sel:[0,1,0] op_sel_hi:[1,1,1]
	v_pk_fma_f32 v[156:157], v[16:17], v[50:51], v[156:157] op_sel:[0,1,0] op_sel_hi:[1,1,1]
	v_pk_fma_f32 v[158:159], v[10:11], v[52:53], v[158:159] op_sel_hi:[1,0,1]
	v_pk_fma_f32 v[160:161], v[12:13], v[52:53], v[160:161] op_sel_hi:[1,0,1]
	v_pk_fma_f32 v[158:159], v[14:15], v[52:53], v[158:159] op_sel:[0,1,0] op_sel_hi:[1,1,1]
	v_pk_fma_f32 v[160:161], v[16:17], v[52:53], v[160:161] op_sel:[0,1,0] op_sel_hi:[1,1,1]
	v_pk_fma_f32 v[162:163], v[10:11], v[54:55], v[162:163] op_sel_hi:[1,0,1]
	v_pk_fma_f32 v[164:165], v[12:13], v[54:55], v[164:165] op_sel_hi:[1,0,1]
	v_pk_fma_f32 v[162:163], v[14:15], v[54:55], v[162:163] op_sel:[0,1,0] op_sel_hi:[1,1,1]
	v_pk_fma_f32 v[164:165], v[16:17], v[54:55], v[164:165] op_sel:[0,1,0] op_sel_hi:[1,1,1]
	ds_read_b64 v[34:35], v211 offset:64
	ds_read_b64 v[36:37], v211 offset:4160
	ds_read_b64 v[38:39], v211 offset:8256
	ds_read_b64 v[40:41], v211 offset:12352
	ds_read_b64 v[42:43], v211 offset:16448
	ds_read_b64 v[44:45], v211 offset:20544
	ds_read_b64 v[46:47], v211 offset:24640
	ds_read_b64 v[48:49], v211 offset:28736
	ds_read_b64 v[50:51], v211 offset:32832
	ds_read_b64 v[52:53], v211 offset:36928
	ds_read_b64 v[54:55], v211 offset:41024
	v_add_u32_e32 v211, 64, v211
	v_add_u32_e32 v212, 64, v212
	v_add_u32_e32 v213, 64, v213
	s_waitcnt lgkmcnt(11)
	v_pk_fma_f32 v[166:167], v[10:11], v[56:57], v[166:167] op_sel_hi:[1,0,1]
	v_pk_fma_f32 v[168:169], v[12:13], v[56:57], v[168:169] op_sel_hi:[1,0,1]
	v_pk_fma_f32 v[166:167], v[14:15], v[56:57], v[166:167] op_sel:[0,1,0] op_sel_hi:[1,1,1]
	v_pk_fma_f32 v[168:169], v[16:17], v[56:57], v[168:169] op_sel:[0,1,0] op_sel_hi:[1,1,1]
	v_pk_fma_f32 v[170:171], v[10:11], v[58:59], v[170:171] op_sel_hi:[1,0,1]
	v_pk_fma_f32 v[172:173], v[12:13], v[58:59], v[172:173] op_sel_hi:[1,0,1]
	v_pk_fma_f32 v[170:171], v[14:15], v[58:59], v[170:171] op_sel:[0,1,0] op_sel_hi:[1,1,1]
	v_pk_fma_f32 v[172:173], v[16:17], v[58:59], v[172:173] op_sel:[0,1,0] op_sel_hi:[1,1,1]
	v_pk_fma_f32 v[174:175], v[10:11], v[60:61], v[174:175] op_sel_hi:[1,0,1]
	v_pk_fma_f32 v[176:177], v[12:13], v[60:61], v[176:177] op_sel_hi:[1,0,1]
	v_pk_fma_f32 v[174:175], v[14:15], v[60:61], v[174:175] op_sel:[0,1,0] op_sel_hi:[1,1,1]
	v_pk_fma_f32 v[176:177], v[16:17], v[60:61], v[176:177] op_sel:[0,1,0] op_sel_hi:[1,1,1]
	v_pk_fma_f32 v[178:179], v[10:11], v[62:63], v[178:179] op_sel_hi:[1,0,1]
	v_pk_fma_f32 v[180:181], v[12:13], v[62:63], v[180:181] op_sel_hi:[1,0,1]
	v_pk_fma_f32 v[178:179], v[14:15], v[62:63], v[178:179] op_sel:[0,1,0] op_sel_hi:[1,1,1]
	v_pk_fma_f32 v[180:181], v[16:17], v[62:63], v[180:181] op_sel:[0,1,0] op_sel_hi:[1,1,1]
	v_pk_fma_f32 v[182:183], v[10:11], v[64:65], v[182:183] op_sel_hi:[1,0,1]
	v_pk_fma_f32 v[184:185], v[12:13], v[64:65], v[184:185] op_sel_hi:[1,0,1]
; #define LAS __attribute__((address_space(3)))
; __device__ void phase_setup(const Params& p, LAS unsigned char* lds) {
;     ...
;             for (int k = 0; k < D; k += 16) {
;                 f32x4 w[16];
; #pragma unroll
;                 for (int kk = 0; kk < 16; ++kk) w[kk] = *(const f32x4*)(wp + (size_t)(k + kk) * (NMOD * D));
; #pragma unroll
;                 for (int i = 0; i < 5; ++i) { const int r = (i < 4) ? wid + 8 * i : 32;
; #pragma unroll
;                     for (int k4 = 0; k4 < 4; ++k4) { const f32x4 s4 = *(const LAS f32x4*)(sc + r * D + k + 4 * k4);
;                         a[i] += s4[0] * w[4 * k4] + s4[1] * w[4 * k4 + 1] + s4[2] * w[4 * k4 + 2] + s4[3] * w[4 * k4 + 3]; } }
	v_pk_fma_f32 v[182:183], v[14:15], v[64:65], v[182:183] op_sel:[0,1,0] op_sel_hi:[1,1,1]
	v_pk_fma_f32 v[184:185], v[16:17], v[64:65], v[184:185] op_sel:[0,1,0] op_sel_hi:[1,1,1]
	v_pk_fma_f32 v[186:187], v[10:11], v[66:67], v[186:187] op_sel_hi:[1,0,1]
	v_pk_fma_f32 v[188:189], v[12:13], v[66:67], v[188:189] op_sel_hi:[1,0,1]
	v_pk_fma_f32 v[186:187], v[14:15], v[66:67], v[186:187] op_sel:[0,1,0] op_sel_hi:[1,1,1]
	v_pk_fma_f32 v[188:189], v[16:17], v[66:67], v[188:189] op_sel:[0,1,0] op_sel_hi:[1,1,1]
	v_pk_fma_f32 v[190:191], v[10:11], v[68:69], v[190:191] op_sel_hi:[1,0,1]
	v_pk_fma_f32 v[192:193], v[12:13], v[68:69], v[192:193] op_sel_hi:[1,0,1]
	v_pk_fma_f32 v[190:191], v[14:15], v[68:69], v[190:191] op_sel:[0,1,0] op_sel_hi:[1,1,1]
	v_pk_fma_f32 v[192:193], v[16:17], v[68:69], v[192:193] op_sel:[0,1,0] op_sel_hi:[1,1,1]
	v_pk_fma_f32 v[194:195], v[10:11], v[70:71], v[194:195] op_sel_hi:[1,0,1]
	v_pk_fma_f32 v[196:197], v[12:13], v[70:71], v[196:197] op_sel_hi:[1,0,1]
	v_pk_fma_f32 v[194:195], v[14:15], v[70:71], v[194:195] op_sel:[0,1,0] op_sel_hi:[1,1,1]
	v_pk_fma_f32 v[196:197], v[16:17], v[70:71], v[196:197] op_sel:[0,1,0] op_sel_hi:[1,1,1]
	v_pk_fma_f32 v[198:199], v[10:11], v[72:73], v[198:199] op_sel_hi:[1,0,1]
	v_pk_fma_f32 v[200:201], v[12:13], v[72:73], v[200:201] op_sel_hi:[1,0,1]
	v_pk_fma_f32 v[198:199], v[14:15], v[72:73], v[198:199] op_sel:[0,1,0] op_sel_hi:[1,1,1]
	v_pk_fma_f32 v[200:201], v[16:17], v[72:73], v[200:201] op_sel:[0,1,0] op_sel_hi:[1,1,1]
	v_pk_fma_f32 v[202:203], v[10:11], v[74:75], v[202:203] op_sel_hi:[1,0,1]
	v_pk_fma_f32 v[204:205], v[12:13], v[74:75], v[204:205] op_sel_hi:[1,0,1]
	v_pk_fma_f32 v[202:203], v[14:15], v[74:75], v[202:203] op_sel:[0,1,0] op_sel_hi:[1,1,1]
	v_pk_fma_f32 v[204:205], v[16:17], v[74:75], v[204:205] op_sel:[0,1,0] op_sel_hi:[1,1,1]
	v_pk_fma_f32 v[206:207], v[10:11], v[76:77], v[206:207] op_sel_hi:[1,0,1]
	v_pk_fma_f32 v[208:209], v[12:13], v[76:77], v[208:209] op_sel_hi:[1,0,1]
	v_pk_fma_f32 v[206:207], v[14:15], v[76:77], v[206:207] op_sel:[0,1,0] op_sel_hi:[1,1,1]
	v_pk_fma_f32 v[208:209], v[16:17], v[76:77], v[208:209] op_sel:[0,1,0] op_sel_hi:[1,1,1]
	ds_read_b64 v[56:57], v211 offset:45056
	ds_read_b64 v[58:59], v211 offset:49152
	ds_read_b64 v[60:61], v211 offset:53248
	ds_read_b64 v[62:63], v211 offset:57344
	ds_read_b64 v[64:65], v211 offset:61440
	ds_read_b64 v[66:67], v212
	ds_read_b64 v[68:69], v212 offset:4096
	ds_read_b64 v[70:71], v212 offset:8192
	ds_read_b64 v[72:73], v212 offset:12288
	ds_read_b64 v[74:75], v212 offset:16384
	ds_read_b64 v[76:77], v212 offset:20480
	s_waitcnt vmcnt(2) lgkmcnt(11)
	v_pk_fma_f32 v[78:79], v[18:19], v[34:35], v[78:79] op_sel_hi:[1,0,1]
	v_pk_fma_f32 v[80:81], v[20:21], v[34:35], v[80:81] op_sel_hi:[1,0,1]
	v_pk_fma_f32 v[78:79], v[22:23], v[34:35], v[78:79] op_sel:[0,1,0] op_sel_hi:[1,1,1]
	v_pk_fma_f32 v[80:81], v[24:25], v[34:35], v[80:81] op_sel:[0,1,0] op_sel_hi:[1,1,1]
	v_pk_fma_f32 v[82:83], v[18:19], v[36:37], v[82:83] op_sel_hi:[1,0,1]
	v_pk_fma_f32 v[84:85], v[20:21], v[36:37], v[84:85] op_sel_hi:[1,0,1]
	v_pk_fma_f32 v[82:83], v[22:23], v[36:37], v[82:83] op_sel:[0,1,0] op_sel_hi:[1,1,1]
	v_pk_fma_f32 v[84:85], v[24:25], v[36:37], v[84:85] op_sel:[0,1,0] op_sel_hi:[1,1,1]
	v_pk_fma_f32 v[86:87], v[18:19], v[38:39], v[86:87] op_sel_hi:[1,0,1]
	v_pk_fma_f32 v[88:89], v[20:21], v[38:39], v[88:89] op_sel_hi:[1,0,1]
	v_pk_fma_f32 v[86:87], v[22:23], v[38:39], v[86:87] op_sel:[0,1,0] op_sel_hi:[1,1,1]
	v_pk_fma_f32 v[88:89], v[24:25], v[38:39], v[88:89] op_sel:[0,1,0] op_sel_hi:[1,1,1]
	v_pk_fma_f32 v[90:91], v[18:19], v[40:41], v[90:91] op_sel_hi:[1,0,1]
	v_pk_fma_f32 v[92:93], v[20:21], v[40:41], v[92:93] op_sel_hi:[1,0,1]
	v_pk_fma_f32 v[90:91], v[22:23], v[40:41], v[90:91] op_sel:[0,1,0] op_sel_hi:[1,1,1]
	v_pk_fma_f32 v[92:93], v[24:25], v[40:41], v[92:93] op_sel:[0,1,0] op_sel_hi:[1,1,1]
	v_pk_fma_f32 v[94:95], v[18:19], v[42:43], v[94:95] op_sel_hi:[1,0,1]
	v_pk_fma_f32 v[96:97], v[20:21], v[42:43], v[96:97] op_sel_hi:[1,0,1]
	v_pk_fma_f32 v[94:95], v[22:23], v[42:43], v[94:95] op_sel:[0,1,0] op_sel_hi:[1,1,1]
	v_pk_fma_f32 v[96:97], v[24:25], v[42:43], v[96:97] op_sel:[0,1,0] op_sel_hi:[1,1,1]
	v_pk_fma_f32 v[98:99], v[18:19], v[44:45], v[98:99] op_sel_hi:[1,0,1]
	v_pk_fma_f32 v[100:101], v[20:21], v[44:45], v[100:101] op_sel_hi:[1,0,1]
	v_pk_fma_f32 v[98:99], v[22:23], v[44:45], v[98:99] op_sel:[0,1,0] op_sel_hi:[1,1,1]
	v_pk_fma_f32 v[100:101], v[24:25], v[44:45], v[100:101] op_sel:[0,1,0] op_sel_hi:[1,1,1]
	v_pk_fma_f32 v[102:103], v[18:19], v[46:47], v[102:103] op_sel_hi:[1,0,1]
	v_pk_fma_f32 v[104:105], v[20:21], v[46:47], v[104:105] op_sel_hi:[1,0,1]
	v_pk_fma_f32 v[102:103], v[22:23], v[46:47], v[102:103] op_sel:[0,1,0] op_sel_hi:[1,1,1]
	v_pk_fma_f32 v[104:105], v[24:25], v[46:47], v[104:105] op_sel:[0,1,0] op_sel_hi:[1,1,1]
	v_pk_fma_f32 v[106:107], v[18:19], v[48:49], v[106:107] op_sel_hi:[1,0,1]
	v_pk_fma_f32 v[108:109], v[20:21], v[48:49], v[108:109] op_sel_hi:[1,0,1]
	v_pk_fma_f32 v[106:107], v[22:23], v[48:49], v[106:107] op_sel:[0,1,0] op_sel_hi:[1,1,1]
	v_pk_fma_f32 v[108:109], v[24:25], v[48:49], v[108:109] op_sel:[0,1,0] op_sel_hi:[1,1,1]
	v_pk_fma_f32 v[110:111], v[18:19], v[50:51], v[110:111] op_sel_hi:[1,0,1]
	v_pk_fma_f32 v[112:113], v[20:21], v[50:51], v[112:113] op_sel_hi:[1,0,1]
	v_pk_fma_f32 v[110:111], v[22:23], v[50:51], v[110:111] op_sel:[0,1,0] op_sel_hi:[1,1,1]
	v_pk_fma_f32 v[112:113], v[24:25], v[50:51], v[112:113] op_sel:[0,1,0] op_sel_hi:[1,1,1]
	v_pk_fma_f32 v[114:115], v[18:19], v[52:53], v[114:115] op_sel_hi:[1,0,1]
	v_pk_fma_f32 v[116:117], v[20:21], v[52:53], v[116:117] op_sel_hi:[1,0,1]
	v_pk_fma_f32 v[114:115], v[22:23], v[52:53], v[114:115] op_sel:[0,1,0] op_sel_hi:[1,1,1]
	v_pk_fma_f32 v[116:117], v[24:25], v[52:53], v[116:117] op_sel:[0,1,0] op_sel_hi:[1,1,1]
	v_pk_fma_f32 v[118:119], v[18:19], v[54:55], v[118:119] op_sel_hi:[1,0,1]
	v_pk_fma_f32 v[120:121], v[20:21], v[54:55], v[120:121] op_sel_hi:[1,0,1]
	v_pk_fma_f32 v[118:119], v[22:23], v[54:55], v[118:119] op_sel:[0,1,0] op_sel_hi:[1,1,1]
	v_pk_fma_f32 v[120:121], v[24:25], v[54:55], v[120:121] op_sel:[0,1,0] op_sel_hi:[1,1,1]
	ds_read_b64 v[34:35], v212 offset:24576
	ds_read_b64 v[36:37], v212 offset:28672
	ds_read_b64 v[38:39], v212 offset:32768
	ds_read_b64 v[40:41], v212 offset:36864
	ds_read_b64 v[42:43], v212 offset:40960
	ds_read_b64 v[44:45], v212 offset:45056
	ds_read_b64 v[46:47], v212 offset:49152
	ds_read_b64 v[48:49], v212 offset:53248
	ds_read_b64 v[50:51], v212 offset:57344
	ds_read_b64 v[52:53], v212 offset:61440
	ds_read_b64 v[54:55], v213
	s_waitcnt lgkmcnt(11)
; #define LAS __attribute__((address_space(3)))
; __device__ void phase_setup(const Params& p, LAS unsigned char* lds) {
;     ...
;             for (int k = 0; k < D; k += 16) {
;                 f32x4 w[16];
; #pragma unroll
;                 for (int kk = 0; kk < 16; ++kk) w[kk] = *(const f32x4*)(wp + (size_t)(k + kk) * (NMOD * D));
; #pragma unroll
;                 for (int i = 0; i < 5; ++i) { const int r = (i < 4) ? wid + 8 * i : 32;
; #pragma unroll
;                     for (int k4 = 0; k4 < 4; ++k4) { const f32x4 s4 = *(const LAS f32x4*)(sc + r * D + k + 4 * k4);
;                         a[i] += s4[0] * w[4 * k4] + s4[1] * w[4 * k4 + 1] + s4[2] * w[4 * k4 + 2] + s4[3] * w[4 * k4 + 3]; } }
	v_pk_fma_f32 v[122:123], v[18:19], v[56:57], v[122:123] op_sel_hi:[1,0,1]
	v_pk_fma_f32 v[124:125], v[20:21], v[56:57], v[124:125] op_sel_hi:[1,0,1]
	v_pk_fma_f32 v[122:123], v[22:23], v[56:57], v[122:123] op_sel:[0,1,0] op_sel_hi:[1,1,1]
	v_pk_fma_f32 v[124:125], v[24:25], v[56:57], v[124:125] op_sel:[0,1,0] op_sel_hi:[1,1,1]
	v_pk_fma_f32 v[126:127], v[18:19], v[58:59], v[126:127] op_sel_hi:[1,0,1]
	v_pk_fma_f32 v[128:129], v[20:21], v[58:59], v[128:129] op_sel_hi:[1,0,1]
	v_pk_fma_f32 v[126:127], v[22:23], v[58:59], v[126:127] op_sel:[0,1,0] op_sel_hi:[1,1,1]
	v_pk_fma_f32 v[128:129], v[24:25], v[58:59], v[128:129] op_sel:[0,1,0] op_sel_hi:[1,1,1]
	v_pk_fma_f32 v[130:131], v[18:19], v[60:61], v[130:131] op_sel_hi:[1,0,1]
	v_pk_fma_f32 v[132:133], v[20:21], v[60:61], v[132:133] op_sel_hi:[1,0,1]
	v_pk_fma_f32 v[130:131], v[22:23], v[60:61], v[130:131] op_sel:[0,1,0] op_sel_hi:[1,1,1]
	v_pk_fma_f32 v[132:133], v[24:25], v[60:61], v[132:133] op_sel:[0,1,0] op_sel_hi:[1,1,1]
	v_pk_fma_f32 v[134:135], v[18:19], v[62:63], v[134:135] op_sel_hi:[1,0,1]
	v_pk_fma_f32 v[136:137], v[20:21], v[62:63], v[136:137] op_sel_hi:[1,0,1]
	v_pk_fma_f32 v[134:135], v[22:23], v[62:63], v[134:135] op_sel:[0,1,0] op_sel_hi:[1,1,1]
	v_pk_fma_f32 v[136:137], v[24:25], v[62:63], v[136:137] op_sel:[0,1,0] op_sel_hi:[1,1,1]
	v_pk_fma_f32 v[138:139], v[18:19], v[64:65], v[138:139] op_sel_hi:[1,0,1]
	v_pk_fma_f32 v[140:141], v[20:21], v[64:65], v[140:141] op_sel_hi:[1,0,1]
	v_pk_fma_f32 v[138:139], v[22:23], v[64:65], v[138:139] op_sel:[0,1,0] op_sel_hi:[1,1,1]
	v_pk_fma_f32 v[140:141], v[24:25], v[64:65], v[140:141] op_sel:[0,1,0] op_sel_hi:[1,1,1]
	v_pk_fma_f32 v[142:143], v[18:19], v[66:67], v[142:143] op_sel_hi:[1,0,1]
	v_pk_fma_f32 v[144:145], v[20:21], v[66:67], v[144:145] op_sel_hi:[1,0,1]
	v_pk_fma_f32 v[142:143], v[22:23], v[66:67], v[142:143] op_sel:[0,1,0] op_sel_hi:[1,1,1]
	v_pk_fma_f32 v[144:145], v[24:25], v[66:67], v[144:145] op_sel:[0,1,0] op_sel_hi:[1,1,1]
	v_pk_fma_f32 v[146:147], v[18:19], v[68:69], v[146:147] op_sel_hi:[1,0,1]
	v_pk_fma_f32 v[148:149], v[20:21], v[68:69], v[148:149] op_sel_hi:[1,0,1]
	v_pk_fma_f32 v[146:147], v[22:23], v[68:69], v[146:147] op_sel:[0,1,0] op_sel_hi:[1,1,1]
	v_pk_fma_f32 v[148:149], v[24:25], v[68:69], v[148:149] op_sel:[0,1,0] op_sel_hi:[1,1,1]
	v_pk_fma_f32 v[150:151], v[18:19], v[70:71], v[150:151] op_sel_hi:[1,0,1]
	v_pk_fma_f32 v[152:153], v[20:21], v[70:71], v[152:153] op_sel_hi:[1,0,1]
	v_pk_fma_f32 v[150:151], v[22:23], v[70:71], v[150:151] op_sel:[0,1,0] op_sel_hi:[1,1,1]
	v_pk_fma_f32 v[152:153], v[24:25], v[70:71], v[152:153] op_sel:[0,1,0] op_sel_hi:[1,1,1]
	v_pk_fma_f32 v[154:155], v[18:19], v[72:73], v[154:155] op_sel_hi:[1,0,1]
	v_pk_fma_f32 v[156:157], v[20:21], v[72:73], v[156:157] op_sel_hi:[1,0,1]
	v_pk_fma_f32 v[154:155], v[22:23], v[72:73], v[154:155] op_sel:[0,1,0] op_sel_hi:[1,1,1]
	v_pk_fma_f32 v[156:157], v[24:25], v[72:73], v[156:157] op_sel:[0,1,0] op_sel_hi:[1,1,1]
	v_pk_fma_f32 v[158:159], v[18:19], v[74:75], v[158:159] op_sel_hi:[1,0,1]
	v_pk_fma_f32 v[160:161], v[20:21], v[74:75], v[160:161] op_sel_hi:[1,0,1]
	v_pk_fma_f32 v[158:159], v[22:23], v[74:75], v[158:159] op_sel:[0,1,0] op_sel_hi:[1,1,1]
	v_pk_fma_f32 v[160:161], v[24:25], v[74:75], v[160:161] op_sel:[0,1,0] op_sel_hi:[1,1,1]
	v_pk_fma_f32 v[162:163], v[18:19], v[76:77], v[162:163] op_sel_hi:[1,0,1]
	v_pk_fma_f32 v[164:165], v[20:21], v[76:77], v[164:165] op_sel_hi:[1,0,1]
	v_pk_fma_f32 v[162:163], v[22:23], v[76:77], v[162:163] op_sel:[0,1,0] op_sel_hi:[1,1,1]
	v_pk_fma_f32 v[164:165], v[24:25], v[76:77], v[164:165] op_sel:[0,1,0] op_sel_hi:[1,1,1]
	ds_read_b64 v[56:57], v211 offset:64
	ds_read_b64 v[58:59], v211 offset:4160
	ds_read_b64 v[60:61], v211 offset:8256
	ds_read_b64 v[62:63], v211 offset:12352
	ds_read_b64 v[64:65], v211 offset:16448
	ds_read_b64 v[66:67], v211 offset:20544
	ds_read_b64 v[68:69], v211 offset:24640
	ds_read_b64 v[70:71], v211 offset:28736
	ds_read_b64 v[72:73], v211 offset:32832
	ds_read_b64 v[74:75], v211 offset:36928
	ds_read_b64 v[76:77], v211 offset:41024
	v_add_u32_e32 v211, 64, v211
	v_add_u32_e32 v212, 64, v212
	v_add_u32_e32 v213, 64, v213
	s_waitcnt lgkmcnt(11)
	v_pk_fma_f32 v[166:167], v[18:19], v[34:35], v[166:167] op_sel_hi:[1,0,1]
	v_pk_fma_f32 v[168:169], v[20:21], v[34:35], v[168:169] op_sel_hi:[1,0,1]
	v_pk_fma_f32 v[166:167], v[22:23], v[34:35], v[166:167] op_sel:[0,1,0] op_sel_hi:[1,1,1]
	v_pk_fma_f32 v[168:169], v[24:25], v[34:35], v[168:169] op_sel:[0,1,0] op_sel_hi:[1,1,1]
	v_pk_fma_f32 v[170:171], v[18:19], v[36:37], v[170:171] op_sel_hi:[1,0,1]
	v_pk_fma_f32 v[172:173], v[20:21], v[36:37], v[172:173] op_sel_hi:[1,0,1]
	v_pk_fma_f32 v[170:171], v[22:23], v[36:37], v[170:171] op_sel:[0,1,0] op_sel_hi:[1,1,1]
	v_pk_fma_f32 v[172:173], v[24:25], v[36:37], v[172:173] op_sel:[0,1,0] op_sel_hi:[1,1,1]
	v_pk_fma_f32 v[174:175], v[18:19], v[38:39], v[174:175] op_sel_hi:[1,0,1]
	v_pk_fma_f32 v[176:177], v[20:21], v[38:39], v[176:177] op_sel_hi:[1,0,1]
	v_pk_fma_f32 v[174:175], v[22:23], v[38:39], v[174:175] op_sel:[0,1,0] op_sel_hi:[1,1,1]
	v_pk_fma_f32 v[176:177], v[24:25], v[38:39], v[176:177] op_sel:[0,1,0] op_sel_hi:[1,1,1]
	v_pk_fma_f32 v[178:179], v[18:19], v[40:41], v[178:179] op_sel_hi:[1,0,1]
	v_pk_fma_f32 v[180:181], v[20:21], v[40:41], v[180:181] op_sel_hi:[1,0,1]
	v_pk_fma_f32 v[178:179], v[22:23], v[40:41], v[178:179] op_sel:[0,1,0] op_sel_hi:[1,1,1]
	v_pk_fma_f32 v[180:181], v[24:25], v[40:41], v[180:181] op_sel:[0,1,0] op_sel_hi:[1,1,1]
	v_pk_fma_f32 v[182:183], v[18:19], v[42:43], v[182:183] op_sel_hi:[1,0,1]
	v_pk_fma_f32 v[184:185], v[20:21], v[42:43], v[184:185] op_sel_hi:[1,0,1]
; #define LAS __attribute__((address_space(3)))
; __device__ void phase_setup(const Params& p, LAS unsigned char* lds) {
;     ...
;             for (int k = 0; k < D; k += 16) {
;                 f32x4 w[16];
; #pragma unroll
;                 for (int kk = 0; kk < 16; ++kk) w[kk] = *(const f32x4*)(wp + (size_t)(k + kk) * (NMOD * D));
; #pragma unroll
;                 for (int i = 0; i < 5; ++i) { const int r = (i < 4) ? wid + 8 * i : 32;
; #pragma unroll
;                     for (int k4 = 0; k4 < 4; ++k4) { const f32x4 s4 = *(const LAS f32x4*)(sc + r * D + k + 4 * k4);
;                         a[i] += s4[0] * w[4 * k4] + s4[1] * w[4 * k4 + 1] + s4[2] * w[4 * k4 + 2] + s4[3] * w[4 * k4 + 3]; } }
	v_pk_fma_f32 v[182:183], v[22:23], v[42:43], v[182:183] op_sel:[0,1,0] op_sel_hi:[1,1,1]
	v_pk_fma_f32 v[184:185], v[24:25], v[42:43], v[184:185] op_sel:[0,1,0] op_sel_hi:[1,1,1]
	v_pk_fma_f32 v[186:187], v[18:19], v[44:45], v[186:187] op_sel_hi:[1,0,1]
	v_pk_fma_f32 v[188:189], v[20:21], v[44:45], v[188:189] op_sel_hi:[1,0,1]
	v_pk_fma_f32 v[186:187], v[22:23], v[44:45], v[186:187] op_sel:[0,1,0] op_sel_hi:[1,1,1]
	v_pk_fma_f32 v[188:189], v[24:25], v[44:45], v[188:189] op_sel:[0,1,0] op_sel_hi:[1,1,1]
	v_pk_fma_f32 v[190:191], v[18:19], v[46:47], v[190:191] op_sel_hi:[1,0,1]
	v_pk_fma_f32 v[192:193], v[20:21], v[46:47], v[192:193] op_sel_hi:[1,0,1]
	v_pk_fma_f32 v[190:191], v[22:23], v[46:47], v[190:191] op_sel:[0,1,0] op_sel_hi:[1,1,1]
	v_pk_fma_f32 v[192:193], v[24:25], v[46:47], v[192:193] op_sel:[0,1,0] op_sel_hi:[1,1,1]
	v_pk_fma_f32 v[194:195], v[18:19], v[48:49], v[194:195] op_sel_hi:[1,0,1]
	v_pk_fma_f32 v[196:197], v[20:21], v[48:49], v[196:197] op_sel_hi:[1,0,1]
	v_pk_fma_f32 v[194:195], v[22:23], v[48:49], v[194:195] op_sel:[0,1,0] op_sel_hi:[1,1,1]
	v_pk_fma_f32 v[196:197], v[24:25], v[48:49], v[196:197] op_sel:[0,1,0] op_sel_hi:[1,1,1]
	v_pk_fma_f32 v[198:199], v[18:19], v[50:51], v[198:199] op_sel_hi:[1,0,1]
	v_pk_fma_f32 v[200:201], v[20:21], v[50:51], v[200:201] op_sel_hi:[1,0,1]
	v_pk_fma_f32 v[198:199], v[22:23], v[50:51], v[198:199] op_sel:[0,1,0] op_sel_hi:[1,1,1]
	v_pk_fma_f32 v[200:201], v[24:25], v[50:51], v[200:201] op_sel:[0,1,0] op_sel_hi:[1,1,1]
	v_pk_fma_f32 v[202:203], v[18:19], v[52:53], v[202:203] op_sel_hi:[1,0,1]
	v_pk_fma_f32 v[204:205], v[20:21], v[52:53], v[204:205] op_sel_hi:[1,0,1]
	v_pk_fma_f32 v[202:203], v[22:23], v[52:53], v[202:203] op_sel:[0,1,0] op_sel_hi:[1,1,1]
	v_pk_fma_f32 v[204:205], v[24:25], v[52:53], v[204:205] op_sel:[0,1,0] op_sel_hi:[1,1,1]
	v_pk_fma_f32 v[206:207], v[18:19], v[54:55], v[206:207] op_sel_hi:[1,0,1]
	v_pk_fma_f32 v[208:209], v[20:21], v[54:55], v[208:209] op_sel_hi:[1,0,1]
	v_pk_fma_f32 v[206:207], v[22:23], v[54:55], v[206:207] op_sel:[0,1,0] op_sel_hi:[1,1,1]
	v_pk_fma_f32 v[208:209], v[24:25], v[54:55], v[208:209] op_sel:[0,1,0] op_sel_hi:[1,1,1]
	ds_read_b64 v[34:35], v211 offset:45056
	ds_read_b64 v[36:37], v211 offset:49152
	ds_read_b64 v[38:39], v211 offset:53248
	ds_read_b64 v[40:41], v211 offset:57344
	ds_read_b64 v[42:43], v211 offset:61440
	ds_read_b64 v[44:45], v212
	ds_read_b64 v[46:47], v212 offset:4096
	ds_read_b64 v[48:49], v212 offset:8192
	ds_read_b64 v[50:51], v212 offset:12288
	ds_read_b64 v[52:53], v212 offset:16384
	ds_read_b64 v[54:55], v212 offset:20480
	s_waitcnt vmcnt(0) lgkmcnt(11)
	v_pk_fma_f32 v[78:79], v[26:27], v[56:57], v[78:79] op_sel_hi:[1,0,1]
	v_pk_fma_f32 v[80:81], v[28:29], v[56:57], v[80:81] op_sel_hi:[1,0,1]
	v_pk_fma_f32 v[78:79], v[30:31], v[56:57], v[78:79] op_sel:[0,1,0] op_sel_hi:[1,1,1]
	v_pk_fma_f32 v[80:81], v[32:33], v[56:57], v[80:81] op_sel:[0,1,0] op_sel_hi:[1,1,1]
	v_pk_fma_f32 v[82:83], v[26:27], v[58:59], v[82:83] op_sel_hi:[1,0,1]
	v_pk_fma_f32 v[84:85], v[28:29], v[58:59], v[84:85] op_sel_hi:[1,0,1]
	v_pk_fma_f32 v[82:83], v[30:31], v[58:59], v[82:83] op_sel:[0,1,0] op_sel_hi:[1,1,1]
	v_pk_fma_f32 v[84:85], v[32:33], v[58:59], v[84:85] op_sel:[0,1,0] op_sel_hi:[1,1,1]
	v_pk_fma_f32 v[86:87], v[26:27], v[60:61], v[86:87] op_sel_hi:[1,0,1]
	v_pk_fma_f32 v[88:89], v[28:29], v[60:61], v[88:89] op_sel_hi:[1,0,1]
	v_pk_fma_f32 v[86:87], v[30:31], v[60:61], v[86:87] op_sel:[0,1,0] op_sel_hi:[1,1,1]
	v_pk_fma_f32 v[88:89], v[32:33], v[60:61], v[88:89] op_sel:[0,1,0] op_sel_hi:[1,1,1]
	v_pk_fma_f32 v[90:91], v[26:27], v[62:63], v[90:91] op_sel_hi:[1,0,1]
	v_pk_fma_f32 v[92:93], v[28:29], v[62:63], v[92:93] op_sel_hi:[1,0,1]
	v_pk_fma_f32 v[90:91], v[30:31], v[62:63], v[90:91] op_sel:[0,1,0] op_sel_hi:[1,1,1]
	v_pk_fma_f32 v[92:93], v[32:33], v[62:63], v[92:93] op_sel:[0,1,0] op_sel_hi:[1,1,1]
	v_pk_fma_f32 v[94:95], v[26:27], v[64:65], v[94:95] op_sel_hi:[1,0,1]
	v_pk_fma_f32 v[96:97], v[28:29], v[64:65], v[96:97] op_sel_hi:[1,0,1]
	v_pk_fma_f32 v[94:95], v[30:31], v[64:65], v[94:95] op_sel:[0,1,0] op_sel_hi:[1,1,1]
	v_pk_fma_f32 v[96:97], v[32:33], v[64:65], v[96:97] op_sel:[0,1,0] op_sel_hi:[1,1,1]
	v_pk_fma_f32 v[98:99], v[26:27], v[66:67], v[98:99] op_sel_hi:[1,0,1]
	v_pk_fma_f32 v[100:101], v[28:29], v[66:67], v[100:101] op_sel_hi:[1,0,1]
	v_pk_fma_f32 v[98:99], v[30:31], v[66:67], v[98:99] op_sel:[0,1,0] op_sel_hi:[1,1,1]
	v_pk_fma_f32 v[100:101], v[32:33], v[66:67], v[100:101] op_sel:[0,1,0] op_sel_hi:[1,1,1]
	v_pk_fma_f32 v[102:103], v[26:27], v[68:69], v[102:103] op_sel_hi:[1,0,1]
	v_pk_fma_f32 v[104:105], v[28:29], v[68:69], v[104:105] op_sel_hi:[1,0,1]
	v_pk_fma_f32 v[102:103], v[30:31], v[68:69], v[102:103] op_sel:[0,1,0] op_sel_hi:[1,1,1]
	v_pk_fma_f32 v[104:105], v[32:33], v[68:69], v[104:105] op_sel:[0,1,0] op_sel_hi:[1,1,1]
	v_pk_fma_f32 v[106:107], v[26:27], v[70:71], v[106:107] op_sel_hi:[1,0,1]
	v_pk_fma_f32 v[108:109], v[28:29], v[70:71], v[108:109] op_sel_hi:[1,0,1]
	v_pk_fma_f32 v[106:107], v[30:31], v[70:71], v[106:107] op_sel:[0,1,0] op_sel_hi:[1,1,1]
	v_pk_fma_f32 v[108:109], v[32:33], v[70:71], v[108:109] op_sel:[0,1,0] op_sel_hi:[1,1,1]
	v_pk_fma_f32 v[110:111], v[26:27], v[72:73], v[110:111] op_sel_hi:[1,0,1]
	v_pk_fma_f32 v[112:113], v[28:29], v[72:73], v[112:113] op_sel_hi:[1,0,1]
	v_pk_fma_f32 v[110:111], v[30:31], v[72:73], v[110:111] op_sel:[0,1,0] op_sel_hi:[1,1,1]
	v_pk_fma_f32 v[112:113], v[32:33], v[72:73], v[112:113] op_sel:[0,1,0] op_sel_hi:[1,1,1]
	v_pk_fma_f32 v[114:115], v[26:27], v[74:75], v[114:115] op_sel_hi:[1,0,1]
	v_pk_fma_f32 v[116:117], v[28:29], v[74:75], v[116:117] op_sel_hi:[1,0,1]
	v_pk_fma_f32 v[114:115], v[30:31], v[74:75], v[114:115] op_sel:[0,1,0] op_sel_hi:[1,1,1]
	v_pk_fma_f32 v[116:117], v[32:33], v[74:75], v[116:117] op_sel:[0,1,0] op_sel_hi:[1,1,1]
	v_pk_fma_f32 v[118:119], v[26:27], v[76:77], v[118:119] op_sel_hi:[1,0,1]
	v_pk_fma_f32 v[120:121], v[28:29], v[76:77], v[120:121] op_sel_hi:[1,0,1]
	v_pk_fma_f32 v[118:119], v[30:31], v[76:77], v[118:119] op_sel:[0,1,0] op_sel_hi:[1,1,1]
	v_pk_fma_f32 v[120:121], v[32:33], v[76:77], v[120:121] op_sel:[0,1,0] op_sel_hi:[1,1,1]
	ds_read_b64 v[56:57], v212 offset:24576
	ds_read_b64 v[58:59], v212 offset:28672
	ds_read_b64 v[60:61], v212 offset:32768
	ds_read_b64 v[62:63], v212 offset:36864
	ds_read_b64 v[64:65], v212 offset:40960
	ds_read_b64 v[66:67], v212 offset:45056
	ds_read_b64 v[68:69], v212 offset:49152
	ds_read_b64 v[70:71], v212 offset:53248
	ds_read_b64 v[72:73], v212 offset:57344
	ds_read_b64 v[74:75], v212 offset:61440
	ds_read_b64 v[76:77], v213
	s_waitcnt lgkmcnt(11)
; #define LAS __attribute__((address_space(3)))
; __device__ void phase_setup(const Params& p, LAS unsigned char* lds) {
;     ...
;             for (int k = 0; k < D; k += 16) {
;                 f32x4 w[16];
; #pragma unroll
;                 for (int kk = 0; kk < 16; ++kk) w[kk] = *(const f32x4*)(wp + (size_t)(k + kk) * (NMOD * D));
; #pragma unroll
;                 for (int i = 0; i < 5; ++i) { const int r = (i < 4) ? wid + 8 * i : 32;
; #pragma unroll
;                     for (int k4 = 0; k4 < 4; ++k4) { const f32x4 s4 = *(const LAS f32x4*)(sc + r * D + k + 4 * k4);
;                         a[i] += s4[0] * w[4 * k4] + s4[1] * w[4 * k4 + 1] + s4[2] * w[4 * k4 + 2] + s4[3] * w[4 * k4 + 3]; } }
	v_pk_fma_f32 v[122:123], v[26:27], v[34:35], v[122:123] op_sel_hi:[1,0,1]
	v_pk_fma_f32 v[124:125], v[28:29], v[34:35], v[124:125] op_sel_hi:[1,0,1]
	v_pk_fma_f32 v[122:123], v[30:31], v[34:35], v[122:123] op_sel:[0,1,0] op_sel_hi:[1,1,1]
	v_pk_fma_f32 v[124:125], v[32:33], v[34:35], v[124:125] op_sel:[0,1,0] op_sel_hi:[1,1,1]
	v_pk_fma_f32 v[126:127], v[26:27], v[36:37], v[126:127] op_sel_hi:[1,0,1]
	v_pk_fma_f32 v[128:129], v[28:29], v[36:37], v[128:129] op_sel_hi:[1,0,1]
	v_pk_fma_f32 v[126:127], v[30:31], v[36:37], v[126:127] op_sel:[0,1,0] op_sel_hi:[1,1,1]
	v_pk_fma_f32 v[128:129], v[32:33], v[36:37], v[128:129] op_sel:[0,1,0] op_sel_hi:[1,1,1]
	v_pk_fma_f32 v[130:131], v[26:27], v[38:39], v[130:131] op_sel_hi:[1,0,1]
	v_pk_fma_f32 v[132:133], v[28:29], v[38:39], v[132:133] op_sel_hi:[1,0,1]
	v_pk_fma_f32 v[130:131], v[30:31], v[38:39], v[130:131] op_sel:[0,1,0] op_sel_hi:[1,1,1]
	v_pk_fma_f32 v[132:133], v[32:33], v[38:39], v[132:133] op_sel:[0,1,0] op_sel_hi:[1,1,1]
	v_pk_fma_f32 v[134:135], v[26:27], v[40:41], v[134:135] op_sel_hi:[1,0,1]
	v_pk_fma_f32 v[136:137], v[28:29], v[40:41], v[136:137] op_sel_hi:[1,0,1]
	v_pk_fma_f32 v[134:135], v[30:31], v[40:41], v[134:135] op_sel:[0,1,0] op_sel_hi:[1,1,1]
	v_pk_fma_f32 v[136:137], v[32:33], v[40:41], v[136:137] op_sel:[0,1,0] op_sel_hi:[1,1,1]
	v_pk_fma_f32 v[138:139], v[26:27], v[42:43], v[138:139] op_sel_hi:[1,0,1]
	v_pk_fma_f32 v[140:141], v[28:29], v[42:43], v[140:141] op_sel_hi:[1,0,1]
	v_pk_fma_f32 v[138:139], v[30:31], v[42:43], v[138:139] op_sel:[0,1,0] op_sel_hi:[1,1,1]
	v_pk_fma_f32 v[140:141], v[32:33], v[42:43], v[140:141] op_sel:[0,1,0] op_sel_hi:[1,1,1]
	v_pk_fma_f32 v[142:143], v[26:27], v[44:45], v[142:143] op_sel_hi:[1,0,1]
	v_pk_fma_f32 v[144:145], v[28:29], v[44:45], v[144:145] op_sel_hi:[1,0,1]
	v_pk_fma_f32 v[142:143], v[30:31], v[44:45], v[142:143] op_sel:[0,1,0] op_sel_hi:[1,1,1]
	v_pk_fma_f32 v[144:145], v[32:33], v[44:45], v[144:145] op_sel:[0,1,0] op_sel_hi:[1,1,1]
	v_pk_fma_f32 v[146:147], v[26:27], v[46:47], v[146:147] op_sel_hi:[1,0,1]
	v_pk_fma_f32 v[148:149], v[28:29], v[46:47], v[148:149] op_sel_hi:[1,0,1]
	v_pk_fma_f32 v[146:147], v[30:31], v[46:47], v[146:147] op_sel:[0,1,0] op_sel_hi:[1,1,1]
	v_pk_fma_f32 v[148:149], v[32:33], v[46:47], v[148:149] op_sel:[0,1,0] op_sel_hi:[1,1,1]
	v_pk_fma_f32 v[150:151], v[26:27], v[48:49], v[150:151] op_sel_hi:[1,0,1]
	v_pk_fma_f32 v[152:153], v[28:29], v[48:49], v[152:153] op_sel_hi:[1,0,1]
	v_pk_fma_f32 v[150:151], v[30:31], v[48:49], v[150:151] op_sel:[0,1,0] op_sel_hi:[1,1,1]
	v_pk_fma_f32 v[152:153], v[32:33], v[48:49], v[152:153] op_sel:[0,1,0] op_sel_hi:[1,1,1]
	v_pk_fma_f32 v[154:155], v[26:27], v[50:51], v[154:155] op_sel_hi:[1,0,1]
	v_pk_fma_f32 v[156:157], v[28:29], v[50:51], v[156:157] op_sel_hi:[1,0,1]
	v_pk_fma_f32 v[154:155], v[30:31], v[50:51], v[154:155] op_sel:[0,1,0] op_sel_hi:[1,1,1]
	v_pk_fma_f32 v[156:157], v[32:33], v[50:51], v[156:157] op_sel:[0,1,0] op_sel_hi:[1,1,1]
	v_pk_fma_f32 v[158:159], v[26:27], v[52:53], v[158:159] op_sel_hi:[1,0,1]
	v_pk_fma_f32 v[160:161], v[28:29], v[52:53], v[160:161] op_sel_hi:[1,0,1]
	v_pk_fma_f32 v[158:159], v[30:31], v[52:53], v[158:159] op_sel:[0,1,0] op_sel_hi:[1,1,1]
	v_pk_fma_f32 v[160:161], v[32:33], v[52:53], v[160:161] op_sel:[0,1,0] op_sel_hi:[1,1,1]
	v_pk_fma_f32 v[162:163], v[26:27], v[54:55], v[162:163] op_sel_hi:[1,0,1]
	v_pk_fma_f32 v[164:165], v[28:29], v[54:55], v[164:165] op_sel_hi:[1,0,1]
	v_pk_fma_f32 v[162:163], v[30:31], v[54:55], v[162:163] op_sel:[0,1,0] op_sel_hi:[1,1,1]
	v_pk_fma_f32 v[164:165], v[32:33], v[54:55], v[164:165] op_sel:[0,1,0] op_sel_hi:[1,1,1]
	ds_read_b64 v[34:35], v211 offset:64
	ds_read_b64 v[36:37], v211 offset:4160
	ds_read_b64 v[38:39], v211 offset:8256
	ds_read_b64 v[40:41], v211 offset:12352
	ds_read_b64 v[42:43], v211 offset:16448
	ds_read_b64 v[44:45], v211 offset:20544
	ds_read_b64 v[46:47], v211 offset:24640
	ds_read_b64 v[48:49], v211 offset:28736
	ds_read_b64 v[50:51], v211 offset:32832
	ds_read_b64 v[52:53], v211 offset:36928
	ds_read_b64 v[54:55], v211 offset:41024
	v_add_u32_e32 v211, 64, v211
	v_add_u32_e32 v212, 64, v212
	v_add_u32_e32 v213, 64, v213
	s_waitcnt lgkmcnt(11)
	v_pk_fma_f32 v[166:167], v[26:27], v[56:57], v[166:167] op_sel_hi:[1,0,1]
	v_pk_fma_f32 v[168:169], v[28:29], v[56:57], v[168:169] op_sel_hi:[1,0,1]
	v_pk_fma_f32 v[166:167], v[30:31], v[56:57], v[166:167] op_sel:[0,1,0] op_sel_hi:[1,1,1]
	v_pk_fma_f32 v[168:169], v[32:33], v[56:57], v[168:169] op_sel:[0,1,0] op_sel_hi:[1,1,1]
	v_pk_fma_f32 v[170:171], v[26:27], v[58:59], v[170:171] op_sel_hi:[1,0,1]
	v_pk_fma_f32 v[172:173], v[28:29], v[58:59], v[172:173] op_sel_hi:[1,0,1]
	v_pk_fma_f32 v[170:171], v[30:31], v[58:59], v[170:171] op_sel:[0,1,0] op_sel_hi:[1,1,1]
	v_pk_fma_f32 v[172:173], v[32:33], v[58:59], v[172:173] op_sel:[0,1,0] op_sel_hi:[1,1,1]
	v_pk_fma_f32 v[174:175], v[26:27], v[60:61], v[174:175] op_sel_hi:[1,0,1]
	v_pk_fma_f32 v[176:177], v[28:29], v[60:61], v[176:177] op_sel_hi:[1,0,1]
	v_pk_fma_f32 v[174:175], v[30:31], v[60:61], v[174:175] op_sel:[0,1,0] op_sel_hi:[1,1,1]
	v_pk_fma_f32 v[176:177], v[32:33], v[60:61], v[176:177] op_sel:[0,1,0] op_sel_hi:[1,1,1]
	v_pk_fma_f32 v[178:179], v[26:27], v[62:63], v[178:179] op_sel_hi:[1,0,1]
	v_pk_fma_f32 v[180:181], v[28:29], v[62:63], v[180:181] op_sel_hi:[1,0,1]
	v_pk_fma_f32 v[178:179], v[30:31], v[62:63], v[178:179] op_sel:[0,1,0] op_sel_hi:[1,1,1]
	v_pk_fma_f32 v[180:181], v[32:33], v[62:63], v[180:181] op_sel:[0,1,0] op_sel_hi:[1,1,1]
	v_pk_fma_f32 v[182:183], v[26:27], v[64:65], v[182:183] op_sel_hi:[1,0,1]
	v_pk_fma_f32 v[184:185], v[28:29], v[64:65], v[184:185] op_sel_hi:[1,0,1]
; #define LAS __attribute__((address_space(3)))
; __device__ void phase_setup(const Params& p, LAS unsigned char* lds) {
;     ...
;                 for (int i = 0; i < 5; ++i) { const int r = (i < 4) ? wid + 8 * i : 32;
; #pragma unroll
;                     for (int k4 = 0; k4 < 4; ++k4) { const f32x4 s4 = *(const LAS f32x4*)(sc + r * D + k + 4 * k4);
;                         a[i] += s4[0] * w[4 * k4] + s4[1] * w[4 * k4 + 1] + s4[2] * w[4 * k4 + 2] + s4[3] * w[4 * k4 + 3]; } }
;             }
;             const f32x4 bv = *(const f32x4*)(p.in[I_BMOD] + (size_t)l * (NMOD * D) + n0);
; #pragma unroll
;             for (int i = 0; i < 5; ++i) { const int r = (i < 4) ? wid + 8 * i : 32; if (i < 4 || wid == 0) *(f32x4*)(MOD + ((size_t)l * 33 + r) * (NMOD * D) + n0) = a[i] + bv; }
	v_pk_fma_f32 v[182:183], v[30:31], v[64:65], v[182:183] op_sel:[0,1,0] op_sel_hi:[1,1,1]
	v_pk_fma_f32 v[184:185], v[32:33], v[64:65], v[184:185] op_sel:[0,1,0] op_sel_hi:[1,1,1]
	v_pk_fma_f32 v[186:187], v[26:27], v[66:67], v[186:187] op_sel_hi:[1,0,1]
	v_pk_fma_f32 v[188:189], v[28:29], v[66:67], v[188:189] op_sel_hi:[1,0,1]
	v_pk_fma_f32 v[186:187], v[30:31], v[66:67], v[186:187] op_sel:[0,1,0] op_sel_hi:[1,1,1]
	v_pk_fma_f32 v[188:189], v[32:33], v[66:67], v[188:189] op_sel:[0,1,0] op_sel_hi:[1,1,1]
	v_pk_fma_f32 v[190:191], v[26:27], v[68:69], v[190:191] op_sel_hi:[1,0,1]
	v_pk_fma_f32 v[192:193], v[28:29], v[68:69], v[192:193] op_sel_hi:[1,0,1]
	v_pk_fma_f32 v[190:191], v[30:31], v[68:69], v[190:191] op_sel:[0,1,0] op_sel_hi:[1,1,1]
	v_pk_fma_f32 v[192:193], v[32:33], v[68:69], v[192:193] op_sel:[0,1,0] op_sel_hi:[1,1,1]
	v_pk_fma_f32 v[194:195], v[26:27], v[70:71], v[194:195] op_sel_hi:[1,0,1]
	v_pk_fma_f32 v[196:197], v[28:29], v[70:71], v[196:197] op_sel_hi:[1,0,1]
	v_pk_fma_f32 v[194:195], v[30:31], v[70:71], v[194:195] op_sel:[0,1,0] op_sel_hi:[1,1,1]
	v_pk_fma_f32 v[196:197], v[32:33], v[70:71], v[196:197] op_sel:[0,1,0] op_sel_hi:[1,1,1]
	v_pk_fma_f32 v[198:199], v[26:27], v[72:73], v[198:199] op_sel_hi:[1,0,1]
	v_pk_fma_f32 v[200:201], v[28:29], v[72:73], v[200:201] op_sel_hi:[1,0,1]
	v_pk_fma_f32 v[198:199], v[30:31], v[72:73], v[198:199] op_sel:[0,1,0] op_sel_hi:[1,1,1]
	v_pk_fma_f32 v[200:201], v[32:33], v[72:73], v[200:201] op_sel:[0,1,0] op_sel_hi:[1,1,1]
	v_pk_fma_f32 v[202:203], v[26:27], v[74:75], v[202:203] op_sel_hi:[1,0,1]
	v_pk_fma_f32 v[204:205], v[28:29], v[74:75], v[204:205] op_sel_hi:[1,0,1]
	v_pk_fma_f32 v[202:203], v[30:31], v[74:75], v[202:203] op_sel:[0,1,0] op_sel_hi:[1,1,1]
	v_pk_fma_f32 v[204:205], v[32:33], v[74:75], v[204:205] op_sel:[0,1,0] op_sel_hi:[1,1,1]
	v_pk_fma_f32 v[206:207], v[26:27], v[76:77], v[206:207] op_sel_hi:[1,0,1]
	v_pk_fma_f32 v[208:209], v[28:29], v[76:77], v[208:209] op_sel_hi:[1,0,1]
	v_pk_fma_f32 v[206:207], v[30:31], v[76:77], v[206:207] op_sel:[0,1,0] op_sel_hi:[1,1,1]
	v_pk_fma_f32 v[208:209], v[32:33], v[76:77], v[208:209] op_sel:[0,1,0] op_sel_hi:[1,1,1]
	s_waitcnt lgkmcnt(0)
	v_add_f32_dpp v78, v78, v78 row_ror:8 row_mask:0xf bank_mask:0xf
	v_add_f32_dpp v79, v79, v79 row_ror:8 row_mask:0xf bank_mask:0xf
	v_add_f32_dpp v80, v80, v80 row_ror:8 row_mask:0xf bank_mask:0xf
	v_add_f32_dpp v81, v81, v81 row_ror:8 row_mask:0xf bank_mask:0xf
	v_add_f32_dpp v82, v82, v82 row_ror:8 row_mask:0xf bank_mask:0xf
	v_add_f32_dpp v83, v83, v83 row_ror:8 row_mask:0xf bank_mask:0xf
	v_add_f32_dpp v84, v84, v84 row_ror:8 row_mask:0xf bank_mask:0xf
	v_add_f32_dpp v85, v85, v85 row_ror:8 row_mask:0xf bank_mask:0xf
	v_add_f32_dpp v86, v86, v86 row_ror:8 row_mask:0xf bank_mask:0xf
	v_add_f32_dpp v87, v87, v87 row_ror:8 row_mask:0xf bank_mask:0xf
	v_add_f32_dpp v88, v88, v88 row_ror:8 row_mask:0xf bank_mask:0xf
	v_add_f32_dpp v89, v89, v89 row_ror:8 row_mask:0xf bank_mask:0xf
	v_add_f32_dpp v90, v90, v90 row_ror:8 row_mask:0xf bank_mask:0xf
	v_add_f32_dpp v91, v91, v91 row_ror:8 row_mask:0xf bank_mask:0xf
	v_add_f32_dpp v92, v92, v92 row_ror:8 row_mask:0xf bank_mask:0xf
	v_add_f32_dpp v93, v93, v93 row_ror:8 row_mask:0xf bank_mask:0xf
	v_add_f32_dpp v94, v94, v94 row_ror:8 row_mask:0xf bank_mask:0xf
	v_add_f32_dpp v95, v95, v95 row_ror:8 row_mask:0xf bank_mask:0xf
	v_add_f32_dpp v96, v96, v96 row_ror:8 row_mask:0xf bank_mask:0xf
	v_add_f32_dpp v97, v97, v97 row_ror:8 row_mask:0xf bank_mask:0xf
	v_add_f32_dpp v98, v98, v98 row_ror:8 row_mask:0xf bank_mask:0xf
	v_add_f32_dpp v99, v99, v99 row_ror:8 row_mask:0xf bank_mask:0xf
	v_add_f32_dpp v100, v100, v100 row_ror:8 row_mask:0xf bank_mask:0xf
	v_add_f32_dpp v101, v101, v101 row_ror:8 row_mask:0xf bank_mask:0xf
	v_add_f32_dpp v102, v102, v102 row_ror:8 row_mask:0xf bank_mask:0xf
	v_add_f32_dpp v103, v103, v103 row_ror:8 row_mask:0xf bank_mask:0xf
	v_add_f32_dpp v104, v104, v104 row_ror:8 row_mask:0xf bank_mask:0xf
	v_add_f32_dpp v105, v105, v105 row_ror:8 row_mask:0xf bank_mask:0xf
	v_add_f32_dpp v106, v106, v106 row_ror:8 row_mask:0xf bank_mask:0xf
	v_add_f32_dpp v107, v107, v107 row_ror:8 row_mask:0xf bank_mask:0xf
	v_add_f32_dpp v108, v108, v108 row_ror:8 row_mask:0xf bank_mask:0xf
	v_add_f32_dpp v109, v109, v109 row_ror:8 row_mask:0xf bank_mask:0xf
	v_add_f32_dpp v110, v110, v110 row_ror:8 row_mask:0xf bank_mask:0xf
	v_add_f32_dpp v111, v111, v111 row_ror:8 row_mask:0xf bank_mask:0xf
	v_add_f32_dpp v112, v112, v112 row_ror:8 row_mask:0xf bank_mask:0xf
	v_add_f32_dpp v113, v113, v113 row_ror:8 row_mask:0xf bank_mask:0xf
	v_add_f32_dpp v114, v114, v114 row_ror:8 row_mask:0xf bank_mask:0xf
	v_add_f32_dpp v115, v115, v115 row_ror:8 row_mask:0xf bank_mask:0xf
	v_add_f32_dpp v116, v116, v116 row_ror:8 row_mask:0xf bank_mask:0xf
	v_add_f32_dpp v117, v117, v117 row_ror:8 row_mask:0xf bank_mask:0xf
	v_add_f32_dpp v118, v118, v118 row_ror:8 row_mask:0xf bank_mask:0xf
	v_add_f32_dpp v119, v119, v119 row_ror:8 row_mask:0xf bank_mask:0xf
	v_add_f32_dpp v120, v120, v120 row_ror:8 row_mask:0xf bank_mask:0xf
	v_add_f32_dpp v121, v121, v121 row_ror:8 row_mask:0xf bank_mask:0xf
	v_add_f32_dpp v122, v122, v122 row_ror:8 row_mask:0xf bank_mask:0xf
	v_add_f32_dpp v123, v123, v123 row_ror:8 row_mask:0xf bank_mask:0xf
	v_add_f32_dpp v124, v124, v124 row_ror:8 row_mask:0xf bank_mask:0xf
	v_add_f32_dpp v125, v125, v125 row_ror:8 row_mask:0xf bank_mask:0xf
	v_add_f32_dpp v126, v126, v126 row_ror:8 row_mask:0xf bank_mask:0xf
	v_add_f32_dpp v127, v127, v127 row_ror:8 row_mask:0xf bank_mask:0xf
	v_add_f32_dpp v128, v128, v128 row_ror:8 row_mask:0xf bank_mask:0xf
; #define LAS __attribute__((address_space(3)))
; __device__ void phase_setup(const Params& p, LAS unsigned char* lds) {
;     ...
;                 for (int i = 0; i < 5; ++i) { const int r = (i < 4) ? wid + 8 * i : 32;
; #pragma unroll
;                     for (int k4 = 0; k4 < 4; ++k4) { const f32x4 s4 = *(const LAS f32x4*)(sc + r * D + k + 4 * k4);
;                         a[i] += s4[0] * w[4 * k4] + s4[1] * w[4 * k4 + 1] + s4[2] * w[4 * k4 + 2] + s4[3] * w[4 * k4 + 3]; } }
;             }
;             const f32x4 bv = *(const f32x4*)(p.in[I_BMOD] + (size_t)l * (NMOD * D) + n0);
; #pragma unroll
;             for (int i = 0; i < 5; ++i) { const int r = (i < 4) ? wid + 8 * i : 32; if (i < 4 || wid == 0) *(f32x4*)(MOD + ((size_t)l * 33 + r) * (NMOD * D) + n0) = a[i] + bv; }
	v_add_f32_dpp v129, v129, v129 row_ror:8 row_mask:0xf bank_mask:0xf
	v_add_f32_dpp v130, v130, v130 row_ror:8 row_mask:0xf bank_mask:0xf
	v_add_f32_dpp v131, v131, v131 row_ror:8 row_mask:0xf bank_mask:0xf
	v_add_f32_dpp v132, v132, v132 row_ror:8 row_mask:0xf bank_mask:0xf
	v_add_f32_dpp v133, v133, v133 row_ror:8 row_mask:0xf bank_mask:0xf
	v_add_f32_dpp v134, v134, v134 row_ror:8 row_mask:0xf bank_mask:0xf
	v_add_f32_dpp v135, v135, v135 row_ror:8 row_mask:0xf bank_mask:0xf
	v_add_f32_dpp v136, v136, v136 row_ror:8 row_mask:0xf bank_mask:0xf
	v_add_f32_dpp v137, v137, v137 row_ror:8 row_mask:0xf bank_mask:0xf
	v_add_f32_dpp v138, v138, v138 row_ror:8 row_mask:0xf bank_mask:0xf
	v_add_f32_dpp v139, v139, v139 row_ror:8 row_mask:0xf bank_mask:0xf
	v_add_f32_dpp v140, v140, v140 row_ror:8 row_mask:0xf bank_mask:0xf
	v_add_f32_dpp v141, v141, v141 row_ror:8 row_mask:0xf bank_mask:0xf
	v_add_f32_dpp v142, v142, v142 row_ror:8 row_mask:0xf bank_mask:0xf
	v_add_f32_dpp v143, v143, v143 row_ror:8 row_mask:0xf bank_mask:0xf
	v_add_f32_dpp v144, v144, v144 row_ror:8 row_mask:0xf bank_mask:0xf
	v_add_f32_dpp v145, v145, v145 row_ror:8 row_mask:0xf bank_mask:0xf
	v_add_f32_dpp v146, v146, v146 row_ror:8 row_mask:0xf bank_mask:0xf
	v_add_f32_dpp v147, v147, v147 row_ror:8 row_mask:0xf bank_mask:0xf
	v_add_f32_dpp v148, v148, v148 row_ror:8 row_mask:0xf bank_mask:0xf
	v_add_f32_dpp v149, v149, v149 row_ror:8 row_mask:0xf bank_mask:0xf
	v_add_f32_dpp v150, v150, v150 row_ror:8 row_mask:0xf bank_mask:0xf
	v_add_f32_dpp v151, v151, v151 row_ror:8 row_mask:0xf bank_mask:0xf
	v_add_f32_dpp v152, v152, v152 row_ror:8 row_mask:0xf bank_mask:0xf
	v_add_f32_dpp v153, v153, v153 row_ror:8 row_mask:0xf bank_mask:0xf
	v_add_f32_dpp v154, v154, v154 row_ror:8 row_mask:0xf bank_mask:0xf
	v_add_f32_dpp v155, v155, v155 row_ror:8 row_mask:0xf bank_mask:0xf
	v_add_f32_dpp v156, v156, v156 row_ror:8 row_mask:0xf bank_mask:0xf
	v_add_f32_dpp v157, v157, v157 row_ror:8 row_mask:0xf bank_mask:0xf
	v_add_f32_dpp v158, v158, v158 row_ror:8 row_mask:0xf bank_mask:0xf
	v_add_f32_dpp v159, v159, v159 row_ror:8 row_mask:0xf bank_mask:0xf
	v_add_f32_dpp v160, v160, v160 row_ror:8 row_mask:0xf bank_mask:0xf
	v_add_f32_dpp v161, v161, v161 row_ror:8 row_mask:0xf bank_mask:0xf
	v_add_f32_dpp v162, v162, v162 row_ror:8 row_mask:0xf bank_mask:0xf
	v_add_f32_dpp v163, v163, v163 row_ror:8 row_mask:0xf bank_mask:0xf
	v_add_f32_dpp v164, v164, v164 row_ror:8 row_mask:0xf bank_mask:0xf
	v_add_f32_dpp v165, v165, v165 row_ror:8 row_mask:0xf bank_mask:0xf
	v_add_f32_dpp v166, v166, v166 row_ror:8 row_mask:0xf bank_mask:0xf
	v_add_f32_dpp v167, v167, v167 row_ror:8 row_mask:0xf bank_mask:0xf
	v_add_f32_dpp v168, v168, v168 row_ror:8 row_mask:0xf bank_mask:0xf
	v_add_f32_dpp v169, v169, v169 row_ror:8 row_mask:0xf bank_mask:0xf
	v_add_f32_dpp v170, v170, v170 row_ror:8 row_mask:0xf bank_mask:0xf
	v_add_f32_dpp v171, v171, v171 row_ror:8 row_mask:0xf bank_mask:0xf
	v_add_f32_dpp v172, v172, v172 row_ror:8 row_mask:0xf bank_mask:0xf
	v_add_f32_dpp v173, v173, v173 row_ror:8 row_mask:0xf bank_mask:0xf
	v_add_f32_dpp v174, v174, v174 row_ror:8 row_mask:0xf bank_mask:0xf
	v_add_f32_dpp v175, v175, v175 row_ror:8 row_mask:0xf bank_mask:0xf
	v_add_f32_dpp v176, v176, v176 row_ror:8 row_mask:0xf bank_mask:0xf
	v_add_f32_dpp v177, v177, v177 row_ror:8 row_mask:0xf bank_mask:0xf
	v_add_f32_dpp v178, v178, v178 row_ror:8 row_mask:0xf bank_mask:0xf
	v_add_f32_dpp v179, v179, v179 row_ror:8 row_mask:0xf bank_mask:0xf
	v_add_f32_dpp v180, v180, v180 row_ror:8 row_mask:0xf bank_mask:0xf
	v_add_f32_dpp v181, v181, v181 row_ror:8 row_mask:0xf bank_mask:0xf
	v_add_f32_dpp v182, v182, v182 row_ror:8 row_mask:0xf bank_mask:0xf
	v_add_f32_dpp v183, v183, v183 row_ror:8 row_mask:0xf bank_mask:0xf
	v_add_f32_dpp v184, v184, v184 row_ror:8 row_mask:0xf bank_mask:0xf
	v_add_f32_dpp v185, v185, v185 row_ror:8 row_mask:0xf bank_mask:0xf
	v_add_f32_dpp v186, v186, v186 row_ror:8 row_mask:0xf bank_mask:0xf
	v_add_f32_dpp v187, v187, v187 row_ror:8 row_mask:0xf bank_mask:0xf
	v_add_f32_dpp v188, v188, v188 row_ror:8 row_mask:0xf bank_mask:0xf
	v_add_f32_dpp v189, v189, v189 row_ror:8 row_mask:0xf bank_mask:0xf
	v_add_f32_dpp v190, v190, v190 row_ror:8 row_mask:0xf bank_mask:0xf
	v_add_f32_dpp v191, v191, v191 row_ror:8 row_mask:0xf bank_mask:0xf
	v_add_f32_dpp v192, v192, v192 row_ror:8 row_mask:0xf bank_mask:0xf
	v_add_f32_dpp v193, v193, v193 row_ror:8 row_mask:0xf bank_mask:0xf
	v_add_f32_dpp v194, v194, v194 row_ror:8 row_mask:0xf bank_mask:0xf
	v_add_f32_dpp v195, v195, v195 row_ror:8 row_mask:0xf bank_mask:0xf
	v_add_f32_dpp v196, v196, v196 row_ror:8 row_mask:0xf bank_mask:0xf
	v_add_f32_dpp v197, v197, v197 row_ror:8 row_mask:0xf bank_mask:0xf
	v_add_f32_dpp v198, v198, v198 row_ror:8 row_mask:0xf bank_mask:0xf
	v_add_f32_dpp v199, v199, v199 row_ror:8 row_mask:0xf bank_mask:0xf
	v_add_f32_dpp v200, v200, v200 row_ror:8 row_mask:0xf bank_mask:0xf
	v_add_f32_dpp v201, v201, v201 row_ror:8 row_mask:0xf bank_mask:0xf
	v_add_f32_dpp v202, v202, v202 row_ror:8 row_mask:0xf bank_mask:0xf
	v_add_f32_dpp v203, v203, v203 row_ror:8 row_mask:0xf bank_mask:0xf
	v_add_f32_dpp v204, v204, v204 row_ror:8 row_mask:0xf bank_mask:0xf
	v_add_f32_dpp v205, v205, v205 row_ror:8 row_mask:0xf bank_mask:0xf
	v_add_f32_dpp v206, v206, v206 row_ror:8 row_mask:0xf bank_mask:0xf
	v_add_f32_dpp v207, v207, v207 row_ror:8 row_mask:0xf bank_mask:0xf
	v_add_f32_dpp v208, v208, v208 row_ror:8 row_mask:0xf bank_mask:0xf
	v_add_f32_dpp v209, v209, v209 row_ror:8 row_mask:0xf bank_mask:0xf
	v_mov_b32_e32 v2, v78
	v_mov_b32_e32 v3, v79
; #define LAS __attribute__((address_space(3)))
; __device__ void phase_setup(const Params& p, LAS unsigned char* lds) {
;     ...
;                 for (int i = 0; i < 5; ++i) { const int r = (i < 4) ? wid + 8 * i : 32;
; #pragma unroll
;                     for (int k4 = 0; k4 < 4; ++k4) { const f32x4 s4 = *(const LAS f32x4*)(sc + r * D + k + 4 * k4);
;                         a[i] += s4[0] * w[4 * k4] + s4[1] * w[4 * k4 + 1] + s4[2] * w[4 * k4 + 2] + s4[3] * w[4 * k4 + 3]; } }
;             }
;             const f32x4 bv = *(const f32x4*)(p.in[I_BMOD] + (size_t)l * (NMOD * D) + n0);
; #pragma unroll
;             for (int i = 0; i < 5; ++i) { const int r = (i < 4) ? wid + 8 * i : 32; if (i < 4 || wid == 0) *(f32x4*)(MOD + ((size_t)l * 33 + r) * (NMOD * D) + n0) = a[i] + bv; }
	v_mov_b32_e32 v4, v80
	v_mov_b32_e32 v5, v81
	s_nop 1
	v_permlane16_swap_b32_e32 v2, v78
	v_permlane16_swap_b32_e32 v3, v79
	v_permlane16_swap_b32_e32 v4, v80
	v_permlane16_swap_b32_e32 v5, v81
	v_add_f32_e32 v78, v78, v2
	v_add_f32_e32 v79, v79, v3
	v_add_f32_e32 v80, v80, v4
	v_add_f32_e32 v81, v81, v5
	v_mov_b32_e32 v2, v82
	v_mov_b32_e32 v3, v83
	v_mov_b32_e32 v4, v84
	v_mov_b32_e32 v5, v85
	s_nop 1
	v_permlane16_swap_b32_e32 v2, v82
	v_permlane16_swap_b32_e32 v3, v83
	v_permlane16_swap_b32_e32 v4, v84
	v_permlane16_swap_b32_e32 v5, v85
	v_add_f32_e32 v82, v82, v2
	v_add_f32_e32 v83, v83, v3
	v_add_f32_e32 v84, v84, v4
	v_add_f32_e32 v85, v85, v5
	v_mov_b32_e32 v2, v86
	v_mov_b32_e32 v3, v87
	v_mov_b32_e32 v4, v88
	v_mov_b32_e32 v5, v89
	s_nop 1
	v_permlane16_swap_b32_e32 v2, v86
	v_permlane16_swap_b32_e32 v3, v87
	v_permlane16_swap_b32_e32 v4, v88
	v_permlane16_swap_b32_e32 v5, v89
	v_add_f32_e32 v86, v86, v2
	v_add_f32_e32 v87, v87, v3
	v_add_f32_e32 v88, v88, v4
	v_add_f32_e32 v89, v89, v5
	v_mov_b32_e32 v2, v90
	v_mov_b32_e32 v3, v91
	v_mov_b32_e32 v4, v92
	v_mov_b32_e32 v5, v93
	s_nop 1
	v_permlane16_swap_b32_e32 v2, v90
	v_permlane16_swap_b32_e32 v3, v91
	v_permlane16_swap_b32_e32 v4, v92
	v_permlane16_swap_b32_e32 v5, v93
	v_add_f32_e32 v90, v90, v2
	v_add_f32_e32 v91, v91, v3
	v_add_f32_e32 v92, v92, v4
	v_add_f32_e32 v93, v93, v5
	v_mov_b32_e32 v2, v94
	v_mov_b32_e32 v3, v95
	v_mov_b32_e32 v4, v96
	v_mov_b32_e32 v5, v97
	s_nop 1
	v_permlane16_swap_b32_e32 v2, v94
	v_permlane16_swap_b32_e32 v3, v95
	v_permlane16_swap_b32_e32 v4, v96
	v_permlane16_swap_b32_e32 v5, v97
	v_add_f32_e32 v94, v94, v2
	v_add_f32_e32 v95, v95, v3
	v_add_f32_e32 v96, v96, v4
	v_add_f32_e32 v97, v97, v5
	v_mov_b32_e32 v2, v98
	v_mov_b32_e32 v3, v99
	v_mov_b32_e32 v4, v100
	v_mov_b32_e32 v5, v101
	s_nop 1
	v_permlane16_swap_b32_e32 v2, v98
	v_permlane16_swap_b32_e32 v3, v99
	v_permlane16_swap_b32_e32 v4, v100
	v_permlane16_swap_b32_e32 v5, v101
	v_add_f32_e32 v98, v98, v2
	v_add_f32_e32 v99, v99, v3
	v_add_f32_e32 v100, v100, v4
	v_add_f32_e32 v101, v101, v5
	v_mov_b32_e32 v2, v102
	v_mov_b32_e32 v3, v103
	v_mov_b32_e32 v4, v104
	v_mov_b32_e32 v5, v105
	s_nop 1
	v_permlane16_swap_b32_e32 v2, v102
	v_permlane16_swap_b32_e32 v3, v103
	v_permlane16_swap_b32_e32 v4, v104
	v_permlane16_swap_b32_e32 v5, v105
	v_add_f32_e32 v102, v102, v2
	v_add_f32_e32 v103, v103, v3
	v_add_f32_e32 v104, v104, v4
	v_add_f32_e32 v105, v105, v5
	v_mov_b32_e32 v2, v106
	v_mov_b32_e32 v3, v107
	v_mov_b32_e32 v4, v108
	v_mov_b32_e32 v5, v109
	s_nop 1
	v_permlane16_swap_b32_e32 v2, v106
	v_permlane16_swap_b32_e32 v3, v107
	v_permlane16_swap_b32_e32 v4, v108
	v_permlane16_swap_b32_e32 v5, v109
	v_add_f32_e32 v106, v106, v2
	v_add_f32_e32 v107, v107, v3
	v_add_f32_e32 v108, v108, v4
	v_add_f32_e32 v109, v109, v5
	v_mov_b32_e32 v2, v110
	v_mov_b32_e32 v3, v111
	v_mov_b32_e32 v4, v112
	v_mov_b32_e32 v5, v113
	s_nop 1
	v_permlane16_swap_b32_e32 v2, v110
	v_permlane16_swap_b32_e32 v3, v111
	v_permlane16_swap_b32_e32 v4, v112
	v_permlane16_swap_b32_e32 v5, v113
	v_add_f32_e32 v110, v110, v2
	v_add_f32_e32 v111, v111, v3
	v_add_f32_e32 v112, v112, v4
	v_add_f32_e32 v113, v113, v5
	v_mov_b32_e32 v2, v114
	v_mov_b32_e32 v3, v115
	v_mov_b32_e32 v4, v116
	v_mov_b32_e32 v5, v117
	s_nop 1
	v_permlane16_swap_b32_e32 v2, v114
	v_permlane16_swap_b32_e32 v3, v115
	v_permlane16_swap_b32_e32 v4, v116
	v_permlane16_swap_b32_e32 v5, v117
	v_add_f32_e32 v114, v114, v2
	v_add_f32_e32 v115, v115, v3
	v_add_f32_e32 v116, v116, v4
	v_add_f32_e32 v117, v117, v5
	v_mov_b32_e32 v2, v118
	v_mov_b32_e32 v3, v119
	v_mov_b32_e32 v4, v120
	v_mov_b32_e32 v5, v121
	s_nop 1
	v_permlane16_swap_b32_e32 v2, v118
	v_permlane16_swap_b32_e32 v3, v119
	v_permlane16_swap_b32_e32 v4, v120
	v_permlane16_swap_b32_e32 v5, v121
	v_add_f32_e32 v118, v118, v2
	v_add_f32_e32 v119, v119, v3
	v_add_f32_e32 v120, v120, v4
	v_add_f32_e32 v121, v121, v5
	v_mov_b32_e32 v2, v122
	v_mov_b32_e32 v3, v123
	v_mov_b32_e32 v4, v124
	v_mov_b32_e32 v5, v125
	s_nop 1
	v_permlane16_swap_b32_e32 v2, v122
	v_permlane16_swap_b32_e32 v3, v123
	v_permlane16_swap_b32_e32 v4, v124
	v_permlane16_swap_b32_e32 v5, v125
	v_add_f32_e32 v122, v122, v2
	v_add_f32_e32 v123, v123, v3
	v_add_f32_e32 v124, v124, v4
	v_add_f32_e32 v125, v125, v5
	v_mov_b32_e32 v2, v126
	v_mov_b32_e32 v3, v127
	v_mov_b32_e32 v4, v128
	v_mov_b32_e32 v5, v129
	s_nop 1
	v_permlane16_swap_b32_e32 v2, v126
	v_permlane16_swap_b32_e32 v3, v127
	v_permlane16_swap_b32_e32 v4, v128
	v_permlane16_swap_b32_e32 v5, v129
	v_add_f32_e32 v126, v126, v2
	v_add_f32_e32 v127, v127, v3
	v_add_f32_e32 v128, v128, v4
	v_add_f32_e32 v129, v129, v5
	v_mov_b32_e32 v2, v130
	v_mov_b32_e32 v3, v131
	v_mov_b32_e32 v4, v132
	v_mov_b32_e32 v5, v133
	s_nop 1
	v_permlane16_swap_b32_e32 v2, v130
	v_permlane16_swap_b32_e32 v3, v131
	v_permlane16_swap_b32_e32 v4, v132
	v_permlane16_swap_b32_e32 v5, v133
	v_add_f32_e32 v130, v130, v2
	v_add_f32_e32 v131, v131, v3
	v_add_f32_e32 v132, v132, v4
	v_add_f32_e32 v133, v133, v5
	v_mov_b32_e32 v2, v134
	v_mov_b32_e32 v3, v135
	v_mov_b32_e32 v4, v136
	v_mov_b32_e32 v5, v137
	s_nop 1
	v_permlane16_swap_b32_e32 v2, v134
	v_permlane16_swap_b32_e32 v3, v135
	v_permlane16_swap_b32_e32 v4, v136
	v_permlane16_swap_b32_e32 v5, v137
	v_add_f32_e32 v134, v134, v2
	v_add_f32_e32 v135, v135, v3
	v_add_f32_e32 v136, v136, v4
	v_add_f32_e32 v137, v137, v5
	v_mov_b32_e32 v2, v138
	v_mov_b32_e32 v3, v139
	v_mov_b32_e32 v4, v140
	v_mov_b32_e32 v5, v141
	s_nop 1
	v_permlane16_swap_b32_e32 v2, v138
	v_permlane16_swap_b32_e32 v3, v139
	v_permlane16_swap_b32_e32 v4, v140
	v_permlane16_swap_b32_e32 v5, v141
; #define LAS __attribute__((address_space(3)))
; __device__ void phase_setup(const Params& p, LAS unsigned char* lds) {
;     ...
;                 for (int i = 0; i < 5; ++i) { const int r = (i < 4) ? wid + 8 * i : 32;
; #pragma unroll
;                     for (int k4 = 0; k4 < 4; ++k4) { const f32x4 s4 = *(const LAS f32x4*)(sc + r * D + k + 4 * k4);
;                         a[i] += s4[0] * w[4 * k4] + s4[1] * w[4 * k4 + 1] + s4[2] * w[4 * k4 + 2] + s4[3] * w[4 * k4 + 3]; } }
;             }
;             const f32x4 bv = *(const f32x4*)(p.in[I_BMOD] + (size_t)l * (NMOD * D) + n0);
; #pragma unroll
;             for (int i = 0; i < 5; ++i) { const int r = (i < 4) ? wid + 8 * i : 32; if (i < 4 || wid == 0) *(f32x4*)(MOD + ((size_t)l * 33 + r) * (NMOD * D) + n0) = a[i] + bv; }
	v_add_f32_e32 v138, v138, v2
	v_add_f32_e32 v139, v139, v3
	v_add_f32_e32 v140, v140, v4
	v_add_f32_e32 v141, v141, v5
	v_mov_b32_e32 v2, v142
	v_mov_b32_e32 v3, v143
	v_mov_b32_e32 v4, v144
	v_mov_b32_e32 v5, v145
	s_nop 1
	v_permlane16_swap_b32_e32 v2, v142
	v_permlane16_swap_b32_e32 v3, v143
	v_permlane16_swap_b32_e32 v4, v144
	v_permlane16_swap_b32_e32 v5, v145
	v_add_f32_e32 v142, v142, v2
	v_add_f32_e32 v143, v143, v3
	v_add_f32_e32 v144, v144, v4
	v_add_f32_e32 v145, v145, v5
	v_mov_b32_e32 v2, v146
	v_mov_b32_e32 v3, v147
	v_mov_b32_e32 v4, v148
	v_mov_b32_e32 v5, v149
	s_nop 1
	v_permlane16_swap_b32_e32 v2, v146
	v_permlane16_swap_b32_e32 v3, v147
	v_permlane16_swap_b32_e32 v4, v148
	v_permlane16_swap_b32_e32 v5, v149
	v_add_f32_e32 v146, v146, v2
	v_add_f32_e32 v147, v147, v3
	v_add_f32_e32 v148, v148, v4
	v_add_f32_e32 v149, v149, v5
	v_mov_b32_e32 v2, v150
	v_mov_b32_e32 v3, v151
	v_mov_b32_e32 v4, v152
	v_mov_b32_e32 v5, v153
	s_nop 1
	v_permlane16_swap_b32_e32 v2, v150
	v_permlane16_swap_b32_e32 v3, v151
	v_permlane16_swap_b32_e32 v4, v152
	v_permlane16_swap_b32_e32 v5, v153
	v_add_f32_e32 v150, v150, v2
	v_add_f32_e32 v151, v151, v3
	v_add_f32_e32 v152, v152, v4
	v_add_f32_e32 v153, v153, v5
	v_mov_b32_e32 v2, v154
	v_mov_b32_e32 v3, v155
	v_mov_b32_e32 v4, v156
	v_mov_b32_e32 v5, v157
	s_nop 1
	v_permlane16_swap_b32_e32 v2, v154
	v_permlane16_swap_b32_e32 v3, v155
	v_permlane16_swap_b32_e32 v4, v156
	v_permlane16_swap_b32_e32 v5, v157
	v_add_f32_e32 v154, v154, v2
	v_add_f32_e32 v155, v155, v3
	v_add_f32_e32 v156, v156, v4
	v_add_f32_e32 v157, v157, v5
	v_mov_b32_e32 v2, v158
	v_mov_b32_e32 v3, v159
	v_mov_b32_e32 v4, v160
	v_mov_b32_e32 v5, v161
	s_nop 1
	v_permlane16_swap_b32_e32 v2, v158
	v_permlane16_swap_b32_e32 v3, v159
	v_permlane16_swap_b32_e32 v4, v160
	v_permlane16_swap_b32_e32 v5, v161
	v_add_f32_e32 v158, v158, v2
	v_add_f32_e32 v159, v159, v3
	v_add_f32_e32 v160, v160, v4
	v_add_f32_e32 v161, v161, v5
	v_mov_b32_e32 v2, v162
	v_mov_b32_e32 v3, v163
	v_mov_b32_e32 v4, v164
	v_mov_b32_e32 v5, v165
	s_nop 1
	v_permlane16_swap_b32_e32 v2, v162
	v_permlane16_swap_b32_e32 v3, v163
	v_permlane16_swap_b32_e32 v4, v164
	v_permlane16_swap_b32_e32 v5, v165
	v_add_f32_e32 v162, v162, v2
	v_add_f32_e32 v163, v163, v3
	v_add_f32_e32 v164, v164, v4
	v_add_f32_e32 v165, v165, v5
	v_mov_b32_e32 v2, v166
	v_mov_b32_e32 v3, v167
	v_mov_b32_e32 v4, v168
	v_mov_b32_e32 v5, v169
	s_nop 1
	v_permlane16_swap_b32_e32 v2, v166
	v_permlane16_swap_b32_e32 v3, v167
	v_permlane16_swap_b32_e32 v4, v168
	v_permlane16_swap_b32_e32 v5, v169
	v_add_f32_e32 v166, v166, v2
	v_add_f32_e32 v167, v167, v3
	v_add_f32_e32 v168, v168, v4
	v_add_f32_e32 v169, v169, v5
	v_mov_b32_e32 v2, v170
	v_mov_b32_e32 v3, v171
	v_mov_b32_e32 v4, v172
	v_mov_b32_e32 v5, v173
	s_nop 1
	v_permlane16_swap_b32_e32 v2, v170
	v_permlane16_swap_b32_e32 v3, v171
	v_permlane16_swap_b32_e32 v4, v172
	v_permlane16_swap_b32_e32 v5, v173
	v_add_f32_e32 v170, v170, v2
	v_add_f32_e32 v171, v171, v3
	v_add_f32_e32 v172, v172, v4
	v_add_f32_e32 v173, v173, v5
	v_mov_b32_e32 v2, v174
	v_mov_b32_e32 v3, v175
	v_mov_b32_e32 v4, v176
	v_mov_b32_e32 v5, v177
	s_nop 1
	v_permlane16_swap_b32_e32 v2, v174
	v_permlane16_swap_b32_e32 v3, v175
	v_permlane16_swap_b32_e32 v4, v176
	v_permlane16_swap_b32_e32 v5, v177
	v_add_f32_e32 v174, v174, v2
	v_add_f32_e32 v175, v175, v3
	v_add_f32_e32 v176, v176, v4
	v_add_f32_e32 v177, v177, v5
	v_mov_b32_e32 v2, v178
	v_mov_b32_e32 v3, v179
	v_mov_b32_e32 v4, v180
	v_mov_b32_e32 v5, v181
	s_nop 1
	v_permlane16_swap_b32_e32 v2, v178
	v_permlane16_swap_b32_e32 v3, v179
	v_permlane16_swap_b32_e32 v4, v180
	v_permlane16_swap_b32_e32 v5, v181
	v_add_f32_e32 v178, v178, v2
	v_add_f32_e32 v179, v179, v3
	v_add_f32_e32 v180, v180, v4
	v_add_f32_e32 v181, v181, v5
	v_mov_b32_e32 v2, v182
	v_mov_b32_e32 v3, v183
	v_mov_b32_e32 v4, v184
	v_mov_b32_e32 v5, v185
	s_nop 1
	v_permlane16_swap_b32_e32 v2, v182
	v_permlane16_swap_b32_e32 v3, v183
	v_permlane16_swap_b32_e32 v4, v184
	v_permlane16_swap_b32_e32 v5, v185
	v_add_f32_e32 v182, v182, v2
	v_add_f32_e32 v183, v183, v3
	v_add_f32_e32 v184, v184, v4
	v_add_f32_e32 v185, v185, v5
	v_mov_b32_e32 v2, v186
	v_mov_b32_e32 v3, v187
	v_mov_b32_e32 v4, v188
	v_mov_b32_e32 v5, v189
	s_nop 1
	v_permlane16_swap_b32_e32 v2, v186
	v_permlane16_swap_b32_e32 v3, v187
	v_permlane16_swap_b32_e32 v4, v188
	v_permlane16_swap_b32_e32 v5, v189
	v_add_f32_e32 v186, v186, v2
	v_add_f32_e32 v187, v187, v3
	v_add_f32_e32 v188, v188, v4
	v_add_f32_e32 v189, v189, v5
	v_mov_b32_e32 v2, v190
	v_mov_b32_e32 v3, v191
	v_mov_b32_e32 v4, v192
	v_mov_b32_e32 v5, v193
	s_nop 1
	v_permlane16_swap_b32_e32 v2, v190
	v_permlane16_swap_b32_e32 v3, v191
	v_permlane16_swap_b32_e32 v4, v192
	v_permlane16_swap_b32_e32 v5, v193
	v_add_f32_e32 v190, v190, v2
	v_add_f32_e32 v191, v191, v3
	v_add_f32_e32 v192, v192, v4
	v_add_f32_e32 v193, v193, v5
	v_mov_b32_e32 v2, v194
	v_mov_b32_e32 v3, v195
	v_mov_b32_e32 v4, v196
	v_mov_b32_e32 v5, v197
	s_nop 1
	v_permlane16_swap_b32_e32 v2, v194
	v_permlane16_swap_b32_e32 v3, v195
	v_permlane16_swap_b32_e32 v4, v196
	v_permlane16_swap_b32_e32 v5, v197
	v_add_f32_e32 v194, v194, v2
	v_add_f32_e32 v195, v195, v3
	v_add_f32_e32 v196, v196, v4
	v_add_f32_e32 v197, v197, v5
	v_mov_b32_e32 v2, v198
	v_mov_b32_e32 v3, v199
	v_mov_b32_e32 v4, v200
	v_mov_b32_e32 v5, v201
	s_nop 1
	v_permlane16_swap_b32_e32 v2, v198
	v_permlane16_swap_b32_e32 v3, v199
	v_permlane16_swap_b32_e32 v4, v200
	v_permlane16_swap_b32_e32 v5, v201
	v_add_f32_e32 v198, v198, v2
	v_add_f32_e32 v199, v199, v3
	v_add_f32_e32 v200, v200, v4
; #define LAS __attribute__((address_space(3)))
; __device__ void phase_setup(const Params& p, LAS unsigned char* lds) {
;     ...
;                 for (int i = 0; i < 5; ++i) { const int r = (i < 4) ? wid + 8 * i : 32;
; #pragma unroll
;                     for (int k4 = 0; k4 < 4; ++k4) { const f32x4 s4 = *(const LAS f32x4*)(sc + r * D + k + 4 * k4);
;                         a[i] += s4[0] * w[4 * k4] + s4[1] * w[4 * k4 + 1] + s4[2] * w[4 * k4 + 2] + s4[3] * w[4 * k4 + 3]; } }
;             }
;             const f32x4 bv = *(const f32x4*)(p.in[I_BMOD] + (size_t)l * (NMOD * D) + n0);
; #pragma unroll
;             for (int i = 0; i < 5; ++i) { const int r = (i < 4) ? wid + 8 * i : 32; if (i < 4 || wid == 0) *(f32x4*)(MOD + ((size_t)l * 33 + r) * (NMOD * D) + n0) = a[i] + bv; }
	v_add_f32_e32 v201, v201, v5
	v_mov_b32_e32 v2, v202
	v_mov_b32_e32 v3, v203
	v_mov_b32_e32 v4, v204
	v_mov_b32_e32 v5, v205
	s_nop 1
	v_permlane16_swap_b32_e32 v2, v202
	v_permlane16_swap_b32_e32 v3, v203
	v_permlane16_swap_b32_e32 v4, v204
	v_permlane16_swap_b32_e32 v5, v205
	v_add_f32_e32 v202, v202, v2
	v_add_f32_e32 v203, v203, v3
	v_add_f32_e32 v204, v204, v4
	v_add_f32_e32 v205, v205, v5
	v_mov_b32_e32 v2, v206
	v_mov_b32_e32 v3, v207
	v_mov_b32_e32 v4, v208
	v_mov_b32_e32 v5, v209
	s_nop 1
	v_permlane16_swap_b32_e32 v2, v206
	v_permlane16_swap_b32_e32 v3, v207
	v_permlane16_swap_b32_e32 v4, v208
	v_permlane16_swap_b32_e32 v5, v209
	v_add_f32_e32 v206, v206, v2
	v_add_f32_e32 v207, v207, v3
	v_add_f32_e32 v208, v208, v4
	v_add_f32_e32 v209, v209, v5
	v_mov_b32_e32 v2, v78
	v_mov_b32_e32 v3, v79
	v_mov_b32_e32 v4, v80
	v_mov_b32_e32 v5, v81
	s_nop 1
	v_permlane32_swap_b32_e32 v2, v78
	v_permlane32_swap_b32_e32 v3, v79
	v_permlane32_swap_b32_e32 v4, v80
	v_permlane32_swap_b32_e32 v5, v81
	v_add_f32_e32 v78, v78, v2
	v_add_f32_e32 v79, v79, v3
	v_add_f32_e32 v80, v80, v4
	v_add_f32_e32 v81, v81, v5
	v_mov_b32_e32 v2, v82
	v_mov_b32_e32 v3, v83
	v_mov_b32_e32 v4, v84
	v_mov_b32_e32 v5, v85
	s_nop 1
	v_permlane32_swap_b32_e32 v2, v82
	v_permlane32_swap_b32_e32 v3, v83
	v_permlane32_swap_b32_e32 v4, v84
	v_permlane32_swap_b32_e32 v5, v85
	v_add_f32_e32 v82, v82, v2
	v_add_f32_e32 v83, v83, v3
	v_add_f32_e32 v84, v84, v4
	v_add_f32_e32 v85, v85, v5
	v_mov_b32_e32 v2, v86
	v_mov_b32_e32 v3, v87
	v_mov_b32_e32 v4, v88
	v_mov_b32_e32 v5, v89
	s_nop 1
	v_permlane32_swap_b32_e32 v2, v86
	v_permlane32_swap_b32_e32 v3, v87
	v_permlane32_swap_b32_e32 v4, v88
	v_permlane32_swap_b32_e32 v5, v89
	v_add_f32_e32 v86, v86, v2
	v_add_f32_e32 v87, v87, v3
	v_add_f32_e32 v88, v88, v4
	v_add_f32_e32 v89, v89, v5
	v_mov_b32_e32 v2, v90
	v_mov_b32_e32 v3, v91
	v_mov_b32_e32 v4, v92
	v_mov_b32_e32 v5, v93
	s_nop 1
	v_permlane32_swap_b32_e32 v2, v90
	v_permlane32_swap_b32_e32 v3, v91
	v_permlane32_swap_b32_e32 v4, v92
	v_permlane32_swap_b32_e32 v5, v93
	v_add_f32_e32 v90, v90, v2
	v_add_f32_e32 v91, v91, v3
	v_add_f32_e32 v92, v92, v4
	v_add_f32_e32 v93, v93, v5
	v_mov_b32_e32 v2, v94
	v_mov_b32_e32 v3, v95
	v_mov_b32_e32 v4, v96
	v_mov_b32_e32 v5, v97
	s_nop 1
	v_permlane32_swap_b32_e32 v2, v94
	v_permlane32_swap_b32_e32 v3, v95
	v_permlane32_swap_b32_e32 v4, v96
	v_permlane32_swap_b32_e32 v5, v97
	v_add_f32_e32 v94, v94, v2
	v_add_f32_e32 v95, v95, v3
	v_add_f32_e32 v96, v96, v4
	v_add_f32_e32 v97, v97, v5
	v_mov_b32_e32 v2, v98
	v_mov_b32_e32 v3, v99
	v_mov_b32_e32 v4, v100
	v_mov_b32_e32 v5, v101
	s_nop 1
	v_permlane32_swap_b32_e32 v2, v98
	v_permlane32_swap_b32_e32 v3, v99
	v_permlane32_swap_b32_e32 v4, v100
	v_permlane32_swap_b32_e32 v5, v101
	v_add_f32_e32 v98, v98, v2
	v_add_f32_e32 v99, v99, v3
	v_add_f32_e32 v100, v100, v4
	v_add_f32_e32 v101, v101, v5
	v_mov_b32_e32 v2, v102
	v_mov_b32_e32 v3, v103
	v_mov_b32_e32 v4, v104
	v_mov_b32_e32 v5, v105
	s_nop 1
	v_permlane32_swap_b32_e32 v2, v102
	v_permlane32_swap_b32_e32 v3, v103
	v_permlane32_swap_b32_e32 v4, v104
	v_permlane32_swap_b32_e32 v5, v105
	v_add_f32_e32 v102, v102, v2
	v_add_f32_e32 v103, v103, v3
	v_add_f32_e32 v104, v104, v4
	v_add_f32_e32 v105, v105, v5
	v_mov_b32_e32 v2, v106
	v_mov_b32_e32 v3, v107
	v_mov_b32_e32 v4, v108
	v_mov_b32_e32 v5, v109
	s_nop 1
	v_permlane32_swap_b32_e32 v2, v106
	v_permlane32_swap_b32_e32 v3, v107
	v_permlane32_swap_b32_e32 v4, v108
	v_permlane32_swap_b32_e32 v5, v109
	v_add_f32_e32 v106, v106, v2
	v_add_f32_e32 v107, v107, v3
	v_add_f32_e32 v108, v108, v4
	v_add_f32_e32 v109, v109, v5
	v_mov_b32_e32 v2, v110
	v_mov_b32_e32 v3, v111
	v_mov_b32_e32 v4, v112
	v_mov_b32_e32 v5, v113
	s_nop 1
	v_permlane32_swap_b32_e32 v2, v110
	v_permlane32_swap_b32_e32 v3, v111
	v_permlane32_swap_b32_e32 v4, v112
	v_permlane32_swap_b32_e32 v5, v113
	v_add_f32_e32 v110, v110, v2
	v_add_f32_e32 v111, v111, v3
	v_add_f32_e32 v112, v112, v4
	v_add_f32_e32 v113, v113, v5
	v_mov_b32_e32 v2, v114
	v_mov_b32_e32 v3, v115
	v_mov_b32_e32 v4, v116
	v_mov_b32_e32 v5, v117
	s_nop 1
	v_permlane32_swap_b32_e32 v2, v114
	v_permlane32_swap_b32_e32 v3, v115
	v_permlane32_swap_b32_e32 v4, v116
	v_permlane32_swap_b32_e32 v5, v117
	v_add_f32_e32 v114, v114, v2
	v_add_f32_e32 v115, v115, v3
	v_add_f32_e32 v116, v116, v4
	v_add_f32_e32 v117, v117, v5
	v_mov_b32_e32 v2, v118
	v_mov_b32_e32 v3, v119
	v_mov_b32_e32 v4, v120
	v_mov_b32_e32 v5, v121
	s_nop 1
	v_permlane32_swap_b32_e32 v2, v118
	v_permlane32_swap_b32_e32 v3, v119
	v_permlane32_swap_b32_e32 v4, v120
	v_permlane32_swap_b32_e32 v5, v121
	v_add_f32_e32 v118, v118, v2
	v_add_f32_e32 v119, v119, v3
	v_add_f32_e32 v120, v120, v4
	v_add_f32_e32 v121, v121, v5
	v_mov_b32_e32 v2, v122
	v_mov_b32_e32 v3, v123
	v_mov_b32_e32 v4, v124
	v_mov_b32_e32 v5, v125
	s_nop 1
	v_permlane32_swap_b32_e32 v2, v122
	v_permlane32_swap_b32_e32 v3, v123
	v_permlane32_swap_b32_e32 v4, v124
	v_permlane32_swap_b32_e32 v5, v125
	v_add_f32_e32 v122, v122, v2
	v_add_f32_e32 v123, v123, v3
	v_add_f32_e32 v124, v124, v4
	v_add_f32_e32 v125, v125, v5
	v_mov_b32_e32 v2, v126
	v_mov_b32_e32 v3, v127
	v_mov_b32_e32 v4, v128
	v_mov_b32_e32 v5, v129
	s_nop 1
	v_permlane32_swap_b32_e32 v2, v126
	v_permlane32_swap_b32_e32 v3, v127
	v_permlane32_swap_b32_e32 v4, v128
	v_permlane32_swap_b32_e32 v5, v129
	v_add_f32_e32 v126, v126, v2
	v_add_f32_e32 v127, v127, v3
	v_add_f32_e32 v128, v128, v4
	v_add_f32_e32 v129, v129, v5
	v_mov_b32_e32 v2, v130
	v_mov_b32_e32 v3, v131
	v_mov_b32_e32 v4, v132
	v_mov_b32_e32 v5, v133
	s_nop 1
	v_permlane32_swap_b32_e32 v2, v130
	v_permlane32_swap_b32_e32 v3, v131
; #define LAS __attribute__((address_space(3)))
; __device__ void phase_setup(const Params& p, LAS unsigned char* lds) {
;     ...
;                 for (int i = 0; i < 5; ++i) { const int r = (i < 4) ? wid + 8 * i : 32;
; #pragma unroll
;                     for (int k4 = 0; k4 < 4; ++k4) { const f32x4 s4 = *(const LAS f32x4*)(sc + r * D + k + 4 * k4);
;                         a[i] += s4[0] * w[4 * k4] + s4[1] * w[4 * k4 + 1] + s4[2] * w[4 * k4 + 2] + s4[3] * w[4 * k4 + 3]; } }
;             }
;             const f32x4 bv = *(const f32x4*)(p.in[I_BMOD] + (size_t)l * (NMOD * D) + n0);
; #pragma unroll
;             for (int i = 0; i < 5; ++i) { const int r = (i < 4) ? wid + 8 * i : 32; if (i < 4 || wid == 0) *(f32x4*)(MOD + ((size_t)l * 33 + r) * (NMOD * D) + n0) = a[i] + bv; }
	v_permlane32_swap_b32_e32 v4, v132
	v_permlane32_swap_b32_e32 v5, v133
	v_add_f32_e32 v130, v130, v2
	v_add_f32_e32 v131, v131, v3
	v_add_f32_e32 v132, v132, v4
	v_add_f32_e32 v133, v133, v5
	v_mov_b32_e32 v2, v134
	v_mov_b32_e32 v3, v135
	v_mov_b32_e32 v4, v136
	v_mov_b32_e32 v5, v137
	s_nop 1
	v_permlane32_swap_b32_e32 v2, v134
	v_permlane32_swap_b32_e32 v3, v135
	v_permlane32_swap_b32_e32 v4, v136
	v_permlane32_swap_b32_e32 v5, v137
	v_add_f32_e32 v134, v134, v2
	v_add_f32_e32 v135, v135, v3
	v_add_f32_e32 v136, v136, v4
	v_add_f32_e32 v137, v137, v5
	v_mov_b32_e32 v2, v138
	v_mov_b32_e32 v3, v139
	v_mov_b32_e32 v4, v140
	v_mov_b32_e32 v5, v141
	s_nop 1
	v_permlane32_swap_b32_e32 v2, v138
	v_permlane32_swap_b32_e32 v3, v139
	v_permlane32_swap_b32_e32 v4, v140
	v_permlane32_swap_b32_e32 v5, v141
	v_add_f32_e32 v138, v138, v2
	v_add_f32_e32 v139, v139, v3
	v_add_f32_e32 v140, v140, v4
	v_add_f32_e32 v141, v141, v5
	v_mov_b32_e32 v2, v142
	v_mov_b32_e32 v3, v143
	v_mov_b32_e32 v4, v144
	v_mov_b32_e32 v5, v145
	s_nop 1
	v_permlane32_swap_b32_e32 v2, v142
	v_permlane32_swap_b32_e32 v3, v143
	v_permlane32_swap_b32_e32 v4, v144
	v_permlane32_swap_b32_e32 v5, v145
	v_add_f32_e32 v142, v142, v2
	v_add_f32_e32 v143, v143, v3
	v_add_f32_e32 v144, v144, v4
	v_add_f32_e32 v145, v145, v5
	v_mov_b32_e32 v2, v146
	v_mov_b32_e32 v3, v147
	v_mov_b32_e32 v4, v148
	v_mov_b32_e32 v5, v149
	s_nop 1
	v_permlane32_swap_b32_e32 v2, v146
	v_permlane32_swap_b32_e32 v3, v147
	v_permlane32_swap_b32_e32 v4, v148
	v_permlane32_swap_b32_e32 v5, v149
	v_add_f32_e32 v146, v146, v2
	v_add_f32_e32 v147, v147, v3
	v_add_f32_e32 v148, v148, v4
	v_add_f32_e32 v149, v149, v5
	v_mov_b32_e32 v2, v150
	v_mov_b32_e32 v3, v151
	v_mov_b32_e32 v4, v152
	v_mov_b32_e32 v5, v153
	s_nop 1
	v_permlane32_swap_b32_e32 v2, v150
	v_permlane32_swap_b32_e32 v3, v151
	v_permlane32_swap_b32_e32 v4, v152
	v_permlane32_swap_b32_e32 v5, v153
	v_add_f32_e32 v150, v150, v2
	v_add_f32_e32 v151, v151, v3
	v_add_f32_e32 v152, v152, v4
	v_add_f32_e32 v153, v153, v5
	v_mov_b32_e32 v2, v154
	v_mov_b32_e32 v3, v155
	v_mov_b32_e32 v4, v156
	v_mov_b32_e32 v5, v157
	s_nop 1
	v_permlane32_swap_b32_e32 v2, v154
	v_permlane32_swap_b32_e32 v3, v155
	v_permlane32_swap_b32_e32 v4, v156
	v_permlane32_swap_b32_e32 v5, v157
	v_add_f32_e32 v154, v154, v2
	v_add_f32_e32 v155, v155, v3
	v_add_f32_e32 v156, v156, v4
	v_add_f32_e32 v157, v157, v5
	v_mov_b32_e32 v2, v158
	v_mov_b32_e32 v3, v159
	v_mov_b32_e32 v4, v160
	v_mov_b32_e32 v5, v161
	s_nop 1
	v_permlane32_swap_b32_e32 v2, v158
	v_permlane32_swap_b32_e32 v3, v159
	v_permlane32_swap_b32_e32 v4, v160
	v_permlane32_swap_b32_e32 v5, v161
	v_add_f32_e32 v158, v158, v2
	v_add_f32_e32 v159, v159, v3
	v_add_f32_e32 v160, v160, v4
	v_add_f32_e32 v161, v161, v5
	v_mov_b32_e32 v2, v162
	v_mov_b32_e32 v3, v163
	v_mov_b32_e32 v4, v164
	v_mov_b32_e32 v5, v165
	s_nop 1
	v_permlane32_swap_b32_e32 v2, v162
	v_permlane32_swap_b32_e32 v3, v163
	v_permlane32_swap_b32_e32 v4, v164
	v_permlane32_swap_b32_e32 v5, v165
	v_add_f32_e32 v162, v162, v2
	v_add_f32_e32 v163, v163, v3
	v_add_f32_e32 v164, v164, v4
	v_add_f32_e32 v165, v165, v5
	v_mov_b32_e32 v2, v166
	v_mov_b32_e32 v3, v167
	v_mov_b32_e32 v4, v168
	v_mov_b32_e32 v5, v169
	s_nop 1
	v_permlane32_swap_b32_e32 v2, v166
	v_permlane32_swap_b32_e32 v3, v167
	v_permlane32_swap_b32_e32 v4, v168
	v_permlane32_swap_b32_e32 v5, v169
	v_add_f32_e32 v166, v166, v2
	v_add_f32_e32 v167, v167, v3
	v_add_f32_e32 v168, v168, v4
	v_add_f32_e32 v169, v169, v5
	v_mov_b32_e32 v2, v170
	v_mov_b32_e32 v3, v171
	v_mov_b32_e32 v4, v172
	v_mov_b32_e32 v5, v173
	s_nop 1
	v_permlane32_swap_b32_e32 v2, v170
	v_permlane32_swap_b32_e32 v3, v171
	v_permlane32_swap_b32_e32 v4, v172
	v_permlane32_swap_b32_e32 v5, v173
	v_add_f32_e32 v170, v170, v2
	v_add_f32_e32 v171, v171, v3
	v_add_f32_e32 v172, v172, v4
	v_add_f32_e32 v173, v173, v5
	v_mov_b32_e32 v2, v174
	v_mov_b32_e32 v3, v175
	v_mov_b32_e32 v4, v176
	v_mov_b32_e32 v5, v177
	s_nop 1
	v_permlane32_swap_b32_e32 v2, v174
	v_permlane32_swap_b32_e32 v3, v175
	v_permlane32_swap_b32_e32 v4, v176
	v_permlane32_swap_b32_e32 v5, v177
	v_add_f32_e32 v174, v174, v2
	v_add_f32_e32 v175, v175, v3
	v_add_f32_e32 v176, v176, v4
	v_add_f32_e32 v177, v177, v5
	v_mov_b32_e32 v2, v178
	v_mov_b32_e32 v3, v179
	v_mov_b32_e32 v4, v180
	v_mov_b32_e32 v5, v181
	s_nop 1
	v_permlane32_swap_b32_e32 v2, v178
	v_permlane32_swap_b32_e32 v3, v179
	v_permlane32_swap_b32_e32 v4, v180
	v_permlane32_swap_b32_e32 v5, v181
	v_add_f32_e32 v178, v178, v2
	v_add_f32_e32 v179, v179, v3
	v_add_f32_e32 v180, v180, v4
	v_add_f32_e32 v181, v181, v5
	v_mov_b32_e32 v2, v182
	v_mov_b32_e32 v3, v183
	v_mov_b32_e32 v4, v184
	v_mov_b32_e32 v5, v185
	s_nop 1
	v_permlane32_swap_b32_e32 v2, v182
	v_permlane32_swap_b32_e32 v3, v183
	v_permlane32_swap_b32_e32 v4, v184
	v_permlane32_swap_b32_e32 v5, v185
	v_add_f32_e32 v182, v182, v2
	v_add_f32_e32 v183, v183, v3
	v_add_f32_e32 v184, v184, v4
	v_add_f32_e32 v185, v185, v5
	v_mov_b32_e32 v2, v186
	v_mov_b32_e32 v3, v187
	v_mov_b32_e32 v4, v188
	v_mov_b32_e32 v5, v189
	s_nop 1
	v_permlane32_swap_b32_e32 v2, v186
	v_permlane32_swap_b32_e32 v3, v187
	v_permlane32_swap_b32_e32 v4, v188
	v_permlane32_swap_b32_e32 v5, v189
	v_add_f32_e32 v186, v186, v2
	v_add_f32_e32 v187, v187, v3
	v_add_f32_e32 v188, v188, v4
	v_add_f32_e32 v189, v189, v5
	v_mov_b32_e32 v2, v190
	v_mov_b32_e32 v3, v191
	v_mov_b32_e32 v4, v192
	v_mov_b32_e32 v5, v193
	s_nop 1
	v_permlane32_swap_b32_e32 v2, v190
	v_permlane32_swap_b32_e32 v3, v191
	v_permlane32_swap_b32_e32 v4, v192
	v_permlane32_swap_b32_e32 v5, v193
	v_add_f32_e32 v190, v190, v2
; __device__ void phase_setup(const Params& p, LAS unsigned char* lds) {
;     ...
;             const f32x4 bv = *(const f32x4*)(p.in[I_BMOD] + (size_t)l * (NMOD * D) + n0);
; #pragma unroll
;             for (int i = 0; i < 5; ++i) { const int r = (i < 4) ? wid + 8 * i : 32; if (i < 4 || wid == 0) *(f32x4*)(MOD + ((size_t)l * 33 + r) * (NMOD * D) + n0) = a[i] + bv; }
	v_add_f32_e32 v191, v191, v3
	v_add_f32_e32 v192, v192, v4
	v_add_f32_e32 v193, v193, v5
	v_mov_b32_e32 v2, v194
	v_mov_b32_e32 v3, v195
	v_mov_b32_e32 v4, v196
	v_mov_b32_e32 v5, v197
	s_nop 1
	v_permlane32_swap_b32_e32 v2, v194
	v_permlane32_swap_b32_e32 v3, v195
	v_permlane32_swap_b32_e32 v4, v196
	v_permlane32_swap_b32_e32 v5, v197
	v_add_f32_e32 v194, v194, v2
	v_add_f32_e32 v195, v195, v3
	v_add_f32_e32 v196, v196, v4
	v_add_f32_e32 v197, v197, v5
	v_mov_b32_e32 v2, v198
	v_mov_b32_e32 v3, v199
	v_mov_b32_e32 v4, v200
	v_mov_b32_e32 v5, v201
	s_nop 1
	v_permlane32_swap_b32_e32 v2, v198
	v_permlane32_swap_b32_e32 v3, v199
	v_permlane32_swap_b32_e32 v4, v200
	v_permlane32_swap_b32_e32 v5, v201
	v_add_f32_e32 v198, v198, v2
	v_add_f32_e32 v199, v199, v3
	v_add_f32_e32 v200, v200, v4
	v_add_f32_e32 v201, v201, v5
	v_mov_b32_e32 v2, v202
	v_mov_b32_e32 v3, v203
	v_mov_b32_e32 v4, v204
	v_mov_b32_e32 v5, v205
	s_nop 1
	v_permlane32_swap_b32_e32 v2, v202
	v_permlane32_swap_b32_e32 v3, v203
	v_permlane32_swap_b32_e32 v4, v204
	v_permlane32_swap_b32_e32 v5, v205
	v_add_f32_e32 v202, v202, v2
	v_add_f32_e32 v203, v203, v3
	v_add_f32_e32 v204, v204, v4
	v_add_f32_e32 v205, v205, v5
	v_mov_b32_e32 v2, v206
	v_mov_b32_e32 v3, v207
	v_mov_b32_e32 v4, v208
	v_mov_b32_e32 v5, v209
	s_nop 1
	v_permlane32_swap_b32_e32 v2, v206
	v_permlane32_swap_b32_e32 v3, v207
	v_permlane32_swap_b32_e32 v4, v208
	v_permlane32_swap_b32_e32 v5, v209
	v_add_f32_e32 v206, v206, v2
	v_add_f32_e32 v207, v207, v3
	v_add_f32_e32 v208, v208, v4
	v_add_f32_e32 v209, v209, v5
	s_mul_i32 s4, s9, 0x9000
	s_mul_hi_u32 s5, s9, 0x9000
	s_add_u32 s4, s22, s4
	s_addc_u32 s5, s23, s5
	s_sub_u32 s12, s8, 0
	s_mul_i32 s12, s9, 36
	s_sub_u32 s12, s8, s12
	s_lshl_b32 s12, s12, 10
	v_add_u32_e32 v6, s12, v210
	global_load_dwordx4 v[8:11], v6, s[4:5]
	s_mul_i32 s4, s9, 0x129000
	s_mul_hi_u32 s5, s9, 0x129000
	s_add_u32 s4, s0, s4
	s_addc_u32 s5, s1, s5
	s_mov_b64 s[12:13], exec
	s_mov_b64 exec, 0xff
	s_waitcnt vmcnt(0)
; #define LAS __attribute__((address_space(3)))
; __device__ __forceinline__ int bid_opaque() { int b = blockIdx.x; asm volatile("" : "+s"(b)); return b; }
; __device__ void phase_setup(const Params& p, LAS unsigned char* lds) {
;     ...
;         for (int it = bid_opaque(); it < NL * 36; it += gridDim.x) {
;             const int l = it / 36, cgp = it % 36, n0 = cgp * 256 + lane * 4;
;             const float* wp = p.in[I_WMOD] + (size_t)l * D * (NMOD * D) + n0;
;             f32x4 a[5];
; #pragma unroll
;             for (int i = 0; i < 5; ++i) a[i] = (f32x4){0.f, 0.f, 0.f, 0.f};
;             for (int k = 0; k < D; k += 16) {
;                 f32x4 w[16];
; #pragma unroll
;                 for (int kk = 0; kk < 16; ++kk) w[kk] = *(const f32x4*)(wp + (size_t)(k + kk) * (NMOD * D));
; #pragma unroll
;                 for (int i = 0; i < 5; ++i) { const int r = (i < 4) ? wid + 8 * i : 32;
; #pragma unroll
;                     for (int k4 = 0; k4 < 4; ++k4) { const f32x4 s4 = *(const LAS f32x4*)(sc + r * D + k + 4 * k4);
;                         a[i] += s4[0] * w[4 * k4] + s4[1] * w[4 * k4 + 1] + s4[2] * w[4 * k4 + 2] + s4[3] * w[4 * k4 + 3]; } }
;             }
;             const f32x4 bv = *(const f32x4*)(p.in[I_BMOD] + (size_t)l * (NMOD * D) + n0);
; #pragma unroll
;             for (int i = 0; i < 5; ++i) { const int r = (i < 4) ? wid + 8 * i : 32; if (i < 4 || wid == 0) *(f32x4*)(MOD + ((size_t)l * 33 + r) * (NMOD * D) + n0) = a[i] + bv; }
	v_pk_add_f32 v[78:79], v[78:79], v[8:9]
	v_pk_add_f32 v[80:81], v[80:81], v[10:11]
	global_store_dwordx4 v6, v[78:81], s[4:5]
	v_add_u32_e32 v6, 0x9000, v6
	v_pk_add_f32 v[82:83], v[82:83], v[8:9]
	v_pk_add_f32 v[84:85], v[84:85], v[10:11]
	global_store_dwordx4 v6, v[82:85], s[4:5]
	v_add_u32_e32 v6, 0x9000, v6
	v_pk_add_f32 v[86:87], v[86:87], v[8:9]
	v_pk_add_f32 v[88:89], v[88:89], v[10:11]
	global_store_dwordx4 v6, v[86:89], s[4:5]
	v_add_u32_e32 v6, 0x9000, v6
	v_pk_add_f32 v[90:91], v[90:91], v[8:9]
	v_pk_add_f32 v[92:93], v[92:93], v[10:11]
	global_store_dwordx4 v6, v[90:93], s[4:5]
	v_add_u32_e32 v6, 0x9000, v6
	v_pk_add_f32 v[94:95], v[94:95], v[8:9]
	v_pk_add_f32 v[96:97], v[96:97], v[10:11]
	global_store_dwordx4 v6, v[94:97], s[4:5]
	v_add_u32_e32 v6, 0x9000, v6
	v_pk_add_f32 v[98:99], v[98:99], v[8:9]
	v_pk_add_f32 v[100:101], v[100:101], v[10:11]
	global_store_dwordx4 v6, v[98:101], s[4:5]
	v_add_u32_e32 v6, 0x9000, v6
	v_pk_add_f32 v[102:103], v[102:103], v[8:9]
	v_pk_add_f32 v[104:105], v[104:105], v[10:11]
	global_store_dwordx4 v6, v[102:105], s[4:5]
	v_add_u32_e32 v6, 0x9000, v6
	v_pk_add_f32 v[106:107], v[106:107], v[8:9]
	v_pk_add_f32 v[108:109], v[108:109], v[10:11]
	global_store_dwordx4 v6, v[106:109], s[4:5]
	v_add_u32_e32 v6, 0x9000, v6
	v_pk_add_f32 v[110:111], v[110:111], v[8:9]
	v_pk_add_f32 v[112:113], v[112:113], v[10:11]
	global_store_dwordx4 v6, v[110:113], s[4:5]
	v_add_u32_e32 v6, 0x9000, v6
	v_pk_add_f32 v[114:115], v[114:115], v[8:9]
	v_pk_add_f32 v[116:117], v[116:117], v[10:11]
	global_store_dwordx4 v6, v[114:117], s[4:5]
	v_add_u32_e32 v6, 0x9000, v6
	v_pk_add_f32 v[118:119], v[118:119], v[8:9]
	v_pk_add_f32 v[120:121], v[120:121], v[10:11]
	global_store_dwordx4 v6, v[118:121], s[4:5]
	v_add_u32_e32 v6, 0x9000, v6
	v_pk_add_f32 v[122:123], v[122:123], v[8:9]
	v_pk_add_f32 v[124:125], v[124:125], v[10:11]
	global_store_dwordx4 v6, v[122:125], s[4:5]
	v_add_u32_e32 v6, 0x9000, v6
	v_pk_add_f32 v[126:127], v[126:127], v[8:9]
	v_pk_add_f32 v[128:129], v[128:129], v[10:11]
	global_store_dwordx4 v6, v[126:129], s[4:5]
	v_add_u32_e32 v6, 0x9000, v6
	v_pk_add_f32 v[130:131], v[130:131], v[8:9]
	v_pk_add_f32 v[132:133], v[132:133], v[10:11]
	global_store_dwordx4 v6, v[130:133], s[4:5]
	v_add_u32_e32 v6, 0x9000, v6
	v_pk_add_f32 v[134:135], v[134:135], v[8:9]
	v_pk_add_f32 v[136:137], v[136:137], v[10:11]
	global_store_dwordx4 v6, v[134:137], s[4:5]
	v_add_u32_e32 v6, 0x9000, v6
	v_pk_add_f32 v[138:139], v[138:139], v[8:9]
	v_pk_add_f32 v[140:141], v[140:141], v[10:11]
	global_store_dwordx4 v6, v[138:141], s[4:5]
	v_add_u32_e32 v6, 0x9000, v6
	v_pk_add_f32 v[142:143], v[142:143], v[8:9]
	v_pk_add_f32 v[144:145], v[144:145], v[10:11]
	global_store_dwordx4 v6, v[142:145], s[4:5]
	v_add_u32_e32 v6, 0x9000, v6
	v_pk_add_f32 v[146:147], v[146:147], v[8:9]
	v_pk_add_f32 v[148:149], v[148:149], v[10:11]
	global_store_dwordx4 v6, v[146:149], s[4:5]
	v_add_u32_e32 v6, 0x9000, v6
	v_pk_add_f32 v[150:151], v[150:151], v[8:9]
	v_pk_add_f32 v[152:153], v[152:153], v[10:11]
	global_store_dwordx4 v6, v[150:153], s[4:5]
	v_add_u32_e32 v6, 0x9000, v6
	v_pk_add_f32 v[154:155], v[154:155], v[8:9]
	v_pk_add_f32 v[156:157], v[156:157], v[10:11]
	global_store_dwordx4 v6, v[154:157], s[4:5]
	v_add_u32_e32 v6, 0x9000, v6
	v_pk_add_f32 v[158:159], v[158:159], v[8:9]
	v_pk_add_f32 v[160:161], v[160:161], v[10:11]
	global_store_dwordx4 v6, v[158:161], s[4:5]
	v_add_u32_e32 v6, 0x9000, v6
	v_pk_add_f32 v[162:163], v[162:163], v[8:9]
	v_pk_add_f32 v[164:165], v[164:165], v[10:11]
	global_store_dwordx4 v6, v[162:165], s[4:5]
	v_add_u32_e32 v6, 0x9000, v6
	v_pk_add_f32 v[166:167], v[166:167], v[8:9]
	v_pk_add_f32 v[168:169], v[168:169], v[10:11]
	global_store_dwordx4 v6, v[166:169], s[4:5]
	v_add_u32_e32 v6, 0x9000, v6
	v_pk_add_f32 v[170:171], v[170:171], v[8:9]
	v_pk_add_f32 v[172:173], v[172:173], v[10:11]
	global_store_dwordx4 v6, v[170:173], s[4:5]
	v_add_u32_e32 v6, 0x9000, v6
	v_pk_add_f32 v[174:175], v[174:175], v[8:9]
	v_pk_add_f32 v[176:177], v[176:177], v[10:11]
	global_store_dwordx4 v6, v[174:177], s[4:5]
	v_add_u32_e32 v6, 0x9000, v6
	v_pk_add_f32 v[178:179], v[178:179], v[8:9]
	v_pk_add_f32 v[180:181], v[180:181], v[10:11]
	global_store_dwordx4 v6, v[178:181], s[4:5]
	v_add_u32_e32 v6, 0x9000, v6
	v_pk_add_f32 v[182:183], v[182:183], v[8:9]
	v_pk_add_f32 v[184:185], v[184:185], v[10:11]
	global_store_dwordx4 v6, v[182:185], s[4:5]
	v_add_u32_e32 v6, 0x9000, v6
	v_pk_add_f32 v[186:187], v[186:187], v[8:9]
	v_pk_add_f32 v[188:189], v[188:189], v[10:11]
	global_store_dwordx4 v6, v[186:189], s[4:5]
	v_add_u32_e32 v6, 0x9000, v6
	v_pk_add_f32 v[190:191], v[190:191], v[8:9]
	v_pk_add_f32 v[192:193], v[192:193], v[10:11]
	global_store_dwordx4 v6, v[190:193], s[4:5]
	v_add_u32_e32 v6, 0x9000, v6
	v_pk_add_f32 v[194:195], v[194:195], v[8:9]
	v_pk_add_f32 v[196:197], v[196:197], v[10:11]
	global_store_dwordx4 v6, v[194:197], s[4:5]
	v_add_u32_e32 v6, 0x9000, v6
	v_pk_add_f32 v[198:199], v[198:199], v[8:9]
	v_pk_add_f32 v[200:201], v[200:201], v[10:11]
	global_store_dwordx4 v6, v[198:201], s[4:5]
	v_add_u32_e32 v6, 0x9000, v6
	v_pk_add_f32 v[202:203], v[202:203], v[8:9]
	v_pk_add_f32 v[204:205], v[204:205], v[10:11]
	global_store_dwordx4 v6, v[202:205], s[4:5]
	v_add_u32_e32 v6, 0x9000, v6
	v_pk_add_f32 v[206:207], v[206:207], v[8:9]
	v_pk_add_f32 v[208:209], v[208:209], v[10:11]
	global_store_dwordx4 v6, v[206:209], s[4:5]
	v_add_u32_e32 v6, 0x9000, v6
	s_mov_b64 exec, s[12:13]
	s_add_i32 s8, s8, s10
	s_cmpk_gt_i32 s8, 0x8f
	s_cbranch_scc0 .Lgv_item
